# v20 + SGPR-base addressing for all GEMM LDS-DMA stage loads (no per-load 64-bit VALU add)
# speedup vs baseline: 1.0057x; 1.0051x over previous
.LBB0_219:
	s_ashr_i32 s63, s62, 31
	s_lshl_b64 s[10:11], s[62:63], 21
	s_add_u32 s10, s56, s10
	s_addc_u32 s11, s57, s11
	s_and_b64 s[24:25], s[92:93], exec
	s_cselect_b32 s30, s11, s91
	s_cselect_b32 s31, s10, s90
	s_ashr_i32 s89, s88, 31
	s_lshl_b64 s[24:25], s[88:89], 21
	s_add_u32 s94, s86, s24
	s_addc_u32 s95, s87, s25
	s_and_b64 s[24:25], s[92:93], exec
	s_cselect_b32 s63, s95, s35
	s_cselect_b32 s81, s94, s34
	s_add_u32 vcc_lo, s90, 0x100080
	s_addc_u32 vcc_hi, s91, 0
	s_add_u32 s82, s34, 0x100
	s_addc_u32 s83, s35, 0
	s_mov_b32 s84, -2
	ds_read_b128 v[152:155], v148
	ds_read_b128 v[156:159], v148 offset:1024
	ds_read_b128 v[160:163], v148 offset:2048
	ds_read_b128 v[164:167], v148 offset:3072
	ds_read_b128 v[168:171], v149
	ds_read_b128 v[176:179], v149 offset:1024
	ds_read_b128 v[180:183], v149 offset:2048
	ds_read_b128 v[184:187], v149 offset:3072
	s_add_u32 s24, vcc_lo, 0xfff00080
	s_addc_u32 s25, vcc_hi, -1
	s_cmp_eq_u32 s84, 60
	s_cselect_b32 s91, s30, s25
	s_cselect_b32 s90, s31, s24
	s_cselect_b32 s35, s63, s83
	s_cselect_b32 s34, s81, s82
	s_mov_b32 m0, s47
	ds_read_b128 v[188:191], v150
	ds_read_b128 v[192:195], v150 offset:1024
	ds_read_b128 v[196:199], v150 offset:2048
	ds_read_b128 v[200:203], v150 offset:3072
	ds_read_b128 v[204:207], v150 offset:4096
	ds_read_b128 v[208:211], v150 offset:5120
	ds_read_b128 v[212:215], v150 offset:6144
	ds_read_b128 v[216:219], v150 offset:7168
	global_load_lds_dwordx4 v138, vcc
	s_mov_b32 m0, s50
	s_nop 0
	global_load_lds_dwordx4 v140, vcc
	s_waitcnt vmcnt(8)
	s_waitcnt lgkmcnt(0)
	s_barrier
	s_setprio 1
	s_waitcnt lgkmcnt(0)
	v_mfma_f32_16x16x32_bf16 v[126:129], v[152:155], v[188:191], 0
	v_mfma_f32_16x16x32_bf16 v[122:125], v[160:163], v[188:191], 0
	v_mfma_f32_16x16x32_bf16 v[114:117], v[152:155], v[196:199], 0
	v_mfma_f32_16x16x32_bf16 v[106:109], v[160:163], v[196:199], 0
	v_mfma_f32_16x16x32_bf16 v[98:101], v[152:155], v[204:207], 0
	v_mfma_f32_16x16x32_bf16 v[90:93], v[160:163], v[204:207], 0
	v_mfma_f32_16x16x32_bf16 v[82:85], v[152:155], v[212:215], 0
	v_mfma_f32_16x16x32_bf16 v[74:77], v[160:163], v[212:215], 0
	v_mfma_f32_16x16x32_bf16 v[126:129], v[156:159], v[192:195], v[126:129]
	v_mfma_f32_16x16x32_bf16 v[122:125], v[164:167], v[192:195], v[122:125]
	v_mfma_f32_16x16x32_bf16 v[114:117], v[156:159], v[200:203], v[114:117]
	v_mfma_f32_16x16x32_bf16 v[106:109], v[164:167], v[200:203], v[106:109]
	v_mfma_f32_16x16x32_bf16 v[98:101], v[156:159], v[208:211], v[98:101]
	v_mfma_f32_16x16x32_bf16 v[90:93], v[164:167], v[208:211], v[90:93]
	v_mfma_f32_16x16x32_bf16 v[82:85], v[156:159], v[216:219], v[82:85]
	v_mfma_f32_16x16x32_bf16 v[74:77], v[164:167], v[216:219], v[74:77]
	s_setprio 0
	s_setprio 1
	v_mfma_f32_16x16x32_bf16 v[118:121], v[168:171], v[188:191], 0
	v_mfma_f32_16x16x32_bf16 v[110:113], v[180:183], v[188:191], 0
	v_mfma_f32_16x16x32_bf16 v[102:105], v[168:171], v[196:199], 0
	v_mfma_f32_16x16x32_bf16 v[94:97], v[180:183], v[196:199], 0
	v_mfma_f32_16x16x32_bf16 v[86:89], v[168:171], v[204:207], 0
	v_mfma_f32_16x16x32_bf16 v[78:81], v[180:183], v[204:207], 0
	v_mfma_f32_16x16x32_bf16 v[70:73], v[168:171], v[212:215], 0
	v_mfma_f32_16x16x32_bf16 v[66:69], v[180:183], v[212:215], 0
	v_mfma_f32_16x16x32_bf16 v[118:121], v[176:179], v[192:195], v[118:121]
	v_mfma_f32_16x16x32_bf16 v[110:113], v[184:187], v[192:195], v[110:113]
	v_mfma_f32_16x16x32_bf16 v[102:105], v[176:179], v[200:203], v[102:105]
	v_mfma_f32_16x16x32_bf16 v[94:97], v[184:187], v[200:203], v[94:97]
	v_mfma_f32_16x16x32_bf16 v[86:89], v[176:179], v[208:211], v[86:89]
	v_mfma_f32_16x16x32_bf16 v[78:81], v[184:187], v[208:211], v[78:81]
	v_mfma_f32_16x16x32_bf16 v[70:73], v[176:179], v[216:219], v[70:73]
	v_mfma_f32_16x16x32_bf16 v[66:69], v[184:187], v[216:219], v[66:69]
	s_setprio 0
	s_barrier
	s_mov_b32 m0, s51
	s_add_u32 s24, s34, 0x100000
	ds_read_b128 v[188:191], v150 offset:16384
	ds_read_b128 v[192:195], v150 offset:17408
	ds_read_b128 v[196:199], v150 offset:18432
	ds_read_b128 v[200:203], v150 offset:19456
	ds_read_b128 v[204:207], v150 offset:20480
	ds_read_b128 v[208:211], v150 offset:21504
	ds_read_b128 v[212:215], v150 offset:22528
	ds_read_b128 v[216:219], v150 offset:23552
	global_load_lds_dwordx4 v132, s[34:35]
	s_mov_b32 m0, s75
	s_addc_u32 s25, s35, 0
	global_load_lds_dwordx4 v136, s[34:35]
	s_mov_b32 m0, s78
	s_nop 0
	global_load_lds_dwordx4 v132, s[24:25]
	s_mov_b32 m0, s79
	s_nop 0
	global_load_lds_dwordx4 v136, s[24:25]
	s_mov_b32 m0, s39
	s_nop 0
	global_load_lds_dwordx4 v130, s[90:91]
	s_mov_b32 m0, s40
	s_nop 0
	global_load_lds_dwordx4 v134, s[90:91]
	s_waitcnt vmcnt(8)
	s_waitcnt lgkmcnt(0)
	s_barrier
	s_setprio 1
	s_waitcnt lgkmcnt(0)
	v_mfma_f32_16x16x32_bf16 v[62:65], v[152:155], v[188:191], 0
	v_mfma_f32_16x16x32_bf16 v[58:61], v[160:163], v[188:191], 0
	v_mfma_f32_16x16x32_bf16 v[50:53], v[152:155], v[196:199], 0
	v_mfma_f32_16x16x32_bf16 v[42:45], v[160:163], v[196:199], 0
	v_mfma_f32_16x16x32_bf16 v[34:37], v[152:155], v[204:207], 0
	v_mfma_f32_16x16x32_bf16 v[26:29], v[160:163], v[204:207], 0
	v_mfma_f32_16x16x32_bf16 v[18:21], v[152:155], v[212:215], 0
	v_mfma_f32_16x16x32_bf16 v[10:13], v[160:163], v[212:215], 0
	v_mfma_f32_16x16x32_bf16 v[62:65], v[156:159], v[192:195], v[62:65]
	v_mfma_f32_16x16x32_bf16 v[58:61], v[164:167], v[192:195], v[58:61]
	v_mfma_f32_16x16x32_bf16 v[50:53], v[156:159], v[200:203], v[50:53]
	v_mfma_f32_16x16x32_bf16 v[42:45], v[164:167], v[200:203], v[42:45]
	v_mfma_f32_16x16x32_bf16 v[34:37], v[156:159], v[208:211], v[34:37]
	v_mfma_f32_16x16x32_bf16 v[26:29], v[164:167], v[208:211], v[26:29]
	v_mfma_f32_16x16x32_bf16 v[18:21], v[156:159], v[216:219], v[18:21]
	v_mfma_f32_16x16x32_bf16 v[10:13], v[164:167], v[216:219], v[10:13]
	s_setprio 0
	s_setprio 1
	v_mfma_f32_16x16x32_bf16 v[54:57], v[168:171], v[188:191], 0
	v_mfma_f32_16x16x32_bf16 v[46:49], v[180:183], v[188:191], 0
	v_mfma_f32_16x16x32_bf16 v[38:41], v[168:171], v[196:199], 0
	v_mfma_f32_16x16x32_bf16 v[30:33], v[180:183], v[196:199], 0
	v_mfma_f32_16x16x32_bf16 v[22:25], v[168:171], v[204:207], 0
	v_mfma_f32_16x16x32_bf16 v[14:17], v[180:183], v[204:207], 0
	v_mfma_f32_16x16x32_bf16 v[6:9], v[168:171], v[212:215], 0
	v_mfma_f32_16x16x32_bf16 v[2:5], v[180:183], v[212:215], 0
	v_mfma_f32_16x16x32_bf16 v[54:57], v[176:179], v[192:195], v[54:57]
	v_mfma_f32_16x16x32_bf16 v[46:49], v[184:187], v[192:195], v[46:49]
	v_mfma_f32_16x16x32_bf16 v[38:41], v[176:179], v[200:203], v[38:41]
	v_mfma_f32_16x16x32_bf16 v[30:33], v[184:187], v[200:203], v[30:33]
	v_mfma_f32_16x16x32_bf16 v[22:25], v[176:179], v[208:211], v[22:25]
	v_mfma_f32_16x16x32_bf16 v[14:17], v[184:187], v[208:211], v[14:17]
	v_mfma_f32_16x16x32_bf16 v[6:9], v[176:179], v[216:219], v[6:9]
	v_mfma_f32_16x16x32_bf16 v[2:5], v[184:187], v[216:219], v[2:5]
	s_setprio 0
	s_barrier
	s_add_i32 s85, 0, 0x1c000
	v_add_u32_e32 v175, s85, v146
	ds_read_b128 v[152:155], v151
	ds_read_b128 v[156:159], v151 offset:1024
	ds_read_b128 v[160:163], v151 offset:2048
	ds_read_b128 v[164:167], v151 offset:3072
	ds_read_b128 v[168:171], v175
	ds_read_b128 v[176:179], v175 offset:1024
	ds_read_b128 v[180:183], v175 offset:2048
	ds_read_b128 v[184:187], v175 offset:3072
	s_add_u32 s24, s90, 0x100000
	s_addc_u32 s25, s91, 0
	s_mov_b32 m0, s41
	ds_read_b128 v[188:191], v150 offset:32768
	ds_read_b128 v[192:195], v150 offset:33792
	ds_read_b128 v[196:199], v150 offset:34816
	ds_read_b128 v[200:203], v150 offset:35840
	ds_read_b128 v[204:207], v150 offset:36864
	ds_read_b128 v[208:211], v150 offset:37888
	ds_read_b128 v[212:215], v150 offset:38912
	ds_read_b128 v[216:219], v150 offset:39936
	global_load_lds_dwordx4 v130, s[24:25]
	s_mov_b32 m0, s42
	s_nop 0
	global_load_lds_dwordx4 v134, s[24:25]
	s_waitcnt vmcnt(8)
	s_waitcnt lgkmcnt(0)
	s_barrier
	s_setprio 1
	s_waitcnt lgkmcnt(0)
	v_mfma_f32_16x16x32_bf16 v[126:129], v[152:155], v[188:191], v[126:129]
	v_mfma_f32_16x16x32_bf16 v[122:125], v[160:163], v[188:191], v[122:125]
	v_mfma_f32_16x16x32_bf16 v[114:117], v[152:155], v[196:199], v[114:117]
	v_mfma_f32_16x16x32_bf16 v[106:109], v[160:163], v[196:199], v[106:109]
	v_mfma_f32_16x16x32_bf16 v[98:101], v[152:155], v[204:207], v[98:101]
	v_mfma_f32_16x16x32_bf16 v[90:93], v[160:163], v[204:207], v[90:93]
	v_mfma_f32_16x16x32_bf16 v[82:85], v[152:155], v[212:215], v[82:85]
	v_mfma_f32_16x16x32_bf16 v[74:77], v[160:163], v[212:215], v[74:77]
	v_mfma_f32_16x16x32_bf16 v[126:129], v[156:159], v[192:195], v[126:129]
	v_mfma_f32_16x16x32_bf16 v[122:125], v[164:167], v[192:195], v[122:125]
	v_mfma_f32_16x16x32_bf16 v[114:117], v[156:159], v[200:203], v[114:117]
	v_mfma_f32_16x16x32_bf16 v[106:109], v[164:167], v[200:203], v[106:109]
	v_mfma_f32_16x16x32_bf16 v[98:101], v[156:159], v[208:211], v[98:101]
	v_mfma_f32_16x16x32_bf16 v[90:93], v[164:167], v[208:211], v[90:93]
	v_mfma_f32_16x16x32_bf16 v[82:85], v[156:159], v[216:219], v[82:85]
	v_mfma_f32_16x16x32_bf16 v[74:77], v[164:167], v[216:219], v[74:77]
	s_setprio 0
	s_setprio 1
	v_mfma_f32_16x16x32_bf16 v[118:121], v[168:171], v[188:191], v[118:121]
	v_mfma_f32_16x16x32_bf16 v[110:113], v[180:183], v[188:191], v[110:113]
	v_mfma_f32_16x16x32_bf16 v[102:105], v[168:171], v[196:199], v[102:105]
	v_mfma_f32_16x16x32_bf16 v[94:97], v[180:183], v[196:199], v[94:97]
	v_mfma_f32_16x16x32_bf16 v[86:89], v[168:171], v[204:207], v[86:89]
	v_mfma_f32_16x16x32_bf16 v[78:81], v[180:183], v[204:207], v[78:81]
	v_mfma_f32_16x16x32_bf16 v[70:73], v[168:171], v[212:215], v[70:73]
	v_mfma_f32_16x16x32_bf16 v[66:69], v[180:183], v[212:215], v[66:69]
	v_mfma_f32_16x16x32_bf16 v[118:121], v[176:179], v[192:195], v[118:121]
	v_mfma_f32_16x16x32_bf16 v[110:113], v[184:187], v[192:195], v[110:113]
	v_mfma_f32_16x16x32_bf16 v[102:105], v[176:179], v[200:203], v[102:105]
	v_mfma_f32_16x16x32_bf16 v[94:97], v[184:187], v[200:203], v[94:97]
	v_mfma_f32_16x16x32_bf16 v[86:89], v[176:179], v[208:211], v[86:89]
	v_mfma_f32_16x16x32_bf16 v[78:81], v[184:187], v[208:211], v[78:81]
	v_mfma_f32_16x16x32_bf16 v[70:73], v[176:179], v[216:219], v[70:73]
	v_mfma_f32_16x16x32_bf16 v[66:69], v[184:187], v[216:219], v[66:69]
	s_setprio 0
	s_barrier
	s_add_u32 s12, s34, 0x80
	s_addc_u32 s13, s35, 0
	s_add_u32 s14, s90, 0x80
	s_addc_u32 s15, s91, 0
	s_add_i32 s24, s80, s37
	s_mov_b32 m0, s24
	ds_read_b128 v[188:191], v150 offset:49152
	ds_read_b128 v[192:195], v150 offset:50176
	ds_read_b128 v[196:199], v150 offset:51200
	ds_read_b128 v[200:203], v150 offset:52224
	ds_read_b128 v[204:207], v150 offset:53248
	ds_read_b128 v[208:211], v150 offset:54272
	ds_read_b128 v[212:215], v150 offset:55296
	ds_read_b128 v[216:219], v150 offset:56320
	global_load_lds_dwordx4 v132, s[12:13]
	s_add_i32 m0, s24, 0x2000
	s_add_u32 s24, s34, 0x100080
	s_addc_u32 s25, s35, 0
	s_add_i32 s34, s85, s37
	global_load_lds_dwordx4 v136, s[12:13]
	s_mov_b32 m0, s34
	s_nop 0
	global_load_lds_dwordx4 v132, s[24:25]
	s_add_i32 m0, s34, 0x2000
	s_nop 0
	global_load_lds_dwordx4 v136, s[24:25]
	s_mov_b32 m0, s43
	s_nop 0
	global_load_lds_dwordx4 v130, s[14:15]
	s_mov_b32 m0, s44
	s_nop 0
	global_load_lds_dwordx4 v134, s[14:15]
	s_waitcnt vmcnt(8)
	s_waitcnt lgkmcnt(0)
	s_barrier
	s_setprio 1
	s_waitcnt lgkmcnt(0)
	v_mfma_f32_16x16x32_bf16 v[62:65], v[152:155], v[188:191], v[62:65]
	v_mfma_f32_16x16x32_bf16 v[58:61], v[160:163], v[188:191], v[58:61]
	v_mfma_f32_16x16x32_bf16 v[50:53], v[152:155], v[196:199], v[50:53]
	v_mfma_f32_16x16x32_bf16 v[42:45], v[160:163], v[196:199], v[42:45]
	v_mfma_f32_16x16x32_bf16 v[34:37], v[152:155], v[204:207], v[34:37]
	v_mfma_f32_16x16x32_bf16 v[26:29], v[160:163], v[204:207], v[26:29]
	v_mfma_f32_16x16x32_bf16 v[18:21], v[152:155], v[212:215], v[18:21]
	v_mfma_f32_16x16x32_bf16 v[10:13], v[160:163], v[212:215], v[10:13]
	v_mfma_f32_16x16x32_bf16 v[62:65], v[156:159], v[192:195], v[62:65]
	v_mfma_f32_16x16x32_bf16 v[58:61], v[164:167], v[192:195], v[58:61]
	v_mfma_f32_16x16x32_bf16 v[50:53], v[156:159], v[200:203], v[50:53]
	v_mfma_f32_16x16x32_bf16 v[42:45], v[164:167], v[200:203], v[42:45]
	v_mfma_f32_16x16x32_bf16 v[34:37], v[156:159], v[208:211], v[34:37]
	v_mfma_f32_16x16x32_bf16 v[26:29], v[164:167], v[208:211], v[26:29]
	v_mfma_f32_16x16x32_bf16 v[18:21], v[156:159], v[216:219], v[18:21]
	v_mfma_f32_16x16x32_bf16 v[10:13], v[164:167], v[216:219], v[10:13]
	s_setprio 0
	s_setprio 1
	v_mfma_f32_16x16x32_bf16 v[54:57], v[168:171], v[188:191], v[54:57]
	v_mfma_f32_16x16x32_bf16 v[46:49], v[180:183], v[188:191], v[46:49]
	v_mfma_f32_16x16x32_bf16 v[38:41], v[168:171], v[196:199], v[38:41]
	v_mfma_f32_16x16x32_bf16 v[30:33], v[180:183], v[196:199], v[30:33]
	v_mfma_f32_16x16x32_bf16 v[22:25], v[168:171], v[204:207], v[22:25]
	v_mfma_f32_16x16x32_bf16 v[14:17], v[180:183], v[204:207], v[14:17]
	v_mfma_f32_16x16x32_bf16 v[6:9], v[168:171], v[212:215], v[6:9]
	v_mfma_f32_16x16x32_bf16 v[2:5], v[180:183], v[212:215], v[2:5]
	v_mfma_f32_16x16x32_bf16 v[54:57], v[176:179], v[192:195], v[54:57]
	v_mfma_f32_16x16x32_bf16 v[46:49], v[184:187], v[192:195], v[46:49]
	v_mfma_f32_16x16x32_bf16 v[38:41], v[176:179], v[200:203], v[38:41]
	v_mfma_f32_16x16x32_bf16 v[30:33], v[184:187], v[200:203], v[30:33]
	v_mfma_f32_16x16x32_bf16 v[22:25], v[176:179], v[208:211], v[22:25]
	v_mfma_f32_16x16x32_bf16 v[14:17], v[184:187], v[208:211], v[14:17]
	v_mfma_f32_16x16x32_bf16 v[6:9], v[176:179], v[216:219], v[6:9]
	v_mfma_f32_16x16x32_bf16 v[2:5], v[184:187], v[216:219], v[2:5]
	s_setprio 0
	s_barrier
	s_add_i32 s84, s84, 2
	s_add_u32 vcc_lo, vcc_lo, 0x100
	s_addc_u32 vcc_hi, vcc_hi, 0
	s_add_u32 s82, s82, 0x100
	s_addc_u32 s83, s83, 0
	s_cmp_gt_u32 s84, 61
	s_cbranch_scc1 .Lpeel_exit_0
.LBB0_220:
	ds_read_b128 v[152:155], v148
	ds_read_b128 v[156:159], v148 offset:1024
	ds_read_b128 v[160:163], v148 offset:2048
	ds_read_b128 v[164:167], v148 offset:3072
	ds_read_b128 v[168:171], v149
	ds_read_b128 v[176:179], v149 offset:1024
	ds_read_b128 v[180:183], v149 offset:2048
	ds_read_b128 v[184:187], v149 offset:3072
	s_add_u32 s24, vcc_lo, 0xfff00080
	s_addc_u32 s25, vcc_hi, -1
	s_cmp_eq_u32 s84, 60
	s_cselect_b32 s91, s30, s25
	s_cselect_b32 s90, s31, s24
	s_cselect_b32 s35, s63, s83
	s_cselect_b32 s34, s81, s82
	s_mov_b32 m0, s47
	ds_read_b128 v[188:191], v150
	ds_read_b128 v[192:195], v150 offset:1024
	ds_read_b128 v[196:199], v150 offset:2048
	ds_read_b128 v[200:203], v150 offset:3072
	ds_read_b128 v[204:207], v150 offset:4096
	ds_read_b128 v[208:211], v150 offset:5120
	ds_read_b128 v[212:215], v150 offset:6144
	ds_read_b128 v[216:219], v150 offset:7168
	global_load_lds_dwordx4 v138, vcc
	s_mov_b32 m0, s50
	s_nop 0
	global_load_lds_dwordx4 v140, vcc
	s_waitcnt vmcnt(8)
	s_waitcnt lgkmcnt(0)
	s_barrier
	s_setprio 1
	s_waitcnt lgkmcnt(0)
	v_mfma_f32_16x16x32_bf16 v[126:129], v[152:155], v[188:191], v[126:129]
	v_mfma_f32_16x16x32_bf16 v[122:125], v[160:163], v[188:191], v[122:125]
	v_mfma_f32_16x16x32_bf16 v[114:117], v[152:155], v[196:199], v[114:117]
	v_mfma_f32_16x16x32_bf16 v[106:109], v[160:163], v[196:199], v[106:109]
	v_mfma_f32_16x16x32_bf16 v[98:101], v[152:155], v[204:207], v[98:101]
	v_mfma_f32_16x16x32_bf16 v[90:93], v[160:163], v[204:207], v[90:93]
	v_mfma_f32_16x16x32_bf16 v[82:85], v[152:155], v[212:215], v[82:85]
	v_mfma_f32_16x16x32_bf16 v[74:77], v[160:163], v[212:215], v[74:77]
	v_mfma_f32_16x16x32_bf16 v[126:129], v[156:159], v[192:195], v[126:129]
	v_mfma_f32_16x16x32_bf16 v[122:125], v[164:167], v[192:195], v[122:125]
	v_mfma_f32_16x16x32_bf16 v[114:117], v[156:159], v[200:203], v[114:117]
	v_mfma_f32_16x16x32_bf16 v[106:109], v[164:167], v[200:203], v[106:109]
	v_mfma_f32_16x16x32_bf16 v[98:101], v[156:159], v[208:211], v[98:101]
	v_mfma_f32_16x16x32_bf16 v[90:93], v[164:167], v[208:211], v[90:93]
	v_mfma_f32_16x16x32_bf16 v[82:85], v[156:159], v[216:219], v[82:85]
	v_mfma_f32_16x16x32_bf16 v[74:77], v[164:167], v[216:219], v[74:77]
	s_setprio 0
	s_setprio 1
	v_mfma_f32_16x16x32_bf16 v[118:121], v[168:171], v[188:191], v[118:121]
	v_mfma_f32_16x16x32_bf16 v[110:113], v[180:183], v[188:191], v[110:113]
	v_mfma_f32_16x16x32_bf16 v[102:105], v[168:171], v[196:199], v[102:105]
	v_mfma_f32_16x16x32_bf16 v[94:97], v[180:183], v[196:199], v[94:97]
	v_mfma_f32_16x16x32_bf16 v[86:89], v[168:171], v[204:207], v[86:89]
	v_mfma_f32_16x16x32_bf16 v[78:81], v[180:183], v[204:207], v[78:81]
	v_mfma_f32_16x16x32_bf16 v[70:73], v[168:171], v[212:215], v[70:73]
	v_mfma_f32_16x16x32_bf16 v[66:69], v[180:183], v[212:215], v[66:69]
	v_mfma_f32_16x16x32_bf16 v[118:121], v[176:179], v[192:195], v[118:121]
	v_mfma_f32_16x16x32_bf16 v[110:113], v[184:187], v[192:195], v[110:113]
	v_mfma_f32_16x16x32_bf16 v[102:105], v[176:179], v[200:203], v[102:105]
	v_mfma_f32_16x16x32_bf16 v[94:97], v[184:187], v[200:203], v[94:97]
	v_mfma_f32_16x16x32_bf16 v[86:89], v[176:179], v[208:211], v[86:89]
	v_mfma_f32_16x16x32_bf16 v[78:81], v[184:187], v[208:211], v[78:81]
	v_mfma_f32_16x16x32_bf16 v[70:73], v[176:179], v[216:219], v[70:73]
	v_mfma_f32_16x16x32_bf16 v[66:69], v[184:187], v[216:219], v[66:69]
	s_setprio 0
	s_barrier
	s_mov_b32 m0, s51
	s_add_u32 s24, s34, 0x100000
	ds_read_b128 v[188:191], v150 offset:16384
	ds_read_b128 v[192:195], v150 offset:17408
	ds_read_b128 v[196:199], v150 offset:18432
	ds_read_b128 v[200:203], v150 offset:19456
	ds_read_b128 v[204:207], v150 offset:20480
	ds_read_b128 v[208:211], v150 offset:21504
	ds_read_b128 v[212:215], v150 offset:22528
	ds_read_b128 v[216:219], v150 offset:23552
	global_load_lds_dwordx4 v132, s[34:35]
	s_mov_b32 m0, s75
	s_addc_u32 s25, s35, 0
	global_load_lds_dwordx4 v136, s[34:35]
	s_mov_b32 m0, s78
	s_nop 0
	global_load_lds_dwordx4 v132, s[24:25]
	s_mov_b32 m0, s79
	s_nop 0
	global_load_lds_dwordx4 v136, s[24:25]
	s_mov_b32 m0, s39
	s_nop 0
	global_load_lds_dwordx4 v130, s[90:91]
	s_mov_b32 m0, s40
	s_nop 0
	global_load_lds_dwordx4 v134, s[90:91]
	s_waitcnt vmcnt(8)
	s_waitcnt lgkmcnt(0)
	s_barrier
	s_setprio 1
	s_waitcnt lgkmcnt(0)
	v_mfma_f32_16x16x32_bf16 v[62:65], v[152:155], v[188:191], v[62:65]
	v_mfma_f32_16x16x32_bf16 v[58:61], v[160:163], v[188:191], v[58:61]
	v_mfma_f32_16x16x32_bf16 v[50:53], v[152:155], v[196:199], v[50:53]
	v_mfma_f32_16x16x32_bf16 v[42:45], v[160:163], v[196:199], v[42:45]
	v_mfma_f32_16x16x32_bf16 v[34:37], v[152:155], v[204:207], v[34:37]
	v_mfma_f32_16x16x32_bf16 v[26:29], v[160:163], v[204:207], v[26:29]
	v_mfma_f32_16x16x32_bf16 v[18:21], v[152:155], v[212:215], v[18:21]
	v_mfma_f32_16x16x32_bf16 v[10:13], v[160:163], v[212:215], v[10:13]
	v_mfma_f32_16x16x32_bf16 v[62:65], v[156:159], v[192:195], v[62:65]
	v_mfma_f32_16x16x32_bf16 v[58:61], v[164:167], v[192:195], v[58:61]
	v_mfma_f32_16x16x32_bf16 v[50:53], v[156:159], v[200:203], v[50:53]
	v_mfma_f32_16x16x32_bf16 v[42:45], v[164:167], v[200:203], v[42:45]
	v_mfma_f32_16x16x32_bf16 v[34:37], v[156:159], v[208:211], v[34:37]
	v_mfma_f32_16x16x32_bf16 v[26:29], v[164:167], v[208:211], v[26:29]
	v_mfma_f32_16x16x32_bf16 v[18:21], v[156:159], v[216:219], v[18:21]
	v_mfma_f32_16x16x32_bf16 v[10:13], v[164:167], v[216:219], v[10:13]
	s_setprio 0
	s_setprio 1
	v_mfma_f32_16x16x32_bf16 v[54:57], v[168:171], v[188:191], v[54:57]
	v_mfma_f32_16x16x32_bf16 v[46:49], v[180:183], v[188:191], v[46:49]
	v_mfma_f32_16x16x32_bf16 v[38:41], v[168:171], v[196:199], v[38:41]
	v_mfma_f32_16x16x32_bf16 v[30:33], v[180:183], v[196:199], v[30:33]
	v_mfma_f32_16x16x32_bf16 v[22:25], v[168:171], v[204:207], v[22:25]
	v_mfma_f32_16x16x32_bf16 v[14:17], v[180:183], v[204:207], v[14:17]
	v_mfma_f32_16x16x32_bf16 v[6:9], v[168:171], v[212:215], v[6:9]
	v_mfma_f32_16x16x32_bf16 v[2:5], v[180:183], v[212:215], v[2:5]
	v_mfma_f32_16x16x32_bf16 v[54:57], v[176:179], v[192:195], v[54:57]
	v_mfma_f32_16x16x32_bf16 v[46:49], v[184:187], v[192:195], v[46:49]
	v_mfma_f32_16x16x32_bf16 v[38:41], v[176:179], v[200:203], v[38:41]
	v_mfma_f32_16x16x32_bf16 v[30:33], v[184:187], v[200:203], v[30:33]
	v_mfma_f32_16x16x32_bf16 v[22:25], v[176:179], v[208:211], v[22:25]
	v_mfma_f32_16x16x32_bf16 v[14:17], v[184:187], v[208:211], v[14:17]
	v_mfma_f32_16x16x32_bf16 v[6:9], v[176:179], v[216:219], v[6:9]
	v_mfma_f32_16x16x32_bf16 v[2:5], v[184:187], v[216:219], v[2:5]
	s_setprio 0
	s_barrier
	s_add_i32 s85, 0, 0x1c000
	v_add_u32_e32 v175, s85, v146
	ds_read_b128 v[152:155], v151
	ds_read_b128 v[156:159], v151 offset:1024
	ds_read_b128 v[160:163], v151 offset:2048
	ds_read_b128 v[164:167], v151 offset:3072
	ds_read_b128 v[168:171], v175
	ds_read_b128 v[176:179], v175 offset:1024
	ds_read_b128 v[180:183], v175 offset:2048
	ds_read_b128 v[184:187], v175 offset:3072
	s_add_u32 s24, s90, 0x100000
	s_addc_u32 s25, s91, 0
	s_mov_b32 m0, s41
	ds_read_b128 v[188:191], v150 offset:32768
	ds_read_b128 v[192:195], v150 offset:33792
	ds_read_b128 v[196:199], v150 offset:34816
	ds_read_b128 v[200:203], v150 offset:35840
	ds_read_b128 v[204:207], v150 offset:36864
	ds_read_b128 v[208:211], v150 offset:37888
	ds_read_b128 v[212:215], v150 offset:38912
	ds_read_b128 v[216:219], v150 offset:39936
	global_load_lds_dwordx4 v130, s[24:25]
	s_mov_b32 m0, s42
	s_nop 0
	global_load_lds_dwordx4 v134, s[24:25]
	s_waitcnt vmcnt(8)
	s_waitcnt lgkmcnt(0)
	s_barrier
	s_setprio 1
	s_waitcnt lgkmcnt(0)
	v_mfma_f32_16x16x32_bf16 v[126:129], v[152:155], v[188:191], v[126:129]
	v_mfma_f32_16x16x32_bf16 v[122:125], v[160:163], v[188:191], v[122:125]
	v_mfma_f32_16x16x32_bf16 v[114:117], v[152:155], v[196:199], v[114:117]
	v_mfma_f32_16x16x32_bf16 v[106:109], v[160:163], v[196:199], v[106:109]
	v_mfma_f32_16x16x32_bf16 v[98:101], v[152:155], v[204:207], v[98:101]
	v_mfma_f32_16x16x32_bf16 v[90:93], v[160:163], v[204:207], v[90:93]
	v_mfma_f32_16x16x32_bf16 v[82:85], v[152:155], v[212:215], v[82:85]
	v_mfma_f32_16x16x32_bf16 v[74:77], v[160:163], v[212:215], v[74:77]
	v_mfma_f32_16x16x32_bf16 v[126:129], v[156:159], v[192:195], v[126:129]
	v_mfma_f32_16x16x32_bf16 v[122:125], v[164:167], v[192:195], v[122:125]
	v_mfma_f32_16x16x32_bf16 v[114:117], v[156:159], v[200:203], v[114:117]
	v_mfma_f32_16x16x32_bf16 v[106:109], v[164:167], v[200:203], v[106:109]
	v_mfma_f32_16x16x32_bf16 v[98:101], v[156:159], v[208:211], v[98:101]
	v_mfma_f32_16x16x32_bf16 v[90:93], v[164:167], v[208:211], v[90:93]
	v_mfma_f32_16x16x32_bf16 v[82:85], v[156:159], v[216:219], v[82:85]
	v_mfma_f32_16x16x32_bf16 v[74:77], v[164:167], v[216:219], v[74:77]
	s_setprio 0
	s_setprio 1
	v_mfma_f32_16x16x32_bf16 v[118:121], v[168:171], v[188:191], v[118:121]
	v_mfma_f32_16x16x32_bf16 v[110:113], v[180:183], v[188:191], v[110:113]
	v_mfma_f32_16x16x32_bf16 v[102:105], v[168:171], v[196:199], v[102:105]
	v_mfma_f32_16x16x32_bf16 v[94:97], v[180:183], v[196:199], v[94:97]
	v_mfma_f32_16x16x32_bf16 v[86:89], v[168:171], v[204:207], v[86:89]
	v_mfma_f32_16x16x32_bf16 v[78:81], v[180:183], v[204:207], v[78:81]
	v_mfma_f32_16x16x32_bf16 v[70:73], v[168:171], v[212:215], v[70:73]
	v_mfma_f32_16x16x32_bf16 v[66:69], v[180:183], v[212:215], v[66:69]
	v_mfma_f32_16x16x32_bf16 v[118:121], v[176:179], v[192:195], v[118:121]
	v_mfma_f32_16x16x32_bf16 v[110:113], v[184:187], v[192:195], v[110:113]
	v_mfma_f32_16x16x32_bf16 v[102:105], v[176:179], v[200:203], v[102:105]
	v_mfma_f32_16x16x32_bf16 v[94:97], v[184:187], v[200:203], v[94:97]
	v_mfma_f32_16x16x32_bf16 v[86:89], v[176:179], v[208:211], v[86:89]
	v_mfma_f32_16x16x32_bf16 v[78:81], v[184:187], v[208:211], v[78:81]
	v_mfma_f32_16x16x32_bf16 v[70:73], v[176:179], v[216:219], v[70:73]
	v_mfma_f32_16x16x32_bf16 v[66:69], v[184:187], v[216:219], v[66:69]
	s_setprio 0
	s_barrier
	s_add_u32 s12, s34, 0x80
	s_addc_u32 s13, s35, 0
	s_add_u32 s14, s90, 0x80
	s_addc_u32 s15, s91, 0
	s_add_i32 s24, s80, s37
	s_mov_b32 m0, s24
	ds_read_b128 v[188:191], v150 offset:49152
	ds_read_b128 v[192:195], v150 offset:50176
	ds_read_b128 v[196:199], v150 offset:51200
	ds_read_b128 v[200:203], v150 offset:52224
	ds_read_b128 v[204:207], v150 offset:53248
	ds_read_b128 v[208:211], v150 offset:54272
	ds_read_b128 v[212:215], v150 offset:55296
	ds_read_b128 v[216:219], v150 offset:56320
	global_load_lds_dwordx4 v132, s[12:13]
	s_add_i32 m0, s24, 0x2000
	s_add_u32 s24, s34, 0x100080
	s_addc_u32 s25, s35, 0
	s_add_i32 s34, s85, s37
	global_load_lds_dwordx4 v136, s[12:13]
	s_mov_b32 m0, s34
	s_nop 0
	global_load_lds_dwordx4 v132, s[24:25]
	s_add_i32 m0, s34, 0x2000
	s_nop 0
	global_load_lds_dwordx4 v136, s[24:25]
	s_mov_b32 m0, s43
	s_nop 0
	global_load_lds_dwordx4 v130, s[14:15]
	s_mov_b32 m0, s44
	s_nop 0
	global_load_lds_dwordx4 v134, s[14:15]
	s_waitcnt vmcnt(8)
	s_waitcnt lgkmcnt(0)
	s_barrier
	s_setprio 1
	s_waitcnt lgkmcnt(0)
	v_mfma_f32_16x16x32_bf16 v[62:65], v[152:155], v[188:191], v[62:65]
	v_mfma_f32_16x16x32_bf16 v[58:61], v[160:163], v[188:191], v[58:61]
	v_mfma_f32_16x16x32_bf16 v[50:53], v[152:155], v[196:199], v[50:53]
	v_mfma_f32_16x16x32_bf16 v[42:45], v[160:163], v[196:199], v[42:45]
	v_mfma_f32_16x16x32_bf16 v[34:37], v[152:155], v[204:207], v[34:37]
	v_mfma_f32_16x16x32_bf16 v[26:29], v[160:163], v[204:207], v[26:29]
	v_mfma_f32_16x16x32_bf16 v[18:21], v[152:155], v[212:215], v[18:21]
	v_mfma_f32_16x16x32_bf16 v[10:13], v[160:163], v[212:215], v[10:13]
	v_mfma_f32_16x16x32_bf16 v[62:65], v[156:159], v[192:195], v[62:65]
	v_mfma_f32_16x16x32_bf16 v[58:61], v[164:167], v[192:195], v[58:61]
	v_mfma_f32_16x16x32_bf16 v[50:53], v[156:159], v[200:203], v[50:53]
	v_mfma_f32_16x16x32_bf16 v[42:45], v[164:167], v[200:203], v[42:45]
	v_mfma_f32_16x16x32_bf16 v[34:37], v[156:159], v[208:211], v[34:37]
	v_mfma_f32_16x16x32_bf16 v[26:29], v[164:167], v[208:211], v[26:29]
	v_mfma_f32_16x16x32_bf16 v[18:21], v[156:159], v[216:219], v[18:21]
	v_mfma_f32_16x16x32_bf16 v[10:13], v[164:167], v[216:219], v[10:13]
	s_setprio 0
	s_setprio 1
	v_mfma_f32_16x16x32_bf16 v[54:57], v[168:171], v[188:191], v[54:57]
	v_mfma_f32_16x16x32_bf16 v[46:49], v[180:183], v[188:191], v[46:49]
	v_mfma_f32_16x16x32_bf16 v[38:41], v[168:171], v[196:199], v[38:41]
	v_mfma_f32_16x16x32_bf16 v[30:33], v[180:183], v[196:199], v[30:33]
	v_mfma_f32_16x16x32_bf16 v[22:25], v[168:171], v[204:207], v[22:25]
	v_mfma_f32_16x16x32_bf16 v[14:17], v[180:183], v[204:207], v[14:17]
	v_mfma_f32_16x16x32_bf16 v[6:9], v[168:171], v[212:215], v[6:9]
	v_mfma_f32_16x16x32_bf16 v[2:5], v[180:183], v[212:215], v[2:5]
	v_mfma_f32_16x16x32_bf16 v[54:57], v[176:179], v[192:195], v[54:57]
	v_mfma_f32_16x16x32_bf16 v[46:49], v[184:187], v[192:195], v[46:49]
	v_mfma_f32_16x16x32_bf16 v[38:41], v[176:179], v[200:203], v[38:41]
	v_mfma_f32_16x16x32_bf16 v[30:33], v[184:187], v[200:203], v[30:33]
	v_mfma_f32_16x16x32_bf16 v[22:25], v[176:179], v[208:211], v[22:25]
	v_mfma_f32_16x16x32_bf16 v[14:17], v[184:187], v[208:211], v[14:17]
	v_mfma_f32_16x16x32_bf16 v[6:9], v[176:179], v[216:219], v[6:9]
	v_mfma_f32_16x16x32_bf16 v[2:5], v[184:187], v[216:219], v[2:5]
	s_setprio 0
	s_barrier
	s_add_i32 s84, s84, 2
	s_add_u32 vcc_lo, vcc_lo, 0x100
	s_addc_u32 vcc_hi, vcc_hi, 0
	s_add_u32 s82, s82, 0x100
	s_addc_u32 s83, s83, 0
	s_cmp_gt_u32 s84, 61
	s_cbranch_scc0 .LBB0_220

.LBB0_562:
	s_ashr_i32 s61, s60, 31
	s_lshl_b64 s[24:25], s[60:61], 20
	s_add_u32 s62, s42, s24
	s_addc_u32 s63, s43, s25
	s_and_b64 s[24:25], s[4:5], exec
	s_cselect_b32 s30, s63, s11
	s_cselect_b32 s31, s62, s10
	s_ashr_i32 s47, s46, 31
	s_lshl_b64 s[24:25], s[46:47], 20
	s_add_u32 s78, s58, s24
	s_addc_u32 s79, s59, s25
	s_and_b64 s[24:25], s[4:5], exec
	s_cselect_b32 s47, s79, s35
	s_cselect_b32 s61, s78, s34
	s_add_u32 s82, s10, 0x80080
	s_addc_u32 s83, s11, 0
	s_add_u32 s91, s34, 0x100
	s_addc_u32 s92, s35, 0
	s_mov_b32 s93, -2
	s_waitcnt vmcnt(0)
	ds_read_b128 v[130:133], v187
	ds_read_b128 v[134:137], v187 offset:1024
	ds_read_b128 v[138:141], v187 offset:2048
	ds_read_b128 v[142:145], v187 offset:3072
	ds_read_b128 v[146:149], v188
	ds_read_b128 v[158:161], v188 offset:1024
	ds_read_b128 v[162:165], v188 offset:2048
	ds_read_b128 v[190:193], v188 offset:3072
	s_add_u32 s10, s82, 0xfff80080
	s_addc_u32 s11, s83, -1
	s_cmp_eq_u32 s93, 28
	s_cselect_b32 s35, s30, s11
	s_cselect_b32 s34, s31, s10
	s_cselect_b32 s11, s47, s92
	s_cselect_b32 s10, s61, s91
	s_add_i32 m0, s45, 0xc000
	ds_read_b128 v[194:197], v189
	ds_read_b128 v[198:201], v189 offset:1024
	ds_read_b128 v[202:205], v189 offset:2048
	ds_read_b128 v[206:209], v189 offset:3072
	ds_read_b128 v[210:213], v189 offset:4096
	ds_read_b128 v[214:217], v189 offset:5120
	ds_read_b128 v[218:221], v189 offset:6144
	ds_read_b128 v[222:225], v189 offset:7168
	global_load_lds_dwordx4 v150, s[82:83]
	s_add_i32 m0, s45, 0xe000
	s_nop 0
	global_load_lds_dwordx4 v152, s[82:83]
	s_waitcnt vmcnt(8)
	s_waitcnt lgkmcnt(0)
	s_barrier
	s_setprio 1
	s_waitcnt lgkmcnt(0)
	v_mfma_f32_16x16x32_bf16 v[126:129], v[130:133], v[194:197], 0
	v_mfma_f32_16x16x32_bf16 v[122:125], v[138:141], v[194:197], 0
	v_mfma_f32_16x16x32_bf16 v[110:113], v[130:133], v[202:205], 0
	v_mfma_f32_16x16x32_bf16 v[106:109], v[138:141], v[202:205], 0
	v_mfma_f32_16x16x32_bf16 v[94:97], v[130:133], v[210:213], 0
	v_mfma_f32_16x16x32_bf16 v[90:93], v[138:141], v[210:213], 0
	v_mfma_f32_16x16x32_bf16 v[78:81], v[130:133], v[218:221], 0
	v_mfma_f32_16x16x32_bf16 v[74:77], v[138:141], v[218:221], 0
	v_mfma_f32_16x16x32_bf16 v[126:129], v[134:137], v[198:201], v[126:129]
	v_mfma_f32_16x16x32_bf16 v[122:125], v[142:145], v[198:201], v[122:125]
	v_mfma_f32_16x16x32_bf16 v[110:113], v[134:137], v[206:209], v[110:113]
	v_mfma_f32_16x16x32_bf16 v[106:109], v[142:145], v[206:209], v[106:109]
	v_mfma_f32_16x16x32_bf16 v[94:97], v[134:137], v[214:217], v[94:97]
	v_mfma_f32_16x16x32_bf16 v[90:93], v[142:145], v[214:217], v[90:93]
	v_mfma_f32_16x16x32_bf16 v[78:81], v[134:137], v[222:225], v[78:81]
	v_mfma_f32_16x16x32_bf16 v[74:77], v[142:145], v[222:225], v[74:77]
	s_setprio 0
	s_setprio 1
	v_mfma_f32_16x16x32_bf16 v[118:121], v[146:149], v[194:197], 0
	v_mfma_f32_16x16x32_bf16 v[114:117], v[162:165], v[194:197], 0
	v_mfma_f32_16x16x32_bf16 v[102:105], v[146:149], v[202:205], 0
	v_mfma_f32_16x16x32_bf16 v[98:101], v[162:165], v[202:205], 0
	v_mfma_f32_16x16x32_bf16 v[86:89], v[146:149], v[210:213], 0
	v_mfma_f32_16x16x32_bf16 v[82:85], v[162:165], v[210:213], 0
	v_mfma_f32_16x16x32_bf16 v[70:73], v[146:149], v[218:221], 0
	v_mfma_f32_16x16x32_bf16 v[66:69], v[162:165], v[218:221], 0
	v_mfma_f32_16x16x32_bf16 v[118:121], v[158:161], v[198:201], v[118:121]
	v_mfma_f32_16x16x32_bf16 v[114:117], v[190:193], v[198:201], v[114:117]
	v_mfma_f32_16x16x32_bf16 v[102:105], v[158:161], v[206:209], v[102:105]
	v_mfma_f32_16x16x32_bf16 v[98:101], v[190:193], v[206:209], v[98:101]
	v_mfma_f32_16x16x32_bf16 v[86:89], v[158:161], v[214:217], v[86:89]
	v_mfma_f32_16x16x32_bf16 v[82:85], v[190:193], v[214:217], v[82:85]
	v_mfma_f32_16x16x32_bf16 v[70:73], v[158:161], v[222:225], v[70:73]
	v_mfma_f32_16x16x32_bf16 v[66:69], v[190:193], v[222:225], v[66:69]
	s_setprio 0
	s_barrier
	s_add_i32 s24, s87, s3
	s_mov_b32 m0, s24
	ds_read_b128 v[194:197], v189 offset:16384
	ds_read_b128 v[198:201], v189 offset:17408
	ds_read_b128 v[202:205], v189 offset:18432
	ds_read_b128 v[206:209], v189 offset:19456
	ds_read_b128 v[210:213], v189 offset:20480
	ds_read_b128 v[214:217], v189 offset:21504
	ds_read_b128 v[218:221], v189 offset:22528
	ds_read_b128 v[222:225], v189 offset:23552
	global_load_lds_dwordx4 v178, s[10:11]
	s_add_i32 m0, s24, 0x2000
	s_add_u32 s24, s10, 0x80000
	s_addc_u32 s25, s11, 0
	s_add_i32 s94, s88, s3
	global_load_lds_dwordx4 v182, s[10:11]
	s_mov_b32 m0, s94
	s_nop 0
	global_load_lds_dwordx4 v178, s[24:25]
	s_add_i32 m0, s94, 0x2000
	s_nop 0
	global_load_lds_dwordx4 v182, s[24:25]
	s_mov_b32 m0, s45
	s_nop 0
	global_load_lds_dwordx4 v176, s[34:35]
	s_mov_b32 m0, s50
	s_nop 0
	global_load_lds_dwordx4 v180, s[34:35]
	s_waitcnt vmcnt(8)
	s_waitcnt lgkmcnt(0)
	s_barrier
	s_setprio 1
	s_waitcnt lgkmcnt(0)
	v_mfma_f32_16x16x32_bf16 v[62:65], v[130:133], v[194:197], 0
	v_mfma_f32_16x16x32_bf16 v[58:61], v[138:141], v[194:197], 0
	v_mfma_f32_16x16x32_bf16 v[46:49], v[130:133], v[202:205], 0
	v_mfma_f32_16x16x32_bf16 v[42:45], v[138:141], v[202:205], 0
	v_mfma_f32_16x16x32_bf16 v[30:33], v[130:133], v[210:213], 0
	v_mfma_f32_16x16x32_bf16 v[26:29], v[138:141], v[210:213], 0
	v_mfma_f32_16x16x32_bf16 v[14:17], v[130:133], v[218:221], 0
	v_mfma_f32_16x16x32_bf16 v[10:13], v[138:141], v[218:221], 0
	v_mfma_f32_16x16x32_bf16 v[62:65], v[134:137], v[198:201], v[62:65]
	v_mfma_f32_16x16x32_bf16 v[58:61], v[142:145], v[198:201], v[58:61]
	v_mfma_f32_16x16x32_bf16 v[46:49], v[134:137], v[206:209], v[46:49]
	v_mfma_f32_16x16x32_bf16 v[42:45], v[142:145], v[206:209], v[42:45]
	v_mfma_f32_16x16x32_bf16 v[30:33], v[134:137], v[214:217], v[30:33]
	v_mfma_f32_16x16x32_bf16 v[26:29], v[142:145], v[214:217], v[26:29]
	v_mfma_f32_16x16x32_bf16 v[14:17], v[134:137], v[222:225], v[14:17]
	v_mfma_f32_16x16x32_bf16 v[10:13], v[142:145], v[222:225], v[10:13]
	s_setprio 0
	s_setprio 1
	v_mfma_f32_16x16x32_bf16 v[54:57], v[146:149], v[194:197], 0
	v_mfma_f32_16x16x32_bf16 v[50:53], v[162:165], v[194:197], 0
	v_mfma_f32_16x16x32_bf16 v[38:41], v[146:149], v[202:205], 0
	v_mfma_f32_16x16x32_bf16 v[34:37], v[162:165], v[202:205], 0
	v_mfma_f32_16x16x32_bf16 v[22:25], v[146:149], v[210:213], 0
	v_mfma_f32_16x16x32_bf16 v[18:21], v[162:165], v[210:213], 0
	v_mfma_f32_16x16x32_bf16 v[6:9], v[146:149], v[218:221], 0
	v_mfma_f32_16x16x32_bf16 v[2:5], v[162:165], v[218:221], 0
	v_mfma_f32_16x16x32_bf16 v[54:57], v[158:161], v[198:201], v[54:57]
	v_mfma_f32_16x16x32_bf16 v[50:53], v[190:193], v[198:201], v[50:53]
	v_mfma_f32_16x16x32_bf16 v[38:41], v[158:161], v[206:209], v[38:41]
	v_mfma_f32_16x16x32_bf16 v[34:37], v[190:193], v[206:209], v[34:37]
	v_mfma_f32_16x16x32_bf16 v[22:25], v[158:161], v[214:217], v[22:25]
	v_mfma_f32_16x16x32_bf16 v[18:21], v[190:193], v[214:217], v[18:21]
	v_mfma_f32_16x16x32_bf16 v[6:9], v[158:161], v[222:225], v[6:9]
	v_mfma_f32_16x16x32_bf16 v[2:5], v[190:193], v[222:225], v[2:5]
	s_setprio 0
	s_barrier
	s_add_i32 s94, 0, 0x18000
	s_add_i32 s95, 0, 0x1c000
	v_add_u32_e32 v142, s94, v185
	v_add_u32_e32 v190, s95, v185
	ds_read_b128 v[130:133], v142
	ds_read_b128 v[134:137], v142 offset:1024
	ds_read_b128 v[138:141], v142 offset:2048
	ds_read_b128 v[142:145], v142 offset:3072
	ds_read_b128 v[146:149], v190
	ds_read_b128 v[158:161], v190 offset:1024
	ds_read_b128 v[162:165], v190 offset:2048
	ds_read_b128 v[190:193], v190 offset:3072
	s_add_u32 s24, s34, 0x80000
	s_addc_u32 s25, s35, 0
	s_mov_b32 m0, s51
	ds_read_b128 v[194:197], v189 offset:32768
	ds_read_b128 v[198:201], v189 offset:33792
	ds_read_b128 v[202:205], v189 offset:34816
	ds_read_b128 v[206:209], v189 offset:35840
	ds_read_b128 v[210:213], v189 offset:36864
	ds_read_b128 v[214:217], v189 offset:37888
	ds_read_b128 v[218:221], v189 offset:38912
	ds_read_b128 v[222:225], v189 offset:39936
	global_load_lds_dwordx4 v176, s[24:25]
	s_mov_b32 m0, s75
	s_nop 0
	global_load_lds_dwordx4 v180, s[24:25]
	s_waitcnt vmcnt(8)
	s_waitcnt lgkmcnt(0)
	s_barrier
	s_setprio 1
	s_waitcnt lgkmcnt(0)
	v_mfma_f32_16x16x32_bf16 v[126:129], v[130:133], v[194:197], v[126:129]
	v_mfma_f32_16x16x32_bf16 v[122:125], v[138:141], v[194:197], v[122:125]
	v_mfma_f32_16x16x32_bf16 v[110:113], v[130:133], v[202:205], v[110:113]
	v_mfma_f32_16x16x32_bf16 v[106:109], v[138:141], v[202:205], v[106:109]
	v_mfma_f32_16x16x32_bf16 v[94:97], v[130:133], v[210:213], v[94:97]
	v_mfma_f32_16x16x32_bf16 v[90:93], v[138:141], v[210:213], v[90:93]
	v_mfma_f32_16x16x32_bf16 v[78:81], v[130:133], v[218:221], v[78:81]
	v_mfma_f32_16x16x32_bf16 v[74:77], v[138:141], v[218:221], v[74:77]
	v_mfma_f32_16x16x32_bf16 v[126:129], v[134:137], v[198:201], v[126:129]
	v_mfma_f32_16x16x32_bf16 v[122:125], v[142:145], v[198:201], v[122:125]
	v_mfma_f32_16x16x32_bf16 v[110:113], v[134:137], v[206:209], v[110:113]
	v_mfma_f32_16x16x32_bf16 v[106:109], v[142:145], v[206:209], v[106:109]
	v_mfma_f32_16x16x32_bf16 v[94:97], v[134:137], v[214:217], v[94:97]
	v_mfma_f32_16x16x32_bf16 v[90:93], v[142:145], v[214:217], v[90:93]
	v_mfma_f32_16x16x32_bf16 v[78:81], v[134:137], v[222:225], v[78:81]
	v_mfma_f32_16x16x32_bf16 v[74:77], v[142:145], v[222:225], v[74:77]
	s_setprio 0
	s_setprio 1
	v_mfma_f32_16x16x32_bf16 v[118:121], v[146:149], v[194:197], v[118:121]
	v_mfma_f32_16x16x32_bf16 v[114:117], v[162:165], v[194:197], v[114:117]
	v_mfma_f32_16x16x32_bf16 v[102:105], v[146:149], v[202:205], v[102:105]
	v_mfma_f32_16x16x32_bf16 v[98:101], v[162:165], v[202:205], v[98:101]
	v_mfma_f32_16x16x32_bf16 v[86:89], v[146:149], v[210:213], v[86:89]
	v_mfma_f32_16x16x32_bf16 v[82:85], v[162:165], v[210:213], v[82:85]
	v_mfma_f32_16x16x32_bf16 v[70:73], v[146:149], v[218:221], v[70:73]
	v_mfma_f32_16x16x32_bf16 v[66:69], v[162:165], v[218:221], v[66:69]
	v_mfma_f32_16x16x32_bf16 v[118:121], v[158:161], v[198:201], v[118:121]
	v_mfma_f32_16x16x32_bf16 v[114:117], v[190:193], v[198:201], v[114:117]
	v_mfma_f32_16x16x32_bf16 v[102:105], v[158:161], v[206:209], v[102:105]
	v_mfma_f32_16x16x32_bf16 v[98:101], v[190:193], v[206:209], v[98:101]
	v_mfma_f32_16x16x32_bf16 v[86:89], v[158:161], v[214:217], v[86:89]
	v_mfma_f32_16x16x32_bf16 v[82:85], v[190:193], v[214:217], v[82:85]
	v_mfma_f32_16x16x32_bf16 v[70:73], v[158:161], v[222:225], v[70:73]
	v_mfma_f32_16x16x32_bf16 v[66:69], v[190:193], v[222:225], v[66:69]
	s_setprio 0
	s_barrier
	s_add_u32 s12, s10, 0x80
	s_addc_u32 s13, s11, 0
	s_add_u32 s14, s34, 0x80
	s_addc_u32 s15, s35, 0
	s_add_i32 s24, s94, s3
	s_mov_b32 m0, s24
	ds_read_b128 v[194:197], v189 offset:49152
	ds_read_b128 v[198:201], v189 offset:50176
	ds_read_b128 v[202:205], v189 offset:51200
	ds_read_b128 v[206:209], v189 offset:52224
	ds_read_b128 v[210:213], v189 offset:53248
	ds_read_b128 v[214:217], v189 offset:54272
	ds_read_b128 v[218:221], v189 offset:55296
	ds_read_b128 v[222:225], v189 offset:56320
	global_load_lds_dwordx4 v178, s[12:13]
	s_add_i32 m0, s24, 0x2000
	s_add_u32 s10, s10, 0x80080
	s_addc_u32 s11, s11, 0
	s_add_i32 s24, s95, s3
	global_load_lds_dwordx4 v182, s[12:13]
	s_mov_b32 m0, s24
	s_nop 0
	global_load_lds_dwordx4 v178, s[10:11]
	s_add_i32 m0, s24, 0x2000
	s_nop 0
	global_load_lds_dwordx4 v182, s[10:11]
	s_mov_b32 m0, s84
	s_nop 0
	global_load_lds_dwordx4 v176, s[14:15]
	s_mov_b32 m0, s85
	s_nop 0
	global_load_lds_dwordx4 v180, s[14:15]
	s_waitcnt vmcnt(8)
	s_waitcnt lgkmcnt(0)
	s_barrier
	s_setprio 1
	s_waitcnt lgkmcnt(0)
	v_mfma_f32_16x16x32_bf16 v[62:65], v[130:133], v[194:197], v[62:65]
	v_mfma_f32_16x16x32_bf16 v[58:61], v[138:141], v[194:197], v[58:61]
	v_mfma_f32_16x16x32_bf16 v[46:49], v[130:133], v[202:205], v[46:49]
	v_mfma_f32_16x16x32_bf16 v[42:45], v[138:141], v[202:205], v[42:45]
	v_mfma_f32_16x16x32_bf16 v[30:33], v[130:133], v[210:213], v[30:33]
	v_mfma_f32_16x16x32_bf16 v[26:29], v[138:141], v[210:213], v[26:29]
	v_mfma_f32_16x16x32_bf16 v[14:17], v[130:133], v[218:221], v[14:17]
	v_mfma_f32_16x16x32_bf16 v[10:13], v[138:141], v[218:221], v[10:13]
	v_mfma_f32_16x16x32_bf16 v[62:65], v[134:137], v[198:201], v[62:65]
	v_mfma_f32_16x16x32_bf16 v[58:61], v[142:145], v[198:201], v[58:61]
	v_mfma_f32_16x16x32_bf16 v[46:49], v[134:137], v[206:209], v[46:49]
	v_mfma_f32_16x16x32_bf16 v[42:45], v[142:145], v[206:209], v[42:45]
	v_mfma_f32_16x16x32_bf16 v[30:33], v[134:137], v[214:217], v[30:33]
	v_mfma_f32_16x16x32_bf16 v[26:29], v[142:145], v[214:217], v[26:29]
	v_mfma_f32_16x16x32_bf16 v[14:17], v[134:137], v[222:225], v[14:17]
	v_mfma_f32_16x16x32_bf16 v[10:13], v[142:145], v[222:225], v[10:13]
	s_setprio 0
	s_setprio 1
	v_mfma_f32_16x16x32_bf16 v[54:57], v[146:149], v[194:197], v[54:57]
	v_mfma_f32_16x16x32_bf16 v[50:53], v[162:165], v[194:197], v[50:53]
	v_mfma_f32_16x16x32_bf16 v[38:41], v[146:149], v[202:205], v[38:41]
	v_mfma_f32_16x16x32_bf16 v[34:37], v[162:165], v[202:205], v[34:37]
	v_mfma_f32_16x16x32_bf16 v[22:25], v[146:149], v[210:213], v[22:25]
	v_mfma_f32_16x16x32_bf16 v[18:21], v[162:165], v[210:213], v[18:21]
	v_mfma_f32_16x16x32_bf16 v[6:9], v[146:149], v[218:221], v[6:9]
	v_mfma_f32_16x16x32_bf16 v[2:5], v[162:165], v[218:221], v[2:5]
	v_mfma_f32_16x16x32_bf16 v[54:57], v[158:161], v[198:201], v[54:57]
	v_mfma_f32_16x16x32_bf16 v[50:53], v[190:193], v[198:201], v[50:53]
	v_mfma_f32_16x16x32_bf16 v[38:41], v[158:161], v[206:209], v[38:41]
	v_mfma_f32_16x16x32_bf16 v[34:37], v[190:193], v[206:209], v[34:37]
	v_mfma_f32_16x16x32_bf16 v[22:25], v[158:161], v[214:217], v[22:25]
	v_mfma_f32_16x16x32_bf16 v[18:21], v[190:193], v[214:217], v[18:21]
	v_mfma_f32_16x16x32_bf16 v[6:9], v[158:161], v[222:225], v[6:9]
	v_mfma_f32_16x16x32_bf16 v[2:5], v[190:193], v[222:225], v[2:5]
	s_setprio 0
	s_barrier
	s_add_i32 s93, s93, 2
	s_add_u32 s82, s82, 0x100
	s_addc_u32 s83, s83, 0
	s_add_u32 s91, s91, 0x100
	s_addc_u32 s92, s92, 0
	s_cmp_gt_u32 s93, 29
	s_cbranch_scc1 .Lpeel_exit_1
.LBB0_563:
	ds_read_b128 v[130:133], v187
	ds_read_b128 v[134:137], v187 offset:1024
	ds_read_b128 v[138:141], v187 offset:2048
	ds_read_b128 v[142:145], v187 offset:3072
	ds_read_b128 v[146:149], v188
	ds_read_b128 v[158:161], v188 offset:1024
	ds_read_b128 v[162:165], v188 offset:2048
	ds_read_b128 v[190:193], v188 offset:3072
	s_add_u32 s10, s82, 0xfff80080
	s_addc_u32 s11, s83, -1
	s_cmp_eq_u32 s93, 28
	s_cselect_b32 s35, s30, s11
	s_cselect_b32 s34, s31, s10
	s_cselect_b32 s11, s47, s92
	s_cselect_b32 s10, s61, s91
	s_add_i32 m0, s45, 0xc000
	ds_read_b128 v[194:197], v189
	ds_read_b128 v[198:201], v189 offset:1024
	ds_read_b128 v[202:205], v189 offset:2048
	ds_read_b128 v[206:209], v189 offset:3072
	ds_read_b128 v[210:213], v189 offset:4096
	ds_read_b128 v[214:217], v189 offset:5120
	ds_read_b128 v[218:221], v189 offset:6144
	ds_read_b128 v[222:225], v189 offset:7168
	global_load_lds_dwordx4 v150, s[82:83]
	s_add_i32 m0, s45, 0xe000
	s_nop 0
	global_load_lds_dwordx4 v152, s[82:83]
	s_waitcnt vmcnt(8)
	s_waitcnt lgkmcnt(0)
	s_barrier
	s_setprio 1
	s_waitcnt lgkmcnt(0)
	v_mfma_f32_16x16x32_bf16 v[126:129], v[130:133], v[194:197], v[126:129]
	v_mfma_f32_16x16x32_bf16 v[122:125], v[138:141], v[194:197], v[122:125]
	v_mfma_f32_16x16x32_bf16 v[110:113], v[130:133], v[202:205], v[110:113]
	v_mfma_f32_16x16x32_bf16 v[106:109], v[138:141], v[202:205], v[106:109]
	v_mfma_f32_16x16x32_bf16 v[94:97], v[130:133], v[210:213], v[94:97]
	v_mfma_f32_16x16x32_bf16 v[90:93], v[138:141], v[210:213], v[90:93]
	v_mfma_f32_16x16x32_bf16 v[78:81], v[130:133], v[218:221], v[78:81]
	v_mfma_f32_16x16x32_bf16 v[74:77], v[138:141], v[218:221], v[74:77]
	v_mfma_f32_16x16x32_bf16 v[126:129], v[134:137], v[198:201], v[126:129]
	v_mfma_f32_16x16x32_bf16 v[122:125], v[142:145], v[198:201], v[122:125]
	v_mfma_f32_16x16x32_bf16 v[110:113], v[134:137], v[206:209], v[110:113]
	v_mfma_f32_16x16x32_bf16 v[106:109], v[142:145], v[206:209], v[106:109]
	v_mfma_f32_16x16x32_bf16 v[94:97], v[134:137], v[214:217], v[94:97]
	v_mfma_f32_16x16x32_bf16 v[90:93], v[142:145], v[214:217], v[90:93]
	v_mfma_f32_16x16x32_bf16 v[78:81], v[134:137], v[222:225], v[78:81]
	v_mfma_f32_16x16x32_bf16 v[74:77], v[142:145], v[222:225], v[74:77]
	s_setprio 0
	s_setprio 1
	v_mfma_f32_16x16x32_bf16 v[118:121], v[146:149], v[194:197], v[118:121]
	v_mfma_f32_16x16x32_bf16 v[114:117], v[162:165], v[194:197], v[114:117]
	v_mfma_f32_16x16x32_bf16 v[102:105], v[146:149], v[202:205], v[102:105]
	v_mfma_f32_16x16x32_bf16 v[98:101], v[162:165], v[202:205], v[98:101]
	v_mfma_f32_16x16x32_bf16 v[86:89], v[146:149], v[210:213], v[86:89]
	v_mfma_f32_16x16x32_bf16 v[82:85], v[162:165], v[210:213], v[82:85]
	v_mfma_f32_16x16x32_bf16 v[70:73], v[146:149], v[218:221], v[70:73]
	v_mfma_f32_16x16x32_bf16 v[66:69], v[162:165], v[218:221], v[66:69]
	v_mfma_f32_16x16x32_bf16 v[118:121], v[158:161], v[198:201], v[118:121]
	v_mfma_f32_16x16x32_bf16 v[114:117], v[190:193], v[198:201], v[114:117]
	v_mfma_f32_16x16x32_bf16 v[102:105], v[158:161], v[206:209], v[102:105]
	v_mfma_f32_16x16x32_bf16 v[98:101], v[190:193], v[206:209], v[98:101]
	v_mfma_f32_16x16x32_bf16 v[86:89], v[158:161], v[214:217], v[86:89]
	v_mfma_f32_16x16x32_bf16 v[82:85], v[190:193], v[214:217], v[82:85]
	v_mfma_f32_16x16x32_bf16 v[70:73], v[158:161], v[222:225], v[70:73]
	v_mfma_f32_16x16x32_bf16 v[66:69], v[190:193], v[222:225], v[66:69]
	s_setprio 0
	s_barrier
	s_add_i32 s24, s87, s3
	s_mov_b32 m0, s24
	ds_read_b128 v[194:197], v189 offset:16384
	ds_read_b128 v[198:201], v189 offset:17408
	ds_read_b128 v[202:205], v189 offset:18432
	ds_read_b128 v[206:209], v189 offset:19456
	ds_read_b128 v[210:213], v189 offset:20480
	ds_read_b128 v[214:217], v189 offset:21504
	ds_read_b128 v[218:221], v189 offset:22528
	ds_read_b128 v[222:225], v189 offset:23552
	global_load_lds_dwordx4 v178, s[10:11]
	s_add_i32 m0, s24, 0x2000
	s_add_u32 s24, s10, 0x80000
	s_addc_u32 s25, s11, 0
	s_add_i32 s94, s88, s3
	global_load_lds_dwordx4 v182, s[10:11]
	s_mov_b32 m0, s94
	s_nop 0
	global_load_lds_dwordx4 v178, s[24:25]
	s_add_i32 m0, s94, 0x2000
	s_nop 0
	global_load_lds_dwordx4 v182, s[24:25]
	s_mov_b32 m0, s45
	s_nop 0
	global_load_lds_dwordx4 v176, s[34:35]
	s_mov_b32 m0, s50
	s_nop 0
	global_load_lds_dwordx4 v180, s[34:35]
	s_waitcnt vmcnt(8)
	s_waitcnt lgkmcnt(0)
	s_barrier
	s_setprio 1
	s_waitcnt lgkmcnt(0)
	v_mfma_f32_16x16x32_bf16 v[62:65], v[130:133], v[194:197], v[62:65]
	v_mfma_f32_16x16x32_bf16 v[58:61], v[138:141], v[194:197], v[58:61]
	v_mfma_f32_16x16x32_bf16 v[46:49], v[130:133], v[202:205], v[46:49]
	v_mfma_f32_16x16x32_bf16 v[42:45], v[138:141], v[202:205], v[42:45]
	v_mfma_f32_16x16x32_bf16 v[30:33], v[130:133], v[210:213], v[30:33]
	v_mfma_f32_16x16x32_bf16 v[26:29], v[138:141], v[210:213], v[26:29]
	v_mfma_f32_16x16x32_bf16 v[14:17], v[130:133], v[218:221], v[14:17]
	v_mfma_f32_16x16x32_bf16 v[10:13], v[138:141], v[218:221], v[10:13]
	v_mfma_f32_16x16x32_bf16 v[62:65], v[134:137], v[198:201], v[62:65]
	v_mfma_f32_16x16x32_bf16 v[58:61], v[142:145], v[198:201], v[58:61]
	v_mfma_f32_16x16x32_bf16 v[46:49], v[134:137], v[206:209], v[46:49]
	v_mfma_f32_16x16x32_bf16 v[42:45], v[142:145], v[206:209], v[42:45]
	v_mfma_f32_16x16x32_bf16 v[30:33], v[134:137], v[214:217], v[30:33]
	v_mfma_f32_16x16x32_bf16 v[26:29], v[142:145], v[214:217], v[26:29]
	v_mfma_f32_16x16x32_bf16 v[14:17], v[134:137], v[222:225], v[14:17]
	v_mfma_f32_16x16x32_bf16 v[10:13], v[142:145], v[222:225], v[10:13]
	s_setprio 0
	s_setprio 1
	v_mfma_f32_16x16x32_bf16 v[54:57], v[146:149], v[194:197], v[54:57]
	v_mfma_f32_16x16x32_bf16 v[50:53], v[162:165], v[194:197], v[50:53]
	v_mfma_f32_16x16x32_bf16 v[38:41], v[146:149], v[202:205], v[38:41]
	v_mfma_f32_16x16x32_bf16 v[34:37], v[162:165], v[202:205], v[34:37]
	v_mfma_f32_16x16x32_bf16 v[22:25], v[146:149], v[210:213], v[22:25]
	v_mfma_f32_16x16x32_bf16 v[18:21], v[162:165], v[210:213], v[18:21]
	v_mfma_f32_16x16x32_bf16 v[6:9], v[146:149], v[218:221], v[6:9]
	v_mfma_f32_16x16x32_bf16 v[2:5], v[162:165], v[218:221], v[2:5]
	v_mfma_f32_16x16x32_bf16 v[54:57], v[158:161], v[198:201], v[54:57]
	v_mfma_f32_16x16x32_bf16 v[50:53], v[190:193], v[198:201], v[50:53]
	v_mfma_f32_16x16x32_bf16 v[38:41], v[158:161], v[206:209], v[38:41]
	v_mfma_f32_16x16x32_bf16 v[34:37], v[190:193], v[206:209], v[34:37]
	v_mfma_f32_16x16x32_bf16 v[22:25], v[158:161], v[214:217], v[22:25]
	v_mfma_f32_16x16x32_bf16 v[18:21], v[190:193], v[214:217], v[18:21]
	v_mfma_f32_16x16x32_bf16 v[6:9], v[158:161], v[222:225], v[6:9]
	v_mfma_f32_16x16x32_bf16 v[2:5], v[190:193], v[222:225], v[2:5]
	s_setprio 0
	s_barrier
	s_add_i32 s94, 0, 0x18000
	s_add_i32 s95, 0, 0x1c000
	v_add_u32_e32 v142, s94, v185
	v_add_u32_e32 v190, s95, v185
	ds_read_b128 v[130:133], v142
	ds_read_b128 v[134:137], v142 offset:1024
	ds_read_b128 v[138:141], v142 offset:2048
	ds_read_b128 v[142:145], v142 offset:3072
	ds_read_b128 v[146:149], v190
	ds_read_b128 v[158:161], v190 offset:1024
	ds_read_b128 v[162:165], v190 offset:2048
	ds_read_b128 v[190:193], v190 offset:3072
	s_add_u32 s24, s34, 0x80000
	s_addc_u32 s25, s35, 0
	s_mov_b32 m0, s51
	ds_read_b128 v[194:197], v189 offset:32768
	ds_read_b128 v[198:201], v189 offset:33792
	ds_read_b128 v[202:205], v189 offset:34816
	ds_read_b128 v[206:209], v189 offset:35840
	ds_read_b128 v[210:213], v189 offset:36864
	ds_read_b128 v[214:217], v189 offset:37888
	ds_read_b128 v[218:221], v189 offset:38912
	ds_read_b128 v[222:225], v189 offset:39936
	global_load_lds_dwordx4 v176, s[24:25]
	s_mov_b32 m0, s75
	s_nop 0
	global_load_lds_dwordx4 v180, s[24:25]
	s_waitcnt vmcnt(8)
	s_waitcnt lgkmcnt(0)
	s_barrier
	s_setprio 1
	s_waitcnt lgkmcnt(0)
	v_mfma_f32_16x16x32_bf16 v[126:129], v[130:133], v[194:197], v[126:129]
	v_mfma_f32_16x16x32_bf16 v[122:125], v[138:141], v[194:197], v[122:125]
	v_mfma_f32_16x16x32_bf16 v[110:113], v[130:133], v[202:205], v[110:113]
	v_mfma_f32_16x16x32_bf16 v[106:109], v[138:141], v[202:205], v[106:109]
	v_mfma_f32_16x16x32_bf16 v[94:97], v[130:133], v[210:213], v[94:97]
	v_mfma_f32_16x16x32_bf16 v[90:93], v[138:141], v[210:213], v[90:93]
	v_mfma_f32_16x16x32_bf16 v[78:81], v[130:133], v[218:221], v[78:81]
	v_mfma_f32_16x16x32_bf16 v[74:77], v[138:141], v[218:221], v[74:77]
	v_mfma_f32_16x16x32_bf16 v[126:129], v[134:137], v[198:201], v[126:129]
	v_mfma_f32_16x16x32_bf16 v[122:125], v[142:145], v[198:201], v[122:125]
	v_mfma_f32_16x16x32_bf16 v[110:113], v[134:137], v[206:209], v[110:113]
	v_mfma_f32_16x16x32_bf16 v[106:109], v[142:145], v[206:209], v[106:109]
	v_mfma_f32_16x16x32_bf16 v[94:97], v[134:137], v[214:217], v[94:97]
	v_mfma_f32_16x16x32_bf16 v[90:93], v[142:145], v[214:217], v[90:93]
	v_mfma_f32_16x16x32_bf16 v[78:81], v[134:137], v[222:225], v[78:81]
	v_mfma_f32_16x16x32_bf16 v[74:77], v[142:145], v[222:225], v[74:77]
	s_setprio 0
	s_setprio 1
	v_mfma_f32_16x16x32_bf16 v[118:121], v[146:149], v[194:197], v[118:121]
	v_mfma_f32_16x16x32_bf16 v[114:117], v[162:165], v[194:197], v[114:117]
	v_mfma_f32_16x16x32_bf16 v[102:105], v[146:149], v[202:205], v[102:105]
	v_mfma_f32_16x16x32_bf16 v[98:101], v[162:165], v[202:205], v[98:101]
	v_mfma_f32_16x16x32_bf16 v[86:89], v[146:149], v[210:213], v[86:89]
	v_mfma_f32_16x16x32_bf16 v[82:85], v[162:165], v[210:213], v[82:85]
	v_mfma_f32_16x16x32_bf16 v[70:73], v[146:149], v[218:221], v[70:73]
	v_mfma_f32_16x16x32_bf16 v[66:69], v[162:165], v[218:221], v[66:69]
	v_mfma_f32_16x16x32_bf16 v[118:121], v[158:161], v[198:201], v[118:121]
	v_mfma_f32_16x16x32_bf16 v[114:117], v[190:193], v[198:201], v[114:117]
	v_mfma_f32_16x16x32_bf16 v[102:105], v[158:161], v[206:209], v[102:105]
	v_mfma_f32_16x16x32_bf16 v[98:101], v[190:193], v[206:209], v[98:101]
	v_mfma_f32_16x16x32_bf16 v[86:89], v[158:161], v[214:217], v[86:89]
	v_mfma_f32_16x16x32_bf16 v[82:85], v[190:193], v[214:217], v[82:85]
	v_mfma_f32_16x16x32_bf16 v[70:73], v[158:161], v[222:225], v[70:73]
	v_mfma_f32_16x16x32_bf16 v[66:69], v[190:193], v[222:225], v[66:69]
	s_setprio 0
	s_barrier
	s_add_u32 s12, s10, 0x80
	s_addc_u32 s13, s11, 0
	s_add_u32 s14, s34, 0x80
	s_addc_u32 s15, s35, 0
	s_add_i32 s24, s94, s3
	s_mov_b32 m0, s24
	ds_read_b128 v[194:197], v189 offset:49152
	ds_read_b128 v[198:201], v189 offset:50176
	ds_read_b128 v[202:205], v189 offset:51200
	ds_read_b128 v[206:209], v189 offset:52224
	ds_read_b128 v[210:213], v189 offset:53248
	ds_read_b128 v[214:217], v189 offset:54272
	ds_read_b128 v[218:221], v189 offset:55296
	ds_read_b128 v[222:225], v189 offset:56320
	global_load_lds_dwordx4 v178, s[12:13]
	s_add_i32 m0, s24, 0x2000
	s_add_u32 s10, s10, 0x80080
	s_addc_u32 s11, s11, 0
	s_add_i32 s24, s95, s3
	global_load_lds_dwordx4 v182, s[12:13]
	s_mov_b32 m0, s24
	s_nop 0
	global_load_lds_dwordx4 v178, s[10:11]
	s_add_i32 m0, s24, 0x2000
	s_nop 0
	global_load_lds_dwordx4 v182, s[10:11]
	s_mov_b32 m0, s84
	s_nop 0
	global_load_lds_dwordx4 v176, s[14:15]
	s_mov_b32 m0, s85
	s_nop 0
	global_load_lds_dwordx4 v180, s[14:15]
	s_waitcnt vmcnt(8)
	s_waitcnt lgkmcnt(0)
	s_barrier
	s_setprio 1
	s_waitcnt lgkmcnt(0)
	v_mfma_f32_16x16x32_bf16 v[62:65], v[130:133], v[194:197], v[62:65]
	v_mfma_f32_16x16x32_bf16 v[58:61], v[138:141], v[194:197], v[58:61]
	v_mfma_f32_16x16x32_bf16 v[46:49], v[130:133], v[202:205], v[46:49]
	v_mfma_f32_16x16x32_bf16 v[42:45], v[138:141], v[202:205], v[42:45]
	v_mfma_f32_16x16x32_bf16 v[30:33], v[130:133], v[210:213], v[30:33]
	v_mfma_f32_16x16x32_bf16 v[26:29], v[138:141], v[210:213], v[26:29]
	v_mfma_f32_16x16x32_bf16 v[14:17], v[130:133], v[218:221], v[14:17]
	v_mfma_f32_16x16x32_bf16 v[10:13], v[138:141], v[218:221], v[10:13]
	v_mfma_f32_16x16x32_bf16 v[62:65], v[134:137], v[198:201], v[62:65]
	v_mfma_f32_16x16x32_bf16 v[58:61], v[142:145], v[198:201], v[58:61]
	v_mfma_f32_16x16x32_bf16 v[46:49], v[134:137], v[206:209], v[46:49]
	v_mfma_f32_16x16x32_bf16 v[42:45], v[142:145], v[206:209], v[42:45]
	v_mfma_f32_16x16x32_bf16 v[30:33], v[134:137], v[214:217], v[30:33]
	v_mfma_f32_16x16x32_bf16 v[26:29], v[142:145], v[214:217], v[26:29]
	v_mfma_f32_16x16x32_bf16 v[14:17], v[134:137], v[222:225], v[14:17]
	v_mfma_f32_16x16x32_bf16 v[10:13], v[142:145], v[222:225], v[10:13]
	s_setprio 0
	s_setprio 1
	v_mfma_f32_16x16x32_bf16 v[54:57], v[146:149], v[194:197], v[54:57]
	v_mfma_f32_16x16x32_bf16 v[50:53], v[162:165], v[194:197], v[50:53]
	v_mfma_f32_16x16x32_bf16 v[38:41], v[146:149], v[202:205], v[38:41]
	v_mfma_f32_16x16x32_bf16 v[34:37], v[162:165], v[202:205], v[34:37]
	v_mfma_f32_16x16x32_bf16 v[22:25], v[146:149], v[210:213], v[22:25]
	v_mfma_f32_16x16x32_bf16 v[18:21], v[162:165], v[210:213], v[18:21]
	v_mfma_f32_16x16x32_bf16 v[6:9], v[146:149], v[218:221], v[6:9]
	v_mfma_f32_16x16x32_bf16 v[2:5], v[162:165], v[218:221], v[2:5]
	v_mfma_f32_16x16x32_bf16 v[54:57], v[158:161], v[198:201], v[54:57]
	v_mfma_f32_16x16x32_bf16 v[50:53], v[190:193], v[198:201], v[50:53]
	v_mfma_f32_16x16x32_bf16 v[38:41], v[158:161], v[206:209], v[38:41]
	v_mfma_f32_16x16x32_bf16 v[34:37], v[190:193], v[206:209], v[34:37]
	v_mfma_f32_16x16x32_bf16 v[22:25], v[158:161], v[214:217], v[22:25]
	v_mfma_f32_16x16x32_bf16 v[18:21], v[190:193], v[214:217], v[18:21]
	v_mfma_f32_16x16x32_bf16 v[6:9], v[158:161], v[222:225], v[6:9]
	v_mfma_f32_16x16x32_bf16 v[2:5], v[190:193], v[222:225], v[2:5]
	s_setprio 0
	s_barrier
	s_add_i32 s93, s93, 2
	s_add_u32 s82, s82, 0x100
	s_addc_u32 s83, s83, 0
	s_add_u32 s91, s91, 0x100
	s_addc_u32 s92, s92, 0
	s_cmp_gt_u32 s93, 29
	s_cbranch_scc0 .LBB0_563

.LBB0_578:
	s_ashr_i32 s47, s46, 31
	s_lshl_b64 s[24:25], s[46:47], 20
	s_add_u32 s58, s6, s24
	s_addc_u32 s59, s7, s25
	s_and_b64 s[24:25], s[4:5], exec
	s_cselect_b32 s30, s59, s11
	s_cselect_b32 s31, s58, s10
	s_ashr_i32 s41, s40, 31
	s_lshl_b64 s[24:25], s[40:41], 20
	v_readlane_b32 s12, v255, 48
	v_readlane_b32 s13, v255, 49
	s_add_u32 s60, s12, s24
	s_addc_u32 s61, s13, s25
	s_and_b64 s[24:25], s[4:5], exec
	s_cselect_b32 s41, s61, s35
	s_cselect_b32 s47, s60, s34
	s_add_u32 s78, s10, 0x80080
	s_addc_u32 s79, s11, 0
	s_add_u32 s88, s34, 0x100
	s_addc_u32 s89, s35, 0
	s_mov_b32 s90, -2
	s_waitcnt vmcnt(0)
	ds_read_b128 v[130:133], v1
	ds_read_b128 v[134:137], v1 offset:1024
	ds_read_b128 v[138:141], v1 offset:2048
	ds_read_b128 v[142:145], v1 offset:3072
	ds_read_b128 v[146:149], v206
	ds_read_b128 v[150:153], v206 offset:1024
	ds_read_b128 v[154:157], v206 offset:2048
	ds_read_b128 v[158:161], v206 offset:3072
	s_add_u32 s10, s78, 0xfff80080
	s_addc_u32 s11, s79, -1
	s_cmp_eq_u32 s90, 28
	s_cselect_b32 s35, s30, s11
	s_cselect_b32 s34, s31, s10
	s_cselect_b32 s11, s41, s89
	s_cselect_b32 s10, s47, s88
	s_add_i32 m0, s50, 0xc000
	ds_read_b128 v[162:165], v207
	ds_read_b128 v[166:169], v207 offset:1024
	ds_read_b128 v[170:173], v207 offset:2048
	ds_read_b128 v[192:195], v207 offset:3072
	ds_read_b128 v[196:199], v207 offset:4096
	ds_read_b128 v[200:203], v207 offset:5120
	ds_read_b128 v[208:211], v207 offset:6144
	ds_read_b128 v[212:215], v207 offset:7168
	global_load_lds_dwordx4 v184, s[78:79]
	s_add_i32 m0, s50, 0xe000
	s_nop 0
	global_load_lds_dwordx4 v186, s[78:79]
	s_waitcnt vmcnt(8)
	s_waitcnt lgkmcnt(0)
	s_barrier
	s_setprio 1
	s_waitcnt lgkmcnt(0)
	v_mfma_f32_16x16x32_bf16 v[126:129], v[130:133], v[162:165], 0
	v_mfma_f32_16x16x32_bf16 v[122:125], v[138:141], v[162:165], 0
	v_mfma_f32_16x16x32_bf16 v[110:113], v[130:133], v[170:173], 0
	v_mfma_f32_16x16x32_bf16 v[106:109], v[138:141], v[170:173], 0
	v_mfma_f32_16x16x32_bf16 v[94:97], v[130:133], v[196:199], 0
	v_mfma_f32_16x16x32_bf16 v[90:93], v[138:141], v[196:199], 0
	v_mfma_f32_16x16x32_bf16 v[78:81], v[130:133], v[208:211], 0
	v_mfma_f32_16x16x32_bf16 v[74:77], v[138:141], v[208:211], 0
	v_mfma_f32_16x16x32_bf16 v[126:129], v[134:137], v[166:169], v[126:129]
	v_mfma_f32_16x16x32_bf16 v[122:125], v[142:145], v[166:169], v[122:125]
	v_mfma_f32_16x16x32_bf16 v[110:113], v[134:137], v[192:195], v[110:113]
	v_mfma_f32_16x16x32_bf16 v[106:109], v[142:145], v[192:195], v[106:109]
	v_mfma_f32_16x16x32_bf16 v[94:97], v[134:137], v[200:203], v[94:97]
	v_mfma_f32_16x16x32_bf16 v[90:93], v[142:145], v[200:203], v[90:93]
	v_mfma_f32_16x16x32_bf16 v[78:81], v[134:137], v[212:215], v[78:81]
	v_mfma_f32_16x16x32_bf16 v[74:77], v[142:145], v[212:215], v[74:77]
	s_setprio 0
	s_setprio 1
	v_mfma_f32_16x16x32_bf16 v[118:121], v[146:149], v[162:165], 0
	v_mfma_f32_16x16x32_bf16 v[114:117], v[154:157], v[162:165], 0
	v_mfma_f32_16x16x32_bf16 v[102:105], v[146:149], v[170:173], 0
	v_mfma_f32_16x16x32_bf16 v[98:101], v[154:157], v[170:173], 0
	v_mfma_f32_16x16x32_bf16 v[86:89], v[146:149], v[196:199], 0
	v_mfma_f32_16x16x32_bf16 v[82:85], v[154:157], v[196:199], 0
	v_mfma_f32_16x16x32_bf16 v[70:73], v[146:149], v[208:211], 0
	v_mfma_f32_16x16x32_bf16 v[66:69], v[154:157], v[208:211], 0
	v_mfma_f32_16x16x32_bf16 v[118:121], v[150:153], v[166:169], v[118:121]
	v_mfma_f32_16x16x32_bf16 v[114:117], v[158:161], v[166:169], v[114:117]
	v_mfma_f32_16x16x32_bf16 v[102:105], v[150:153], v[192:195], v[102:105]
	v_mfma_f32_16x16x32_bf16 v[98:101], v[158:161], v[192:195], v[98:101]
	v_mfma_f32_16x16x32_bf16 v[86:89], v[150:153], v[200:203], v[86:89]
	v_mfma_f32_16x16x32_bf16 v[82:85], v[158:161], v[200:203], v[82:85]
	v_mfma_f32_16x16x32_bf16 v[70:73], v[150:153], v[212:215], v[70:73]
	v_mfma_f32_16x16x32_bf16 v[66:69], v[158:161], v[212:215], v[66:69]
	s_setprio 0
	s_barrier
	s_add_i32 s24, s84, s3
	s_mov_b32 m0, s24
	ds_read_b128 v[162:165], v207 offset:16384
	ds_read_b128 v[166:169], v207 offset:17408
	ds_read_b128 v[170:173], v207 offset:18432
	ds_read_b128 v[192:195], v207 offset:19456
	ds_read_b128 v[196:199], v207 offset:20480
	ds_read_b128 v[200:203], v207 offset:21504
	ds_read_b128 v[208:211], v207 offset:22528
	ds_read_b128 v[212:215], v207 offset:23552
	global_load_lds_dwordx4 v178, s[10:11]
	s_add_i32 m0, s24, 0x2000
	s_add_u32 s24, s10, 0x80000
	s_addc_u32 s25, s11, 0
	s_add_i32 s91, s85, s3
	global_load_lds_dwordx4 v182, s[10:11]
	s_mov_b32 m0, s91
	s_nop 0
	global_load_lds_dwordx4 v178, s[24:25]
	s_add_i32 m0, s91, 0x2000
	s_nop 0
	global_load_lds_dwordx4 v182, s[24:25]
	s_mov_b32 m0, s50
	s_nop 0
	global_load_lds_dwordx4 v176, s[34:35]
	s_mov_b32 m0, s51
	s_nop 0
	global_load_lds_dwordx4 v180, s[34:35]
	s_waitcnt vmcnt(8)
	s_waitcnt lgkmcnt(0)
	s_barrier
	s_setprio 1
	s_waitcnt lgkmcnt(0)
	v_mfma_f32_16x16x32_bf16 v[62:65], v[130:133], v[162:165], 0
	v_mfma_f32_16x16x32_bf16 v[58:61], v[138:141], v[162:165], 0
	v_mfma_f32_16x16x32_bf16 v[46:49], v[130:133], v[170:173], 0
	v_mfma_f32_16x16x32_bf16 v[42:45], v[138:141], v[170:173], 0
	v_mfma_f32_16x16x32_bf16 v[30:33], v[130:133], v[196:199], 0
	v_mfma_f32_16x16x32_bf16 v[26:29], v[138:141], v[196:199], 0
	v_mfma_f32_16x16x32_bf16 v[14:17], v[130:133], v[208:211], 0
	v_mfma_f32_16x16x32_bf16 v[10:13], v[138:141], v[208:211], 0
	v_mfma_f32_16x16x32_bf16 v[62:65], v[134:137], v[166:169], v[62:65]
	v_mfma_f32_16x16x32_bf16 v[58:61], v[142:145], v[166:169], v[58:61]
	v_mfma_f32_16x16x32_bf16 v[46:49], v[134:137], v[192:195], v[46:49]
	v_mfma_f32_16x16x32_bf16 v[42:45], v[142:145], v[192:195], v[42:45]
	v_mfma_f32_16x16x32_bf16 v[30:33], v[134:137], v[200:203], v[30:33]
	v_mfma_f32_16x16x32_bf16 v[26:29], v[142:145], v[200:203], v[26:29]
	v_mfma_f32_16x16x32_bf16 v[14:17], v[134:137], v[212:215], v[14:17]
	v_mfma_f32_16x16x32_bf16 v[10:13], v[142:145], v[212:215], v[10:13]
	s_setprio 0
	s_setprio 1
	v_mfma_f32_16x16x32_bf16 v[54:57], v[146:149], v[162:165], 0
	v_mfma_f32_16x16x32_bf16 v[50:53], v[154:157], v[162:165], 0
	v_mfma_f32_16x16x32_bf16 v[38:41], v[146:149], v[170:173], 0
	v_mfma_f32_16x16x32_bf16 v[34:37], v[154:157], v[170:173], 0
	v_mfma_f32_16x16x32_bf16 v[22:25], v[146:149], v[196:199], 0
	v_mfma_f32_16x16x32_bf16 v[18:21], v[154:157], v[196:199], 0
	v_mfma_f32_16x16x32_bf16 v[6:9], v[146:149], v[208:211], 0
	v_mfma_f32_16x16x32_bf16 v[2:5], v[154:157], v[208:211], 0
	v_mfma_f32_16x16x32_bf16 v[54:57], v[150:153], v[166:169], v[54:57]
	v_mfma_f32_16x16x32_bf16 v[50:53], v[158:161], v[166:169], v[50:53]
	v_mfma_f32_16x16x32_bf16 v[38:41], v[150:153], v[192:195], v[38:41]
	v_mfma_f32_16x16x32_bf16 v[34:37], v[158:161], v[192:195], v[34:37]
	v_mfma_f32_16x16x32_bf16 v[22:25], v[150:153], v[200:203], v[22:25]
	v_mfma_f32_16x16x32_bf16 v[18:21], v[158:161], v[200:203], v[18:21]
	v_mfma_f32_16x16x32_bf16 v[6:9], v[150:153], v[212:215], v[6:9]
	v_mfma_f32_16x16x32_bf16 v[2:5], v[158:161], v[212:215], v[2:5]
	s_setprio 0
	s_barrier
	s_add_i32 s91, 0, 0x18000
	s_add_i32 s92, 0, 0x1c000
	v_add_u32_e32 v142, s91, v175
	v_add_u32_e32 v158, s92, v175
	ds_read_b128 v[130:133], v142
	ds_read_b128 v[134:137], v142 offset:1024
	ds_read_b128 v[138:141], v142 offset:2048
	ds_read_b128 v[142:145], v142 offset:3072
	ds_read_b128 v[146:149], v158
	ds_read_b128 v[150:153], v158 offset:1024
	ds_read_b128 v[154:157], v158 offset:2048
	ds_read_b128 v[158:161], v158 offset:3072
	s_add_u32 s24, s34, 0x80000
	s_addc_u32 s25, s35, 0
	s_mov_b32 m0, s63
	ds_read_b128 v[162:165], v207 offset:32768
	ds_read_b128 v[166:169], v207 offset:33792
	ds_read_b128 v[170:173], v207 offset:34816
	ds_read_b128 v[192:195], v207 offset:35840
	ds_read_b128 v[196:199], v207 offset:36864
	ds_read_b128 v[200:203], v207 offset:37888
	ds_read_b128 v[208:211], v207 offset:38912
	ds_read_b128 v[212:215], v207 offset:39936
	global_load_lds_dwordx4 v176, s[24:25]
	s_mov_b32 m0, s75
	s_nop 0
	global_load_lds_dwordx4 v180, s[24:25]
	s_waitcnt vmcnt(8)
	s_waitcnt lgkmcnt(0)
	s_barrier
	s_setprio 1
	s_waitcnt lgkmcnt(0)
	v_mfma_f32_16x16x32_bf16 v[126:129], v[130:133], v[162:165], v[126:129]
	v_mfma_f32_16x16x32_bf16 v[122:125], v[138:141], v[162:165], v[122:125]
	v_mfma_f32_16x16x32_bf16 v[110:113], v[130:133], v[170:173], v[110:113]
	v_mfma_f32_16x16x32_bf16 v[106:109], v[138:141], v[170:173], v[106:109]
	v_mfma_f32_16x16x32_bf16 v[94:97], v[130:133], v[196:199], v[94:97]
	v_mfma_f32_16x16x32_bf16 v[90:93], v[138:141], v[196:199], v[90:93]
	v_mfma_f32_16x16x32_bf16 v[78:81], v[130:133], v[208:211], v[78:81]
	v_mfma_f32_16x16x32_bf16 v[74:77], v[138:141], v[208:211], v[74:77]
	v_mfma_f32_16x16x32_bf16 v[126:129], v[134:137], v[166:169], v[126:129]
	v_mfma_f32_16x16x32_bf16 v[122:125], v[142:145], v[166:169], v[122:125]
	v_mfma_f32_16x16x32_bf16 v[110:113], v[134:137], v[192:195], v[110:113]
	v_mfma_f32_16x16x32_bf16 v[106:109], v[142:145], v[192:195], v[106:109]
	v_mfma_f32_16x16x32_bf16 v[94:97], v[134:137], v[200:203], v[94:97]
	v_mfma_f32_16x16x32_bf16 v[90:93], v[142:145], v[200:203], v[90:93]
	v_mfma_f32_16x16x32_bf16 v[78:81], v[134:137], v[212:215], v[78:81]
	v_mfma_f32_16x16x32_bf16 v[74:77], v[142:145], v[212:215], v[74:77]
	s_setprio 0
	s_setprio 1
	v_mfma_f32_16x16x32_bf16 v[118:121], v[146:149], v[162:165], v[118:121]
	v_mfma_f32_16x16x32_bf16 v[114:117], v[154:157], v[162:165], v[114:117]
	v_mfma_f32_16x16x32_bf16 v[102:105], v[146:149], v[170:173], v[102:105]
	v_mfma_f32_16x16x32_bf16 v[98:101], v[154:157], v[170:173], v[98:101]
	v_mfma_f32_16x16x32_bf16 v[86:89], v[146:149], v[196:199], v[86:89]
	v_mfma_f32_16x16x32_bf16 v[82:85], v[154:157], v[196:199], v[82:85]
	v_mfma_f32_16x16x32_bf16 v[70:73], v[146:149], v[208:211], v[70:73]
	v_mfma_f32_16x16x32_bf16 v[66:69], v[154:157], v[208:211], v[66:69]
	v_mfma_f32_16x16x32_bf16 v[118:121], v[150:153], v[166:169], v[118:121]
	v_mfma_f32_16x16x32_bf16 v[114:117], v[158:161], v[166:169], v[114:117]
	v_mfma_f32_16x16x32_bf16 v[102:105], v[150:153], v[192:195], v[102:105]
	v_mfma_f32_16x16x32_bf16 v[98:101], v[158:161], v[192:195], v[98:101]
	v_mfma_f32_16x16x32_bf16 v[86:89], v[150:153], v[200:203], v[86:89]
	v_mfma_f32_16x16x32_bf16 v[82:85], v[158:161], v[200:203], v[82:85]
	v_mfma_f32_16x16x32_bf16 v[70:73], v[150:153], v[212:215], v[70:73]
	v_mfma_f32_16x16x32_bf16 v[66:69], v[158:161], v[212:215], v[66:69]
	s_setprio 0
	s_barrier
	s_add_u32 s12, s10, 0x80
	s_addc_u32 s13, s11, 0
	s_add_u32 s14, s34, 0x80
	s_addc_u32 s15, s35, 0
	s_add_i32 s24, s91, s3
	s_mov_b32 m0, s24
	ds_read_b128 v[162:165], v207 offset:49152
	ds_read_b128 v[166:169], v207 offset:50176
	ds_read_b128 v[170:173], v207 offset:51200
	ds_read_b128 v[192:195], v207 offset:52224
	ds_read_b128 v[196:199], v207 offset:53248
	ds_read_b128 v[200:203], v207 offset:54272
	ds_read_b128 v[208:211], v207 offset:55296
	ds_read_b128 v[212:215], v207 offset:56320
	global_load_lds_dwordx4 v178, s[12:13]
	s_add_i32 m0, s24, 0x2000
	s_add_u32 s10, s10, 0x80080
	s_addc_u32 s11, s11, 0
	s_add_i32 s24, s92, s3
	global_load_lds_dwordx4 v182, s[12:13]
	s_mov_b32 m0, s24
	s_nop 0
	global_load_lds_dwordx4 v178, s[10:11]
	s_add_i32 m0, s24, 0x2000
	s_nop 0
	global_load_lds_dwordx4 v182, s[10:11]
	s_mov_b32 m0, s81
	s_nop 0
	global_load_lds_dwordx4 v176, s[14:15]
	s_mov_b32 m0, s82
	s_nop 0
	global_load_lds_dwordx4 v180, s[14:15]
	s_waitcnt vmcnt(8)
	s_waitcnt lgkmcnt(0)
	s_barrier
	s_setprio 1
	s_waitcnt lgkmcnt(0)
	v_mfma_f32_16x16x32_bf16 v[62:65], v[130:133], v[162:165], v[62:65]
	v_mfma_f32_16x16x32_bf16 v[58:61], v[138:141], v[162:165], v[58:61]
	v_mfma_f32_16x16x32_bf16 v[46:49], v[130:133], v[170:173], v[46:49]
	v_mfma_f32_16x16x32_bf16 v[42:45], v[138:141], v[170:173], v[42:45]
	v_mfma_f32_16x16x32_bf16 v[30:33], v[130:133], v[196:199], v[30:33]
	v_mfma_f32_16x16x32_bf16 v[26:29], v[138:141], v[196:199], v[26:29]
	v_mfma_f32_16x16x32_bf16 v[14:17], v[130:133], v[208:211], v[14:17]
	v_mfma_f32_16x16x32_bf16 v[10:13], v[138:141], v[208:211], v[10:13]
	v_mfma_f32_16x16x32_bf16 v[62:65], v[134:137], v[166:169], v[62:65]
	v_mfma_f32_16x16x32_bf16 v[58:61], v[142:145], v[166:169], v[58:61]
	v_mfma_f32_16x16x32_bf16 v[46:49], v[134:137], v[192:195], v[46:49]
	v_mfma_f32_16x16x32_bf16 v[42:45], v[142:145], v[192:195], v[42:45]
	v_mfma_f32_16x16x32_bf16 v[30:33], v[134:137], v[200:203], v[30:33]
	v_mfma_f32_16x16x32_bf16 v[26:29], v[142:145], v[200:203], v[26:29]
	v_mfma_f32_16x16x32_bf16 v[14:17], v[134:137], v[212:215], v[14:17]
	v_mfma_f32_16x16x32_bf16 v[10:13], v[142:145], v[212:215], v[10:13]
	s_setprio 0
	s_setprio 1
	v_mfma_f32_16x16x32_bf16 v[54:57], v[146:149], v[162:165], v[54:57]
	v_mfma_f32_16x16x32_bf16 v[50:53], v[154:157], v[162:165], v[50:53]
	v_mfma_f32_16x16x32_bf16 v[38:41], v[146:149], v[170:173], v[38:41]
	v_mfma_f32_16x16x32_bf16 v[34:37], v[154:157], v[170:173], v[34:37]
	v_mfma_f32_16x16x32_bf16 v[22:25], v[146:149], v[196:199], v[22:25]
	v_mfma_f32_16x16x32_bf16 v[18:21], v[154:157], v[196:199], v[18:21]
	v_mfma_f32_16x16x32_bf16 v[6:9], v[146:149], v[208:211], v[6:9]
	v_mfma_f32_16x16x32_bf16 v[2:5], v[154:157], v[208:211], v[2:5]
	v_mfma_f32_16x16x32_bf16 v[54:57], v[150:153], v[166:169], v[54:57]
	v_mfma_f32_16x16x32_bf16 v[50:53], v[158:161], v[166:169], v[50:53]
	v_mfma_f32_16x16x32_bf16 v[38:41], v[150:153], v[192:195], v[38:41]
	v_mfma_f32_16x16x32_bf16 v[34:37], v[158:161], v[192:195], v[34:37]
	v_mfma_f32_16x16x32_bf16 v[22:25], v[150:153], v[200:203], v[22:25]
	v_mfma_f32_16x16x32_bf16 v[18:21], v[158:161], v[200:203], v[18:21]
	v_mfma_f32_16x16x32_bf16 v[6:9], v[150:153], v[212:215], v[6:9]
	v_mfma_f32_16x16x32_bf16 v[2:5], v[158:161], v[212:215], v[2:5]
	s_setprio 0
	s_barrier
	s_add_i32 s90, s90, 2
	s_add_u32 s78, s78, 0x100
	s_addc_u32 s79, s79, 0
	s_add_u32 s88, s88, 0x100
	s_addc_u32 s89, s89, 0
	s_cmp_gt_u32 s90, 29
	s_cbranch_scc1 .Lpeel_exit_2
.LBB0_579:
	ds_read_b128 v[130:133], v1
	ds_read_b128 v[134:137], v1 offset:1024
	ds_read_b128 v[138:141], v1 offset:2048
	ds_read_b128 v[142:145], v1 offset:3072
	ds_read_b128 v[146:149], v206
	ds_read_b128 v[150:153], v206 offset:1024
	ds_read_b128 v[154:157], v206 offset:2048
	ds_read_b128 v[158:161], v206 offset:3072
	s_add_u32 s10, s78, 0xfff80080
	s_addc_u32 s11, s79, -1
	s_cmp_eq_u32 s90, 28
	s_cselect_b32 s35, s30, s11
	s_cselect_b32 s34, s31, s10
	s_cselect_b32 s11, s41, s89
	s_cselect_b32 s10, s47, s88
	s_add_i32 m0, s50, 0xc000
	ds_read_b128 v[162:165], v207
	ds_read_b128 v[166:169], v207 offset:1024
	ds_read_b128 v[170:173], v207 offset:2048
	ds_read_b128 v[192:195], v207 offset:3072
	ds_read_b128 v[196:199], v207 offset:4096
	ds_read_b128 v[200:203], v207 offset:5120
	ds_read_b128 v[208:211], v207 offset:6144
	ds_read_b128 v[212:215], v207 offset:7168
	global_load_lds_dwordx4 v184, s[78:79]
	s_add_i32 m0, s50, 0xe000
	s_nop 0
	global_load_lds_dwordx4 v186, s[78:79]
	s_waitcnt vmcnt(8)
	s_waitcnt lgkmcnt(0)
	s_barrier
	s_setprio 1
	s_waitcnt lgkmcnt(0)
	v_mfma_f32_16x16x32_bf16 v[126:129], v[130:133], v[162:165], v[126:129]
	v_mfma_f32_16x16x32_bf16 v[122:125], v[138:141], v[162:165], v[122:125]
	v_mfma_f32_16x16x32_bf16 v[110:113], v[130:133], v[170:173], v[110:113]
	v_mfma_f32_16x16x32_bf16 v[106:109], v[138:141], v[170:173], v[106:109]
	v_mfma_f32_16x16x32_bf16 v[94:97], v[130:133], v[196:199], v[94:97]
	v_mfma_f32_16x16x32_bf16 v[90:93], v[138:141], v[196:199], v[90:93]
	v_mfma_f32_16x16x32_bf16 v[78:81], v[130:133], v[208:211], v[78:81]
	v_mfma_f32_16x16x32_bf16 v[74:77], v[138:141], v[208:211], v[74:77]
	v_mfma_f32_16x16x32_bf16 v[126:129], v[134:137], v[166:169], v[126:129]
	v_mfma_f32_16x16x32_bf16 v[122:125], v[142:145], v[166:169], v[122:125]
	v_mfma_f32_16x16x32_bf16 v[110:113], v[134:137], v[192:195], v[110:113]
	v_mfma_f32_16x16x32_bf16 v[106:109], v[142:145], v[192:195], v[106:109]
	v_mfma_f32_16x16x32_bf16 v[94:97], v[134:137], v[200:203], v[94:97]
	v_mfma_f32_16x16x32_bf16 v[90:93], v[142:145], v[200:203], v[90:93]
	v_mfma_f32_16x16x32_bf16 v[78:81], v[134:137], v[212:215], v[78:81]
	v_mfma_f32_16x16x32_bf16 v[74:77], v[142:145], v[212:215], v[74:77]
	s_setprio 0
	s_setprio 1
	v_mfma_f32_16x16x32_bf16 v[118:121], v[146:149], v[162:165], v[118:121]
	v_mfma_f32_16x16x32_bf16 v[114:117], v[154:157], v[162:165], v[114:117]
	v_mfma_f32_16x16x32_bf16 v[102:105], v[146:149], v[170:173], v[102:105]
	v_mfma_f32_16x16x32_bf16 v[98:101], v[154:157], v[170:173], v[98:101]
	v_mfma_f32_16x16x32_bf16 v[86:89], v[146:149], v[196:199], v[86:89]
	v_mfma_f32_16x16x32_bf16 v[82:85], v[154:157], v[196:199], v[82:85]
	v_mfma_f32_16x16x32_bf16 v[70:73], v[146:149], v[208:211], v[70:73]
	v_mfma_f32_16x16x32_bf16 v[66:69], v[154:157], v[208:211], v[66:69]
	v_mfma_f32_16x16x32_bf16 v[118:121], v[150:153], v[166:169], v[118:121]
	v_mfma_f32_16x16x32_bf16 v[114:117], v[158:161], v[166:169], v[114:117]
	v_mfma_f32_16x16x32_bf16 v[102:105], v[150:153], v[192:195], v[102:105]
	v_mfma_f32_16x16x32_bf16 v[98:101], v[158:161], v[192:195], v[98:101]
	v_mfma_f32_16x16x32_bf16 v[86:89], v[150:153], v[200:203], v[86:89]
	v_mfma_f32_16x16x32_bf16 v[82:85], v[158:161], v[200:203], v[82:85]
	v_mfma_f32_16x16x32_bf16 v[70:73], v[150:153], v[212:215], v[70:73]
	v_mfma_f32_16x16x32_bf16 v[66:69], v[158:161], v[212:215], v[66:69]
	s_setprio 0
	s_barrier
	s_add_i32 s24, s84, s3
	s_mov_b32 m0, s24
	ds_read_b128 v[162:165], v207 offset:16384
	ds_read_b128 v[166:169], v207 offset:17408
	ds_read_b128 v[170:173], v207 offset:18432
	ds_read_b128 v[192:195], v207 offset:19456
	ds_read_b128 v[196:199], v207 offset:20480
	ds_read_b128 v[200:203], v207 offset:21504
	ds_read_b128 v[208:211], v207 offset:22528
	ds_read_b128 v[212:215], v207 offset:23552
	global_load_lds_dwordx4 v178, s[10:11]
	s_add_i32 m0, s24, 0x2000
	s_add_u32 s24, s10, 0x80000
	s_addc_u32 s25, s11, 0
	s_add_i32 s91, s85, s3
	global_load_lds_dwordx4 v182, s[10:11]
	s_mov_b32 m0, s91
	s_nop 0
	global_load_lds_dwordx4 v178, s[24:25]
	s_add_i32 m0, s91, 0x2000
	s_nop 0
	global_load_lds_dwordx4 v182, s[24:25]
	s_mov_b32 m0, s50
	s_nop 0
	global_load_lds_dwordx4 v176, s[34:35]
	s_mov_b32 m0, s51
	s_nop 0
	global_load_lds_dwordx4 v180, s[34:35]
	s_waitcnt vmcnt(8)
	s_waitcnt lgkmcnt(0)
	s_barrier
	s_setprio 1
	s_waitcnt lgkmcnt(0)
	v_mfma_f32_16x16x32_bf16 v[62:65], v[130:133], v[162:165], v[62:65]
	v_mfma_f32_16x16x32_bf16 v[58:61], v[138:141], v[162:165], v[58:61]
	v_mfma_f32_16x16x32_bf16 v[46:49], v[130:133], v[170:173], v[46:49]
	v_mfma_f32_16x16x32_bf16 v[42:45], v[138:141], v[170:173], v[42:45]
	v_mfma_f32_16x16x32_bf16 v[30:33], v[130:133], v[196:199], v[30:33]
	v_mfma_f32_16x16x32_bf16 v[26:29], v[138:141], v[196:199], v[26:29]
	v_mfma_f32_16x16x32_bf16 v[14:17], v[130:133], v[208:211], v[14:17]
	v_mfma_f32_16x16x32_bf16 v[10:13], v[138:141], v[208:211], v[10:13]
	v_mfma_f32_16x16x32_bf16 v[62:65], v[134:137], v[166:169], v[62:65]
	v_mfma_f32_16x16x32_bf16 v[58:61], v[142:145], v[166:169], v[58:61]
	v_mfma_f32_16x16x32_bf16 v[46:49], v[134:137], v[192:195], v[46:49]
	v_mfma_f32_16x16x32_bf16 v[42:45], v[142:145], v[192:195], v[42:45]
	v_mfma_f32_16x16x32_bf16 v[30:33], v[134:137], v[200:203], v[30:33]
	v_mfma_f32_16x16x32_bf16 v[26:29], v[142:145], v[200:203], v[26:29]
	v_mfma_f32_16x16x32_bf16 v[14:17], v[134:137], v[212:215], v[14:17]
	v_mfma_f32_16x16x32_bf16 v[10:13], v[142:145], v[212:215], v[10:13]
	s_setprio 0
	s_setprio 1
	v_mfma_f32_16x16x32_bf16 v[54:57], v[146:149], v[162:165], v[54:57]
	v_mfma_f32_16x16x32_bf16 v[50:53], v[154:157], v[162:165], v[50:53]
	v_mfma_f32_16x16x32_bf16 v[38:41], v[146:149], v[170:173], v[38:41]
	v_mfma_f32_16x16x32_bf16 v[34:37], v[154:157], v[170:173], v[34:37]
	v_mfma_f32_16x16x32_bf16 v[22:25], v[146:149], v[196:199], v[22:25]
	v_mfma_f32_16x16x32_bf16 v[18:21], v[154:157], v[196:199], v[18:21]
	v_mfma_f32_16x16x32_bf16 v[6:9], v[146:149], v[208:211], v[6:9]
	v_mfma_f32_16x16x32_bf16 v[2:5], v[154:157], v[208:211], v[2:5]
	v_mfma_f32_16x16x32_bf16 v[54:57], v[150:153], v[166:169], v[54:57]
	v_mfma_f32_16x16x32_bf16 v[50:53], v[158:161], v[166:169], v[50:53]
	v_mfma_f32_16x16x32_bf16 v[38:41], v[150:153], v[192:195], v[38:41]
	v_mfma_f32_16x16x32_bf16 v[34:37], v[158:161], v[192:195], v[34:37]
	v_mfma_f32_16x16x32_bf16 v[22:25], v[150:153], v[200:203], v[22:25]
	v_mfma_f32_16x16x32_bf16 v[18:21], v[158:161], v[200:203], v[18:21]
	v_mfma_f32_16x16x32_bf16 v[6:9], v[150:153], v[212:215], v[6:9]
	v_mfma_f32_16x16x32_bf16 v[2:5], v[158:161], v[212:215], v[2:5]
	s_setprio 0
	s_barrier
	s_add_i32 s91, 0, 0x18000
	s_add_i32 s92, 0, 0x1c000
	v_add_u32_e32 v142, s91, v175
	v_add_u32_e32 v158, s92, v175
	ds_read_b128 v[130:133], v142
	ds_read_b128 v[134:137], v142 offset:1024
	ds_read_b128 v[138:141], v142 offset:2048
	ds_read_b128 v[142:145], v142 offset:3072
	ds_read_b128 v[146:149], v158
	ds_read_b128 v[150:153], v158 offset:1024
	ds_read_b128 v[154:157], v158 offset:2048
	ds_read_b128 v[158:161], v158 offset:3072
	s_add_u32 s24, s34, 0x80000
	s_addc_u32 s25, s35, 0
	s_mov_b32 m0, s63
	ds_read_b128 v[162:165], v207 offset:32768
	ds_read_b128 v[166:169], v207 offset:33792
	ds_read_b128 v[170:173], v207 offset:34816
	ds_read_b128 v[192:195], v207 offset:35840
	ds_read_b128 v[196:199], v207 offset:36864
	ds_read_b128 v[200:203], v207 offset:37888
	ds_read_b128 v[208:211], v207 offset:38912
	ds_read_b128 v[212:215], v207 offset:39936
	global_load_lds_dwordx4 v176, s[24:25]
	s_mov_b32 m0, s75
	s_nop 0
	global_load_lds_dwordx4 v180, s[24:25]
	s_waitcnt vmcnt(8)
	s_waitcnt lgkmcnt(0)
	s_barrier
	s_setprio 1
	s_waitcnt lgkmcnt(0)
	v_mfma_f32_16x16x32_bf16 v[126:129], v[130:133], v[162:165], v[126:129]
	v_mfma_f32_16x16x32_bf16 v[122:125], v[138:141], v[162:165], v[122:125]
	v_mfma_f32_16x16x32_bf16 v[110:113], v[130:133], v[170:173], v[110:113]
	v_mfma_f32_16x16x32_bf16 v[106:109], v[138:141], v[170:173], v[106:109]
	v_mfma_f32_16x16x32_bf16 v[94:97], v[130:133], v[196:199], v[94:97]
	v_mfma_f32_16x16x32_bf16 v[90:93], v[138:141], v[196:199], v[90:93]
	v_mfma_f32_16x16x32_bf16 v[78:81], v[130:133], v[208:211], v[78:81]
	v_mfma_f32_16x16x32_bf16 v[74:77], v[138:141], v[208:211], v[74:77]
	v_mfma_f32_16x16x32_bf16 v[126:129], v[134:137], v[166:169], v[126:129]
	v_mfma_f32_16x16x32_bf16 v[122:125], v[142:145], v[166:169], v[122:125]
	v_mfma_f32_16x16x32_bf16 v[110:113], v[134:137], v[192:195], v[110:113]
	v_mfma_f32_16x16x32_bf16 v[106:109], v[142:145], v[192:195], v[106:109]
	v_mfma_f32_16x16x32_bf16 v[94:97], v[134:137], v[200:203], v[94:97]
	v_mfma_f32_16x16x32_bf16 v[90:93], v[142:145], v[200:203], v[90:93]
	v_mfma_f32_16x16x32_bf16 v[78:81], v[134:137], v[212:215], v[78:81]
	v_mfma_f32_16x16x32_bf16 v[74:77], v[142:145], v[212:215], v[74:77]
	s_setprio 0
	s_setprio 1
	v_mfma_f32_16x16x32_bf16 v[118:121], v[146:149], v[162:165], v[118:121]
	v_mfma_f32_16x16x32_bf16 v[114:117], v[154:157], v[162:165], v[114:117]
	v_mfma_f32_16x16x32_bf16 v[102:105], v[146:149], v[170:173], v[102:105]
	v_mfma_f32_16x16x32_bf16 v[98:101], v[154:157], v[170:173], v[98:101]
	v_mfma_f32_16x16x32_bf16 v[86:89], v[146:149], v[196:199], v[86:89]
	v_mfma_f32_16x16x32_bf16 v[82:85], v[154:157], v[196:199], v[82:85]
	v_mfma_f32_16x16x32_bf16 v[70:73], v[146:149], v[208:211], v[70:73]
	v_mfma_f32_16x16x32_bf16 v[66:69], v[154:157], v[208:211], v[66:69]
	v_mfma_f32_16x16x32_bf16 v[118:121], v[150:153], v[166:169], v[118:121]
	v_mfma_f32_16x16x32_bf16 v[114:117], v[158:161], v[166:169], v[114:117]
	v_mfma_f32_16x16x32_bf16 v[102:105], v[150:153], v[192:195], v[102:105]
	v_mfma_f32_16x16x32_bf16 v[98:101], v[158:161], v[192:195], v[98:101]
	v_mfma_f32_16x16x32_bf16 v[86:89], v[150:153], v[200:203], v[86:89]
	v_mfma_f32_16x16x32_bf16 v[82:85], v[158:161], v[200:203], v[82:85]
	v_mfma_f32_16x16x32_bf16 v[70:73], v[150:153], v[212:215], v[70:73]
	v_mfma_f32_16x16x32_bf16 v[66:69], v[158:161], v[212:215], v[66:69]
	s_setprio 0
	s_barrier
	s_add_u32 s12, s10, 0x80
	s_addc_u32 s13, s11, 0
	s_add_u32 s14, s34, 0x80
	s_addc_u32 s15, s35, 0
	s_add_i32 s24, s91, s3
	s_mov_b32 m0, s24
	ds_read_b128 v[162:165], v207 offset:49152
	ds_read_b128 v[166:169], v207 offset:50176
	ds_read_b128 v[170:173], v207 offset:51200
	ds_read_b128 v[192:195], v207 offset:52224
	ds_read_b128 v[196:199], v207 offset:53248
	ds_read_b128 v[200:203], v207 offset:54272
	ds_read_b128 v[208:211], v207 offset:55296
	ds_read_b128 v[212:215], v207 offset:56320
	global_load_lds_dwordx4 v178, s[12:13]
	s_add_i32 m0, s24, 0x2000
	s_add_u32 s10, s10, 0x80080
	s_addc_u32 s11, s11, 0
	s_add_i32 s24, s92, s3
	global_load_lds_dwordx4 v182, s[12:13]
	s_mov_b32 m0, s24
	s_nop 0
	global_load_lds_dwordx4 v178, s[10:11]
	s_add_i32 m0, s24, 0x2000
	s_nop 0
	global_load_lds_dwordx4 v182, s[10:11]
	s_mov_b32 m0, s81
	s_nop 0
	global_load_lds_dwordx4 v176, s[14:15]
	s_mov_b32 m0, s82
	s_nop 0
	global_load_lds_dwordx4 v180, s[14:15]
	s_waitcnt vmcnt(8)
	s_waitcnt lgkmcnt(0)
	s_barrier
	s_setprio 1
	s_waitcnt lgkmcnt(0)
	v_mfma_f32_16x16x32_bf16 v[62:65], v[130:133], v[162:165], v[62:65]
	v_mfma_f32_16x16x32_bf16 v[58:61], v[138:141], v[162:165], v[58:61]
	v_mfma_f32_16x16x32_bf16 v[46:49], v[130:133], v[170:173], v[46:49]
	v_mfma_f32_16x16x32_bf16 v[42:45], v[138:141], v[170:173], v[42:45]
	v_mfma_f32_16x16x32_bf16 v[30:33], v[130:133], v[196:199], v[30:33]
	v_mfma_f32_16x16x32_bf16 v[26:29], v[138:141], v[196:199], v[26:29]
	v_mfma_f32_16x16x32_bf16 v[14:17], v[130:133], v[208:211], v[14:17]
	v_mfma_f32_16x16x32_bf16 v[10:13], v[138:141], v[208:211], v[10:13]
	v_mfma_f32_16x16x32_bf16 v[62:65], v[134:137], v[166:169], v[62:65]
	v_mfma_f32_16x16x32_bf16 v[58:61], v[142:145], v[166:169], v[58:61]
	v_mfma_f32_16x16x32_bf16 v[46:49], v[134:137], v[192:195], v[46:49]
	v_mfma_f32_16x16x32_bf16 v[42:45], v[142:145], v[192:195], v[42:45]
	v_mfma_f32_16x16x32_bf16 v[30:33], v[134:137], v[200:203], v[30:33]
	v_mfma_f32_16x16x32_bf16 v[26:29], v[142:145], v[200:203], v[26:29]
	v_mfma_f32_16x16x32_bf16 v[14:17], v[134:137], v[212:215], v[14:17]
	v_mfma_f32_16x16x32_bf16 v[10:13], v[142:145], v[212:215], v[10:13]
	s_setprio 0
	s_setprio 1
	v_mfma_f32_16x16x32_bf16 v[54:57], v[146:149], v[162:165], v[54:57]
	v_mfma_f32_16x16x32_bf16 v[50:53], v[154:157], v[162:165], v[50:53]
	v_mfma_f32_16x16x32_bf16 v[38:41], v[146:149], v[170:173], v[38:41]
	v_mfma_f32_16x16x32_bf16 v[34:37], v[154:157], v[170:173], v[34:37]
	v_mfma_f32_16x16x32_bf16 v[22:25], v[146:149], v[196:199], v[22:25]
	v_mfma_f32_16x16x32_bf16 v[18:21], v[154:157], v[196:199], v[18:21]
	v_mfma_f32_16x16x32_bf16 v[6:9], v[146:149], v[208:211], v[6:9]
	v_mfma_f32_16x16x32_bf16 v[2:5], v[154:157], v[208:211], v[2:5]
	v_mfma_f32_16x16x32_bf16 v[54:57], v[150:153], v[166:169], v[54:57]
	v_mfma_f32_16x16x32_bf16 v[50:53], v[158:161], v[166:169], v[50:53]
	v_mfma_f32_16x16x32_bf16 v[38:41], v[150:153], v[192:195], v[38:41]
	v_mfma_f32_16x16x32_bf16 v[34:37], v[158:161], v[192:195], v[34:37]
	v_mfma_f32_16x16x32_bf16 v[22:25], v[150:153], v[200:203], v[22:25]
	v_mfma_f32_16x16x32_bf16 v[18:21], v[158:161], v[200:203], v[18:21]
	v_mfma_f32_16x16x32_bf16 v[6:9], v[150:153], v[212:215], v[6:9]
	v_mfma_f32_16x16x32_bf16 v[2:5], v[158:161], v[212:215], v[2:5]
	s_setprio 0
	s_barrier
	s_add_i32 s90, s90, 2
	s_add_u32 s78, s78, 0x100
	s_addc_u32 s79, s79, 0
	s_add_u32 s88, s88, 0x100
	s_addc_u32 s89, s89, 0
	s_cmp_gt_u32 s90, 29
	s_cbranch_scc0 .LBB0_579

.LBB0_649:
	s_ashr_i32 s47, s46, 31
	s_lshl_b64 s[10:11], s[46:47], 21
	s_add_u32 s48, s76, s10
	s_addc_u32 s49, s77, s11
	s_and_b64 s[10:11], s[4:5], exec
	s_cselect_b32 s47, s49, s61
	s_cselect_b32 s85, s48, s60
	s_ashr_i32 s45, s44, 31
	s_lshl_b64 s[10:11], s[44:45], 21
	v_readlane_b32 s12, v255, 50
	v_readlane_b32 s13, v255, 51
	s_add_u32 s56, s12, s10
	s_addc_u32 s57, s13, s11
	s_and_b64 s[10:11], s[4:5], exec
	s_cselect_b32 s45, s57, s35
	s_cselect_b32 s86, s56, s34
	s_add_u32 s60, s60, 0x100080
	s_addc_u32 s61, s61, 0
	s_add_u32 s87, s34, 0x100
	s_addc_u32 s88, s35, 0
	s_mov_b32 s89, -2
	ds_read_b128 v[154:157], v150
	ds_read_b128 v[158:161], v150 offset:1024
	ds_read_b128 v[162:165], v150 offset:2048
	ds_read_b128 v[166:169], v150 offset:3072
	ds_read_b128 v[170:173], v151
	ds_read_b128 v[176:179], v151 offset:1024
	ds_read_b128 v[180:183], v151 offset:2048
	ds_read_b128 v[184:187], v151 offset:3072
	s_add_u32 s10, s60, 0xfff00080
	s_addc_u32 s11, s61, -1
	s_cmp_eq_u32 s89, 60
	s_cselect_b32 s35, s47, s11
	s_cselect_b32 s34, s85, s10
	s_cselect_b32 s11, s45, s88
	s_cselect_b32 s10, s86, s87
	s_add_i32 m0, s50, 0xc000
	ds_read_b128 v[188:191], v152
	ds_read_b128 v[192:195], v152 offset:1024
	ds_read_b128 v[196:199], v152 offset:2048
	ds_read_b128 v[200:203], v152 offset:3072
	ds_read_b128 v[204:207], v152 offset:4096
	ds_read_b128 v[208:211], v152 offset:5120
	ds_read_b128 v[212:215], v152 offset:6144
	ds_read_b128 v[216:219], v152 offset:7168
	global_load_lds_dwordx4 v138, s[60:61]
	s_add_i32 m0, s50, 0xe000
	s_nop 0
	global_load_lds_dwordx4 v140, s[60:61]
	s_waitcnt vmcnt(8)
	s_waitcnt lgkmcnt(0)
	s_barrier
	s_setprio 1
	s_waitcnt lgkmcnt(0)
	v_mfma_f32_16x16x32_bf16 v[126:129], v[154:157], v[188:191], 0
	v_mfma_f32_16x16x32_bf16 v[122:125], v[162:165], v[188:191], 0
	v_mfma_f32_16x16x32_bf16 v[114:117], v[154:157], v[196:199], 0
	v_mfma_f32_16x16x32_bf16 v[106:109], v[162:165], v[196:199], 0
	v_mfma_f32_16x16x32_bf16 v[98:101], v[154:157], v[204:207], 0
	v_mfma_f32_16x16x32_bf16 v[90:93], v[162:165], v[204:207], 0
	v_mfma_f32_16x16x32_bf16 v[82:85], v[154:157], v[212:215], 0
	v_mfma_f32_16x16x32_bf16 v[74:77], v[162:165], v[212:215], 0
	v_mfma_f32_16x16x32_bf16 v[126:129], v[158:161], v[192:195], v[126:129]
	v_mfma_f32_16x16x32_bf16 v[122:125], v[166:169], v[192:195], v[122:125]
	v_mfma_f32_16x16x32_bf16 v[114:117], v[158:161], v[200:203], v[114:117]
	v_mfma_f32_16x16x32_bf16 v[106:109], v[166:169], v[200:203], v[106:109]
	v_mfma_f32_16x16x32_bf16 v[98:101], v[158:161], v[208:211], v[98:101]
	v_mfma_f32_16x16x32_bf16 v[90:93], v[166:169], v[208:211], v[90:93]
	v_mfma_f32_16x16x32_bf16 v[82:85], v[158:161], v[216:219], v[82:85]
	v_mfma_f32_16x16x32_bf16 v[74:77], v[166:169], v[216:219], v[74:77]
	s_setprio 0
	s_setprio 1
	v_mfma_f32_16x16x32_bf16 v[118:121], v[170:173], v[188:191], 0
	v_mfma_f32_16x16x32_bf16 v[110:113], v[180:183], v[188:191], 0
	v_mfma_f32_16x16x32_bf16 v[102:105], v[170:173], v[196:199], 0
	v_mfma_f32_16x16x32_bf16 v[94:97], v[180:183], v[196:199], 0
	v_mfma_f32_16x16x32_bf16 v[86:89], v[170:173], v[204:207], 0
	v_mfma_f32_16x16x32_bf16 v[78:81], v[180:183], v[204:207], 0
	v_mfma_f32_16x16x32_bf16 v[70:73], v[170:173], v[212:215], 0
	v_mfma_f32_16x16x32_bf16 v[66:69], v[180:183], v[212:215], 0
	v_mfma_f32_16x16x32_bf16 v[118:121], v[176:179], v[192:195], v[118:121]
	v_mfma_f32_16x16x32_bf16 v[110:113], v[184:187], v[192:195], v[110:113]
	v_mfma_f32_16x16x32_bf16 v[102:105], v[176:179], v[200:203], v[102:105]
	v_mfma_f32_16x16x32_bf16 v[94:97], v[184:187], v[200:203], v[94:97]
	v_mfma_f32_16x16x32_bf16 v[86:89], v[176:179], v[208:211], v[86:89]
	v_mfma_f32_16x16x32_bf16 v[78:81], v[184:187], v[208:211], v[78:81]
	v_mfma_f32_16x16x32_bf16 v[70:73], v[176:179], v[216:219], v[70:73]
	v_mfma_f32_16x16x32_bf16 v[66:69], v[184:187], v[216:219], v[66:69]
	s_setprio 0
	s_barrier
	s_add_i32 s24, s80, s3
	s_mov_b32 m0, s24
	ds_read_b128 v[188:191], v152 offset:16384
	ds_read_b128 v[192:195], v152 offset:17408
	ds_read_b128 v[196:199], v152 offset:18432
	ds_read_b128 v[200:203], v152 offset:19456
	ds_read_b128 v[204:207], v152 offset:20480
	ds_read_b128 v[208:211], v152 offset:21504
	ds_read_b128 v[212:215], v152 offset:22528
	ds_read_b128 v[216:219], v152 offset:23552
	global_load_lds_dwordx4 v134, s[10:11]
	s_add_i32 m0, s24, 0x2000
	s_add_u32 s24, s10, 0x100000
	s_addc_u32 s25, s11, 0
	s_add_i32 s90, s81, s3
	global_load_lds_dwordx4 v130, s[10:11]
	s_mov_b32 m0, s90
	s_nop 0
	global_load_lds_dwordx4 v134, s[24:25]
	s_add_i32 m0, s90, 0x2000
	s_nop 0
	global_load_lds_dwordx4 v130, s[24:25]
	s_mov_b32 m0, s50
	s_nop 0
	global_load_lds_dwordx4 v136, s[34:35]
	s_mov_b32 m0, s51
	s_nop 0
	global_load_lds_dwordx4 v132, s[34:35]
	s_waitcnt vmcnt(8)
	s_waitcnt lgkmcnt(0)
	s_barrier
	s_setprio 1
	s_waitcnt lgkmcnt(0)
	v_mfma_f32_16x16x32_bf16 v[62:65], v[154:157], v[188:191], 0
	v_mfma_f32_16x16x32_bf16 v[58:61], v[162:165], v[188:191], 0
	v_mfma_f32_16x16x32_bf16 v[50:53], v[154:157], v[196:199], 0
	v_mfma_f32_16x16x32_bf16 v[42:45], v[162:165], v[196:199], 0
	v_mfma_f32_16x16x32_bf16 v[34:37], v[154:157], v[204:207], 0
	v_mfma_f32_16x16x32_bf16 v[26:29], v[162:165], v[204:207], 0
	v_mfma_f32_16x16x32_bf16 v[18:21], v[154:157], v[212:215], 0
	v_mfma_f32_16x16x32_bf16 v[10:13], v[162:165], v[212:215], 0
	v_mfma_f32_16x16x32_bf16 v[62:65], v[158:161], v[192:195], v[62:65]
	v_mfma_f32_16x16x32_bf16 v[58:61], v[166:169], v[192:195], v[58:61]
	v_mfma_f32_16x16x32_bf16 v[50:53], v[158:161], v[200:203], v[50:53]
	v_mfma_f32_16x16x32_bf16 v[42:45], v[166:169], v[200:203], v[42:45]
	v_mfma_f32_16x16x32_bf16 v[34:37], v[158:161], v[208:211], v[34:37]
	v_mfma_f32_16x16x32_bf16 v[26:29], v[166:169], v[208:211], v[26:29]
	v_mfma_f32_16x16x32_bf16 v[18:21], v[158:161], v[216:219], v[18:21]
	v_mfma_f32_16x16x32_bf16 v[10:13], v[166:169], v[216:219], v[10:13]
	s_setprio 0
	s_setprio 1
	v_mfma_f32_16x16x32_bf16 v[54:57], v[170:173], v[188:191], 0
	v_mfma_f32_16x16x32_bf16 v[46:49], v[180:183], v[188:191], 0
	v_mfma_f32_16x16x32_bf16 v[38:41], v[170:173], v[196:199], 0
	v_mfma_f32_16x16x32_bf16 v[30:33], v[180:183], v[196:199], 0
	v_mfma_f32_16x16x32_bf16 v[22:25], v[170:173], v[204:207], 0
	v_mfma_f32_16x16x32_bf16 v[14:17], v[180:183], v[204:207], 0
	v_mfma_f32_16x16x32_bf16 v[6:9], v[170:173], v[212:215], 0
	v_mfma_f32_16x16x32_bf16 v[2:5], v[180:183], v[212:215], 0
	v_mfma_f32_16x16x32_bf16 v[54:57], v[176:179], v[192:195], v[54:57]
	v_mfma_f32_16x16x32_bf16 v[46:49], v[184:187], v[192:195], v[46:49]
	v_mfma_f32_16x16x32_bf16 v[38:41], v[176:179], v[200:203], v[38:41]
	v_mfma_f32_16x16x32_bf16 v[30:33], v[184:187], v[200:203], v[30:33]
	v_mfma_f32_16x16x32_bf16 v[22:25], v[176:179], v[208:211], v[22:25]
	v_mfma_f32_16x16x32_bf16 v[14:17], v[184:187], v[208:211], v[14:17]
	v_mfma_f32_16x16x32_bf16 v[6:9], v[176:179], v[216:219], v[6:9]
	v_mfma_f32_16x16x32_bf16 v[2:5], v[184:187], v[216:219], v[2:5]
	s_setprio 0
	s_barrier
	s_add_i32 s90, 0, 0x18000
	v_add_u32_e32 v153, s90, v148
	s_add_i32 s91, 0, 0x1c000
	ds_read_b128 v[154:157], v153
	ds_read_b128 v[158:161], v153 offset:1024
	ds_read_b128 v[162:165], v153 offset:2048
	ds_read_b128 v[166:169], v153 offset:3072
	v_add_u32_e32 v153, s91, v148
	ds_read_b128 v[170:173], v153
	ds_read_b128 v[176:179], v153 offset:1024
	ds_read_b128 v[180:183], v153 offset:2048
	ds_read_b128 v[184:187], v153 offset:3072
	s_add_u32 s24, s34, 0x100000
	s_addc_u32 s25, s35, 0
	s_mov_b32 m0, s59
	ds_read_b128 v[188:191], v152 offset:32768
	ds_read_b128 v[192:195], v152 offset:33792
	ds_read_b128 v[196:199], v152 offset:34816
	ds_read_b128 v[200:203], v152 offset:35840
	ds_read_b128 v[204:207], v152 offset:36864
	ds_read_b128 v[208:211], v152 offset:37888
	ds_read_b128 v[212:215], v152 offset:38912
	ds_read_b128 v[216:219], v152 offset:39936
	global_load_lds_dwordx4 v136, s[24:25]
	s_mov_b32 m0, s62
	s_nop 0
	global_load_lds_dwordx4 v132, s[24:25]
	s_waitcnt vmcnt(8)
	s_waitcnt lgkmcnt(0)
	s_barrier
	s_setprio 1
	s_waitcnt lgkmcnt(0)
	v_mfma_f32_16x16x32_bf16 v[126:129], v[154:157], v[188:191], v[126:129]
	v_mfma_f32_16x16x32_bf16 v[122:125], v[162:165], v[188:191], v[122:125]
	v_mfma_f32_16x16x32_bf16 v[114:117], v[154:157], v[196:199], v[114:117]
	v_mfma_f32_16x16x32_bf16 v[106:109], v[162:165], v[196:199], v[106:109]
	v_mfma_f32_16x16x32_bf16 v[98:101], v[154:157], v[204:207], v[98:101]
	v_mfma_f32_16x16x32_bf16 v[90:93], v[162:165], v[204:207], v[90:93]
	v_mfma_f32_16x16x32_bf16 v[82:85], v[154:157], v[212:215], v[82:85]
	v_mfma_f32_16x16x32_bf16 v[74:77], v[162:165], v[212:215], v[74:77]
	v_mfma_f32_16x16x32_bf16 v[126:129], v[158:161], v[192:195], v[126:129]
	v_mfma_f32_16x16x32_bf16 v[122:125], v[166:169], v[192:195], v[122:125]
	v_mfma_f32_16x16x32_bf16 v[114:117], v[158:161], v[200:203], v[114:117]
	v_mfma_f32_16x16x32_bf16 v[106:109], v[166:169], v[200:203], v[106:109]
	v_mfma_f32_16x16x32_bf16 v[98:101], v[158:161], v[208:211], v[98:101]
	v_mfma_f32_16x16x32_bf16 v[90:93], v[166:169], v[208:211], v[90:93]
	v_mfma_f32_16x16x32_bf16 v[82:85], v[158:161], v[216:219], v[82:85]
	v_mfma_f32_16x16x32_bf16 v[74:77], v[166:169], v[216:219], v[74:77]
	s_setprio 0
	s_setprio 1
	v_mfma_f32_16x16x32_bf16 v[118:121], v[170:173], v[188:191], v[118:121]
	v_mfma_f32_16x16x32_bf16 v[110:113], v[180:183], v[188:191], v[110:113]
	v_mfma_f32_16x16x32_bf16 v[102:105], v[170:173], v[196:199], v[102:105]
	v_mfma_f32_16x16x32_bf16 v[94:97], v[180:183], v[196:199], v[94:97]
	v_mfma_f32_16x16x32_bf16 v[86:89], v[170:173], v[204:207], v[86:89]
	v_mfma_f32_16x16x32_bf16 v[78:81], v[180:183], v[204:207], v[78:81]
	v_mfma_f32_16x16x32_bf16 v[70:73], v[170:173], v[212:215], v[70:73]
	v_mfma_f32_16x16x32_bf16 v[66:69], v[180:183], v[212:215], v[66:69]
	v_mfma_f32_16x16x32_bf16 v[118:121], v[176:179], v[192:195], v[118:121]
	v_mfma_f32_16x16x32_bf16 v[110:113], v[184:187], v[192:195], v[110:113]
	v_mfma_f32_16x16x32_bf16 v[102:105], v[176:179], v[200:203], v[102:105]
	v_mfma_f32_16x16x32_bf16 v[94:97], v[184:187], v[200:203], v[94:97]
	v_mfma_f32_16x16x32_bf16 v[86:89], v[176:179], v[208:211], v[86:89]
	v_mfma_f32_16x16x32_bf16 v[78:81], v[184:187], v[208:211], v[78:81]
	v_mfma_f32_16x16x32_bf16 v[70:73], v[176:179], v[216:219], v[70:73]
	v_mfma_f32_16x16x32_bf16 v[66:69], v[184:187], v[216:219], v[66:69]
	s_setprio 0
	s_barrier
	s_add_u32 s12, s10, 0x80
	s_addc_u32 s13, s11, 0
	s_add_u32 s14, s34, 0x80
	s_addc_u32 s15, s35, 0
	s_add_i32 s24, s90, s3
	s_mov_b32 m0, s24
	ds_read_b128 v[188:191], v152 offset:49152
	ds_read_b128 v[192:195], v152 offset:50176
	ds_read_b128 v[196:199], v152 offset:51200
	ds_read_b128 v[200:203], v152 offset:52224
	ds_read_b128 v[204:207], v152 offset:53248
	ds_read_b128 v[208:211], v152 offset:54272
	ds_read_b128 v[212:215], v152 offset:55296
	ds_read_b128 v[216:219], v152 offset:56320
	global_load_lds_dwordx4 v134, s[12:13]
	s_add_i32 m0, s24, 0x2000
	s_add_u32 s10, s10, 0x100080
	s_addc_u32 s11, s11, 0
	s_add_i32 s24, s91, s3
	global_load_lds_dwordx4 v130, s[12:13]
	s_mov_b32 m0, s24
	s_nop 0
	global_load_lds_dwordx4 v134, s[10:11]
	s_add_i32 m0, s24, 0x2000
	s_nop 0
	global_load_lds_dwordx4 v130, s[10:11]
	s_mov_b32 m0, s75
	s_nop 0
	global_load_lds_dwordx4 v136, s[14:15]
	s_mov_b32 m0, s78
	s_nop 0
	global_load_lds_dwordx4 v132, s[14:15]
	s_waitcnt vmcnt(8)
	s_waitcnt lgkmcnt(0)
	s_barrier
	s_setprio 1
	s_waitcnt lgkmcnt(0)
	v_mfma_f32_16x16x32_bf16 v[62:65], v[154:157], v[188:191], v[62:65]
	v_mfma_f32_16x16x32_bf16 v[58:61], v[162:165], v[188:191], v[58:61]
	v_mfma_f32_16x16x32_bf16 v[50:53], v[154:157], v[196:199], v[50:53]
	v_mfma_f32_16x16x32_bf16 v[42:45], v[162:165], v[196:199], v[42:45]
	v_mfma_f32_16x16x32_bf16 v[34:37], v[154:157], v[204:207], v[34:37]
	v_mfma_f32_16x16x32_bf16 v[26:29], v[162:165], v[204:207], v[26:29]
	v_mfma_f32_16x16x32_bf16 v[18:21], v[154:157], v[212:215], v[18:21]
	v_mfma_f32_16x16x32_bf16 v[10:13], v[162:165], v[212:215], v[10:13]
	v_mfma_f32_16x16x32_bf16 v[62:65], v[158:161], v[192:195], v[62:65]
	v_mfma_f32_16x16x32_bf16 v[58:61], v[166:169], v[192:195], v[58:61]
	v_mfma_f32_16x16x32_bf16 v[50:53], v[158:161], v[200:203], v[50:53]
	v_mfma_f32_16x16x32_bf16 v[42:45], v[166:169], v[200:203], v[42:45]
	v_mfma_f32_16x16x32_bf16 v[34:37], v[158:161], v[208:211], v[34:37]
	v_mfma_f32_16x16x32_bf16 v[26:29], v[166:169], v[208:211], v[26:29]
	v_mfma_f32_16x16x32_bf16 v[18:21], v[158:161], v[216:219], v[18:21]
	v_mfma_f32_16x16x32_bf16 v[10:13], v[166:169], v[216:219], v[10:13]
	s_setprio 0
	s_setprio 1
	v_mfma_f32_16x16x32_bf16 v[54:57], v[170:173], v[188:191], v[54:57]
	v_mfma_f32_16x16x32_bf16 v[46:49], v[180:183], v[188:191], v[46:49]
	v_mfma_f32_16x16x32_bf16 v[38:41], v[170:173], v[196:199], v[38:41]
	v_mfma_f32_16x16x32_bf16 v[30:33], v[180:183], v[196:199], v[30:33]
	v_mfma_f32_16x16x32_bf16 v[22:25], v[170:173], v[204:207], v[22:25]
	v_mfma_f32_16x16x32_bf16 v[14:17], v[180:183], v[204:207], v[14:17]
	v_mfma_f32_16x16x32_bf16 v[6:9], v[170:173], v[212:215], v[6:9]
	v_mfma_f32_16x16x32_bf16 v[2:5], v[180:183], v[212:215], v[2:5]
	v_mfma_f32_16x16x32_bf16 v[54:57], v[176:179], v[192:195], v[54:57]
	v_mfma_f32_16x16x32_bf16 v[46:49], v[184:187], v[192:195], v[46:49]
	v_mfma_f32_16x16x32_bf16 v[38:41], v[176:179], v[200:203], v[38:41]
	v_mfma_f32_16x16x32_bf16 v[30:33], v[184:187], v[200:203], v[30:33]
	v_mfma_f32_16x16x32_bf16 v[22:25], v[176:179], v[208:211], v[22:25]
	v_mfma_f32_16x16x32_bf16 v[14:17], v[184:187], v[208:211], v[14:17]
	v_mfma_f32_16x16x32_bf16 v[6:9], v[176:179], v[216:219], v[6:9]
	v_mfma_f32_16x16x32_bf16 v[2:5], v[184:187], v[216:219], v[2:5]
	s_setprio 0
	s_barrier
	s_add_i32 s89, s89, 2
	s_add_u32 s60, s60, 0x100
	s_addc_u32 s61, s61, 0
	s_add_u32 s87, s87, 0x100
	s_addc_u32 s88, s88, 0
	s_cmp_gt_u32 s89, 61
	s_cbranch_scc1 .Lpeel_exit_3
.LBB0_650:
	ds_read_b128 v[154:157], v150
	ds_read_b128 v[158:161], v150 offset:1024
	ds_read_b128 v[162:165], v150 offset:2048
	ds_read_b128 v[166:169], v150 offset:3072
	ds_read_b128 v[170:173], v151
	ds_read_b128 v[176:179], v151 offset:1024
	ds_read_b128 v[180:183], v151 offset:2048
	ds_read_b128 v[184:187], v151 offset:3072
	s_add_u32 s10, s60, 0xfff00080
	s_addc_u32 s11, s61, -1
	s_cmp_eq_u32 s89, 60
	s_cselect_b32 s35, s47, s11
	s_cselect_b32 s34, s85, s10
	s_cselect_b32 s11, s45, s88
	s_cselect_b32 s10, s86, s87
	s_add_i32 m0, s50, 0xc000
	ds_read_b128 v[188:191], v152
	ds_read_b128 v[192:195], v152 offset:1024
	ds_read_b128 v[196:199], v152 offset:2048
	ds_read_b128 v[200:203], v152 offset:3072
	ds_read_b128 v[204:207], v152 offset:4096
	ds_read_b128 v[208:211], v152 offset:5120
	ds_read_b128 v[212:215], v152 offset:6144
	ds_read_b128 v[216:219], v152 offset:7168
	global_load_lds_dwordx4 v138, s[60:61]
	s_add_i32 m0, s50, 0xe000
	s_nop 0
	global_load_lds_dwordx4 v140, s[60:61]
	s_waitcnt vmcnt(8)
	s_waitcnt lgkmcnt(0)
	s_barrier
	s_setprio 1
	s_waitcnt lgkmcnt(0)
	v_mfma_f32_16x16x32_bf16 v[126:129], v[154:157], v[188:191], v[126:129]
	v_mfma_f32_16x16x32_bf16 v[122:125], v[162:165], v[188:191], v[122:125]
	v_mfma_f32_16x16x32_bf16 v[114:117], v[154:157], v[196:199], v[114:117]
	v_mfma_f32_16x16x32_bf16 v[106:109], v[162:165], v[196:199], v[106:109]
	v_mfma_f32_16x16x32_bf16 v[98:101], v[154:157], v[204:207], v[98:101]
	v_mfma_f32_16x16x32_bf16 v[90:93], v[162:165], v[204:207], v[90:93]
	v_mfma_f32_16x16x32_bf16 v[82:85], v[154:157], v[212:215], v[82:85]
	v_mfma_f32_16x16x32_bf16 v[74:77], v[162:165], v[212:215], v[74:77]
	v_mfma_f32_16x16x32_bf16 v[126:129], v[158:161], v[192:195], v[126:129]
	v_mfma_f32_16x16x32_bf16 v[122:125], v[166:169], v[192:195], v[122:125]
	v_mfma_f32_16x16x32_bf16 v[114:117], v[158:161], v[200:203], v[114:117]
	v_mfma_f32_16x16x32_bf16 v[106:109], v[166:169], v[200:203], v[106:109]
	v_mfma_f32_16x16x32_bf16 v[98:101], v[158:161], v[208:211], v[98:101]
	v_mfma_f32_16x16x32_bf16 v[90:93], v[166:169], v[208:211], v[90:93]
	v_mfma_f32_16x16x32_bf16 v[82:85], v[158:161], v[216:219], v[82:85]
	v_mfma_f32_16x16x32_bf16 v[74:77], v[166:169], v[216:219], v[74:77]
	s_setprio 0
	s_setprio 1
	v_mfma_f32_16x16x32_bf16 v[118:121], v[170:173], v[188:191], v[118:121]
	v_mfma_f32_16x16x32_bf16 v[110:113], v[180:183], v[188:191], v[110:113]
	v_mfma_f32_16x16x32_bf16 v[102:105], v[170:173], v[196:199], v[102:105]
	v_mfma_f32_16x16x32_bf16 v[94:97], v[180:183], v[196:199], v[94:97]
	v_mfma_f32_16x16x32_bf16 v[86:89], v[170:173], v[204:207], v[86:89]
	v_mfma_f32_16x16x32_bf16 v[78:81], v[180:183], v[204:207], v[78:81]
	v_mfma_f32_16x16x32_bf16 v[70:73], v[170:173], v[212:215], v[70:73]
	v_mfma_f32_16x16x32_bf16 v[66:69], v[180:183], v[212:215], v[66:69]
	v_mfma_f32_16x16x32_bf16 v[118:121], v[176:179], v[192:195], v[118:121]
	v_mfma_f32_16x16x32_bf16 v[110:113], v[184:187], v[192:195], v[110:113]
	v_mfma_f32_16x16x32_bf16 v[102:105], v[176:179], v[200:203], v[102:105]
	v_mfma_f32_16x16x32_bf16 v[94:97], v[184:187], v[200:203], v[94:97]
	v_mfma_f32_16x16x32_bf16 v[86:89], v[176:179], v[208:211], v[86:89]
	v_mfma_f32_16x16x32_bf16 v[78:81], v[184:187], v[208:211], v[78:81]
	v_mfma_f32_16x16x32_bf16 v[70:73], v[176:179], v[216:219], v[70:73]
	v_mfma_f32_16x16x32_bf16 v[66:69], v[184:187], v[216:219], v[66:69]
	s_setprio 0
	s_barrier
	s_add_i32 s24, s80, s3
	s_mov_b32 m0, s24
	ds_read_b128 v[188:191], v152 offset:16384
	ds_read_b128 v[192:195], v152 offset:17408
	ds_read_b128 v[196:199], v152 offset:18432
	ds_read_b128 v[200:203], v152 offset:19456
	ds_read_b128 v[204:207], v152 offset:20480
	ds_read_b128 v[208:211], v152 offset:21504
	ds_read_b128 v[212:215], v152 offset:22528
	ds_read_b128 v[216:219], v152 offset:23552
	global_load_lds_dwordx4 v134, s[10:11]
	s_add_i32 m0, s24, 0x2000
	s_add_u32 s24, s10, 0x100000
	s_addc_u32 s25, s11, 0
	s_add_i32 s90, s81, s3
	global_load_lds_dwordx4 v130, s[10:11]
	s_mov_b32 m0, s90
	s_nop 0
	global_load_lds_dwordx4 v134, s[24:25]
	s_add_i32 m0, s90, 0x2000
	s_nop 0
	global_load_lds_dwordx4 v130, s[24:25]
	s_mov_b32 m0, s50
	s_nop 0
	global_load_lds_dwordx4 v136, s[34:35]
	s_mov_b32 m0, s51
	s_nop 0
	global_load_lds_dwordx4 v132, s[34:35]
	s_waitcnt vmcnt(8)
	s_waitcnt lgkmcnt(0)
	s_barrier
	s_setprio 1
	s_waitcnt lgkmcnt(0)
	v_mfma_f32_16x16x32_bf16 v[62:65], v[154:157], v[188:191], v[62:65]
	v_mfma_f32_16x16x32_bf16 v[58:61], v[162:165], v[188:191], v[58:61]
	v_mfma_f32_16x16x32_bf16 v[50:53], v[154:157], v[196:199], v[50:53]
	v_mfma_f32_16x16x32_bf16 v[42:45], v[162:165], v[196:199], v[42:45]
	v_mfma_f32_16x16x32_bf16 v[34:37], v[154:157], v[204:207], v[34:37]
	v_mfma_f32_16x16x32_bf16 v[26:29], v[162:165], v[204:207], v[26:29]
	v_mfma_f32_16x16x32_bf16 v[18:21], v[154:157], v[212:215], v[18:21]
	v_mfma_f32_16x16x32_bf16 v[10:13], v[162:165], v[212:215], v[10:13]
	v_mfma_f32_16x16x32_bf16 v[62:65], v[158:161], v[192:195], v[62:65]
	v_mfma_f32_16x16x32_bf16 v[58:61], v[166:169], v[192:195], v[58:61]
	v_mfma_f32_16x16x32_bf16 v[50:53], v[158:161], v[200:203], v[50:53]
	v_mfma_f32_16x16x32_bf16 v[42:45], v[166:169], v[200:203], v[42:45]
	v_mfma_f32_16x16x32_bf16 v[34:37], v[158:161], v[208:211], v[34:37]
	v_mfma_f32_16x16x32_bf16 v[26:29], v[166:169], v[208:211], v[26:29]
	v_mfma_f32_16x16x32_bf16 v[18:21], v[158:161], v[216:219], v[18:21]
	v_mfma_f32_16x16x32_bf16 v[10:13], v[166:169], v[216:219], v[10:13]
	s_setprio 0
	s_setprio 1
	v_mfma_f32_16x16x32_bf16 v[54:57], v[170:173], v[188:191], v[54:57]
	v_mfma_f32_16x16x32_bf16 v[46:49], v[180:183], v[188:191], v[46:49]
	v_mfma_f32_16x16x32_bf16 v[38:41], v[170:173], v[196:199], v[38:41]
	v_mfma_f32_16x16x32_bf16 v[30:33], v[180:183], v[196:199], v[30:33]
	v_mfma_f32_16x16x32_bf16 v[22:25], v[170:173], v[204:207], v[22:25]
	v_mfma_f32_16x16x32_bf16 v[14:17], v[180:183], v[204:207], v[14:17]
	v_mfma_f32_16x16x32_bf16 v[6:9], v[170:173], v[212:215], v[6:9]
	v_mfma_f32_16x16x32_bf16 v[2:5], v[180:183], v[212:215], v[2:5]
	v_mfma_f32_16x16x32_bf16 v[54:57], v[176:179], v[192:195], v[54:57]
	v_mfma_f32_16x16x32_bf16 v[46:49], v[184:187], v[192:195], v[46:49]
	v_mfma_f32_16x16x32_bf16 v[38:41], v[176:179], v[200:203], v[38:41]
	v_mfma_f32_16x16x32_bf16 v[30:33], v[184:187], v[200:203], v[30:33]
	v_mfma_f32_16x16x32_bf16 v[22:25], v[176:179], v[208:211], v[22:25]
	v_mfma_f32_16x16x32_bf16 v[14:17], v[184:187], v[208:211], v[14:17]
	v_mfma_f32_16x16x32_bf16 v[6:9], v[176:179], v[216:219], v[6:9]
	v_mfma_f32_16x16x32_bf16 v[2:5], v[184:187], v[216:219], v[2:5]
	s_setprio 0
	s_barrier
	s_add_i32 s90, 0, 0x18000
	v_add_u32_e32 v153, s90, v148
	s_add_i32 s91, 0, 0x1c000
	ds_read_b128 v[154:157], v153
	ds_read_b128 v[158:161], v153 offset:1024
	ds_read_b128 v[162:165], v153 offset:2048
	ds_read_b128 v[166:169], v153 offset:3072
	v_add_u32_e32 v153, s91, v148
	ds_read_b128 v[170:173], v153
	ds_read_b128 v[176:179], v153 offset:1024
	ds_read_b128 v[180:183], v153 offset:2048
	ds_read_b128 v[184:187], v153 offset:3072
	s_add_u32 s24, s34, 0x100000
	s_addc_u32 s25, s35, 0
	s_mov_b32 m0, s59
	ds_read_b128 v[188:191], v152 offset:32768
	ds_read_b128 v[192:195], v152 offset:33792
	ds_read_b128 v[196:199], v152 offset:34816
	ds_read_b128 v[200:203], v152 offset:35840
	ds_read_b128 v[204:207], v152 offset:36864
	ds_read_b128 v[208:211], v152 offset:37888
	ds_read_b128 v[212:215], v152 offset:38912
	ds_read_b128 v[216:219], v152 offset:39936
	global_load_lds_dwordx4 v136, s[24:25]
	s_mov_b32 m0, s62
	s_nop 0
	global_load_lds_dwordx4 v132, s[24:25]
	s_waitcnt vmcnt(8)
	s_waitcnt lgkmcnt(0)
	s_barrier
	s_setprio 1
	s_waitcnt lgkmcnt(0)
	v_mfma_f32_16x16x32_bf16 v[126:129], v[154:157], v[188:191], v[126:129]
	v_mfma_f32_16x16x32_bf16 v[122:125], v[162:165], v[188:191], v[122:125]
	v_mfma_f32_16x16x32_bf16 v[114:117], v[154:157], v[196:199], v[114:117]
	v_mfma_f32_16x16x32_bf16 v[106:109], v[162:165], v[196:199], v[106:109]
	v_mfma_f32_16x16x32_bf16 v[98:101], v[154:157], v[204:207], v[98:101]
	v_mfma_f32_16x16x32_bf16 v[90:93], v[162:165], v[204:207], v[90:93]
	v_mfma_f32_16x16x32_bf16 v[82:85], v[154:157], v[212:215], v[82:85]
	v_mfma_f32_16x16x32_bf16 v[74:77], v[162:165], v[212:215], v[74:77]
	v_mfma_f32_16x16x32_bf16 v[126:129], v[158:161], v[192:195], v[126:129]
	v_mfma_f32_16x16x32_bf16 v[122:125], v[166:169], v[192:195], v[122:125]
	v_mfma_f32_16x16x32_bf16 v[114:117], v[158:161], v[200:203], v[114:117]
	v_mfma_f32_16x16x32_bf16 v[106:109], v[166:169], v[200:203], v[106:109]
	v_mfma_f32_16x16x32_bf16 v[98:101], v[158:161], v[208:211], v[98:101]
	v_mfma_f32_16x16x32_bf16 v[90:93], v[166:169], v[208:211], v[90:93]
	v_mfma_f32_16x16x32_bf16 v[82:85], v[158:161], v[216:219], v[82:85]
	v_mfma_f32_16x16x32_bf16 v[74:77], v[166:169], v[216:219], v[74:77]
	s_setprio 0
	s_setprio 1
	v_mfma_f32_16x16x32_bf16 v[118:121], v[170:173], v[188:191], v[118:121]
	v_mfma_f32_16x16x32_bf16 v[110:113], v[180:183], v[188:191], v[110:113]
	v_mfma_f32_16x16x32_bf16 v[102:105], v[170:173], v[196:199], v[102:105]
	v_mfma_f32_16x16x32_bf16 v[94:97], v[180:183], v[196:199], v[94:97]
	v_mfma_f32_16x16x32_bf16 v[86:89], v[170:173], v[204:207], v[86:89]
	v_mfma_f32_16x16x32_bf16 v[78:81], v[180:183], v[204:207], v[78:81]
	v_mfma_f32_16x16x32_bf16 v[70:73], v[170:173], v[212:215], v[70:73]
	v_mfma_f32_16x16x32_bf16 v[66:69], v[180:183], v[212:215], v[66:69]
	v_mfma_f32_16x16x32_bf16 v[118:121], v[176:179], v[192:195], v[118:121]
	v_mfma_f32_16x16x32_bf16 v[110:113], v[184:187], v[192:195], v[110:113]
	v_mfma_f32_16x16x32_bf16 v[102:105], v[176:179], v[200:203], v[102:105]
	v_mfma_f32_16x16x32_bf16 v[94:97], v[184:187], v[200:203], v[94:97]
	v_mfma_f32_16x16x32_bf16 v[86:89], v[176:179], v[208:211], v[86:89]
	v_mfma_f32_16x16x32_bf16 v[78:81], v[184:187], v[208:211], v[78:81]
	v_mfma_f32_16x16x32_bf16 v[70:73], v[176:179], v[216:219], v[70:73]
	v_mfma_f32_16x16x32_bf16 v[66:69], v[184:187], v[216:219], v[66:69]
	s_setprio 0
	s_barrier
	s_add_u32 s12, s10, 0x80
	s_addc_u32 s13, s11, 0
	s_add_u32 s14, s34, 0x80
	s_addc_u32 s15, s35, 0
	s_add_i32 s24, s90, s3
	s_mov_b32 m0, s24
	ds_read_b128 v[188:191], v152 offset:49152
	ds_read_b128 v[192:195], v152 offset:50176
	ds_read_b128 v[196:199], v152 offset:51200
	ds_read_b128 v[200:203], v152 offset:52224
	ds_read_b128 v[204:207], v152 offset:53248
	ds_read_b128 v[208:211], v152 offset:54272
	ds_read_b128 v[212:215], v152 offset:55296
	ds_read_b128 v[216:219], v152 offset:56320
	global_load_lds_dwordx4 v134, s[12:13]
	s_add_i32 m0, s24, 0x2000
	s_add_u32 s10, s10, 0x100080
	s_addc_u32 s11, s11, 0
	s_add_i32 s24, s91, s3
	global_load_lds_dwordx4 v130, s[12:13]
	s_mov_b32 m0, s24
	s_nop 0
	global_load_lds_dwordx4 v134, s[10:11]
	s_add_i32 m0, s24, 0x2000
	s_nop 0
	global_load_lds_dwordx4 v130, s[10:11]
	s_mov_b32 m0, s75
	s_nop 0
	global_load_lds_dwordx4 v136, s[14:15]
	s_mov_b32 m0, s78
	s_nop 0
	global_load_lds_dwordx4 v132, s[14:15]
	s_waitcnt vmcnt(8)
	s_waitcnt lgkmcnt(0)
	s_barrier
	s_setprio 1
	s_waitcnt lgkmcnt(0)
	v_mfma_f32_16x16x32_bf16 v[62:65], v[154:157], v[188:191], v[62:65]
	v_mfma_f32_16x16x32_bf16 v[58:61], v[162:165], v[188:191], v[58:61]
	v_mfma_f32_16x16x32_bf16 v[50:53], v[154:157], v[196:199], v[50:53]
	v_mfma_f32_16x16x32_bf16 v[42:45], v[162:165], v[196:199], v[42:45]
	v_mfma_f32_16x16x32_bf16 v[34:37], v[154:157], v[204:207], v[34:37]
	v_mfma_f32_16x16x32_bf16 v[26:29], v[162:165], v[204:207], v[26:29]
	v_mfma_f32_16x16x32_bf16 v[18:21], v[154:157], v[212:215], v[18:21]
	v_mfma_f32_16x16x32_bf16 v[10:13], v[162:165], v[212:215], v[10:13]
	v_mfma_f32_16x16x32_bf16 v[62:65], v[158:161], v[192:195], v[62:65]
	v_mfma_f32_16x16x32_bf16 v[58:61], v[166:169], v[192:195], v[58:61]
	v_mfma_f32_16x16x32_bf16 v[50:53], v[158:161], v[200:203], v[50:53]
	v_mfma_f32_16x16x32_bf16 v[42:45], v[166:169], v[200:203], v[42:45]
	v_mfma_f32_16x16x32_bf16 v[34:37], v[158:161], v[208:211], v[34:37]
	v_mfma_f32_16x16x32_bf16 v[26:29], v[166:169], v[208:211], v[26:29]
	v_mfma_f32_16x16x32_bf16 v[18:21], v[158:161], v[216:219], v[18:21]
	v_mfma_f32_16x16x32_bf16 v[10:13], v[166:169], v[216:219], v[10:13]
	s_setprio 0
	s_setprio 1
	v_mfma_f32_16x16x32_bf16 v[54:57], v[170:173], v[188:191], v[54:57]
	v_mfma_f32_16x16x32_bf16 v[46:49], v[180:183], v[188:191], v[46:49]
	v_mfma_f32_16x16x32_bf16 v[38:41], v[170:173], v[196:199], v[38:41]
	v_mfma_f32_16x16x32_bf16 v[30:33], v[180:183], v[196:199], v[30:33]
	v_mfma_f32_16x16x32_bf16 v[22:25], v[170:173], v[204:207], v[22:25]
	v_mfma_f32_16x16x32_bf16 v[14:17], v[180:183], v[204:207], v[14:17]
	v_mfma_f32_16x16x32_bf16 v[6:9], v[170:173], v[212:215], v[6:9]
	v_mfma_f32_16x16x32_bf16 v[2:5], v[180:183], v[212:215], v[2:5]
	v_mfma_f32_16x16x32_bf16 v[54:57], v[176:179], v[192:195], v[54:57]
	v_mfma_f32_16x16x32_bf16 v[46:49], v[184:187], v[192:195], v[46:49]
	v_mfma_f32_16x16x32_bf16 v[38:41], v[176:179], v[200:203], v[38:41]
	v_mfma_f32_16x16x32_bf16 v[30:33], v[184:187], v[200:203], v[30:33]
	v_mfma_f32_16x16x32_bf16 v[22:25], v[176:179], v[208:211], v[22:25]
	v_mfma_f32_16x16x32_bf16 v[14:17], v[184:187], v[208:211], v[14:17]
	v_mfma_f32_16x16x32_bf16 v[6:9], v[176:179], v[216:219], v[6:9]
	v_mfma_f32_16x16x32_bf16 v[2:5], v[184:187], v[216:219], v[2:5]
	s_setprio 0
	s_barrier
	s_add_i32 s89, s89, 2
	s_add_u32 s60, s60, 0x100
	s_addc_u32 s61, s61, 0
	s_add_u32 s87, s87, 0x100
	s_addc_u32 s88, s88, 0
	s_cmp_gt_u32 s89, 61
	s_cbranch_scc0 .LBB0_650

.LBB0_823:
	s_ashr_i32 s27, s26, 31
	s_lshl_b64 s[30:31], s[26:27], 21
	s_add_u32 s40, s42, s30
	s_addc_u32 s41, s43, s31
	s_and_b64 s[30:31], s[38:39], exec
	s_cselect_b32 s27, s41, s11
	s_cselect_b32 s30, s40, s10
	s_ashr_i32 s37, s36, 31
	s_lshl_b64 s[44:45], s[36:37], 21
	v_readlane_b32 s12, v255, 39
	v_readlane_b32 s13, v255, 40
	s_add_u32 s44, s12, s44
	s_addc_u32 s45, s13, s45
	s_and_b64 s[48:49], s[38:39], exec
	s_cselect_b32 s31, s45, s35
	s_cselect_b32 s37, s44, s34
	s_add_u32 s48, s10, 0x100080
	s_addc_u32 s49, s11, 0
	s_add_u32 s83, s34, 0x100
	s_addc_u32 s84, s35, 0
	s_mov_b32 s85, -2
	ds_read_b128 v[152:155], v148
	ds_read_b128 v[156:159], v148 offset:1024
	ds_read_b128 v[160:163], v148 offset:2048
	ds_read_b128 v[164:167], v148 offset:3072
	ds_read_b128 v[168:171], v149
	ds_read_b128 v[176:179], v149 offset:1024
	ds_read_b128 v[180:183], v149 offset:2048
	ds_read_b128 v[184:187], v149 offset:3072
	s_add_u32 s10, s48, 0xfff00080
	s_addc_u32 s11, s49, -1
	s_cmp_eq_u32 s85, 60
	s_cselect_b32 s35, s27, s11
	s_cselect_b32 s34, s30, s10
	s_cselect_b32 s11, s31, s84
	s_cselect_b32 s10, s37, s83
	s_add_i32 m0, s47, 0xc000
	ds_read_b128 v[188:191], v150
	ds_read_b128 v[192:195], v150 offset:1024
	ds_read_b128 v[196:199], v150 offset:2048
	ds_read_b128 v[200:203], v150 offset:3072
	ds_read_b128 v[204:207], v150 offset:4096
	ds_read_b128 v[208:211], v150 offset:5120
	ds_read_b128 v[212:215], v150 offset:6144
	ds_read_b128 v[216:219], v150 offset:7168
	global_load_lds_dwordx4 v138, s[48:49]
	s_add_i32 m0, s47, 0xe000
	s_nop 0
	global_load_lds_dwordx4 v140, s[48:49]
	s_waitcnt vmcnt(8)
	s_waitcnt lgkmcnt(0)
	s_barrier
	s_setprio 1
	s_waitcnt lgkmcnt(0)
	v_mfma_f32_16x16x32_bf16 v[126:129], v[152:155], v[188:191], 0
	v_mfma_f32_16x16x32_bf16 v[118:121], v[160:163], v[188:191], 0
	v_mfma_f32_16x16x32_bf16 v[110:113], v[152:155], v[196:199], 0
	v_mfma_f32_16x16x32_bf16 v[102:105], v[160:163], v[196:199], 0
	v_mfma_f32_16x16x32_bf16 v[94:97], v[152:155], v[204:207], 0
	v_mfma_f32_16x16x32_bf16 v[86:89], v[160:163], v[204:207], 0
	v_mfma_f32_16x16x32_bf16 v[78:81], v[152:155], v[212:215], 0
	v_mfma_f32_16x16x32_bf16 v[70:73], v[160:163], v[212:215], 0
	v_mfma_f32_16x16x32_bf16 v[126:129], v[156:159], v[192:195], v[126:129]
	v_mfma_f32_16x16x32_bf16 v[118:121], v[164:167], v[192:195], v[118:121]
	v_mfma_f32_16x16x32_bf16 v[110:113], v[156:159], v[200:203], v[110:113]
	v_mfma_f32_16x16x32_bf16 v[102:105], v[164:167], v[200:203], v[102:105]
	v_mfma_f32_16x16x32_bf16 v[94:97], v[156:159], v[208:211], v[94:97]
	v_mfma_f32_16x16x32_bf16 v[86:89], v[164:167], v[208:211], v[86:89]
	v_mfma_f32_16x16x32_bf16 v[78:81], v[156:159], v[216:219], v[78:81]
	v_mfma_f32_16x16x32_bf16 v[70:73], v[164:167], v[216:219], v[70:73]
	s_setprio 0
	s_setprio 1
	v_mfma_f32_16x16x32_bf16 v[122:125], v[168:171], v[188:191], 0
	v_mfma_f32_16x16x32_bf16 v[114:117], v[180:183], v[188:191], 0
	v_mfma_f32_16x16x32_bf16 v[106:109], v[168:171], v[196:199], 0
	v_mfma_f32_16x16x32_bf16 v[98:101], v[180:183], v[196:199], 0
	v_mfma_f32_16x16x32_bf16 v[90:93], v[168:171], v[204:207], 0
	v_mfma_f32_16x16x32_bf16 v[82:85], v[180:183], v[204:207], 0
	v_mfma_f32_16x16x32_bf16 v[74:77], v[168:171], v[212:215], 0
	v_mfma_f32_16x16x32_bf16 v[66:69], v[180:183], v[212:215], 0
	v_mfma_f32_16x16x32_bf16 v[122:125], v[176:179], v[192:195], v[122:125]
	v_mfma_f32_16x16x32_bf16 v[114:117], v[184:187], v[192:195], v[114:117]
	v_mfma_f32_16x16x32_bf16 v[106:109], v[176:179], v[200:203], v[106:109]
	v_mfma_f32_16x16x32_bf16 v[98:101], v[184:187], v[200:203], v[98:101]
	v_mfma_f32_16x16x32_bf16 v[90:93], v[176:179], v[208:211], v[90:93]
	v_mfma_f32_16x16x32_bf16 v[82:85], v[184:187], v[208:211], v[82:85]
	v_mfma_f32_16x16x32_bf16 v[74:77], v[176:179], v[216:219], v[74:77]
	v_mfma_f32_16x16x32_bf16 v[66:69], v[184:187], v[216:219], v[66:69]
	s_setprio 0
	s_barrier
	s_add_i32 s86, s61, s51
	s_mov_b32 m0, s86
	ds_read_b128 v[188:191], v150 offset:16384
	ds_read_b128 v[192:195], v150 offset:17408
	ds_read_b128 v[196:199], v150 offset:18432
	ds_read_b128 v[200:203], v150 offset:19456
	ds_read_b128 v[204:207], v150 offset:20480
	ds_read_b128 v[208:211], v150 offset:21504
	ds_read_b128 v[212:215], v150 offset:22528
	ds_read_b128 v[216:219], v150 offset:23552
	global_load_lds_dwordx4 v132, s[10:11]
	s_add_i32 m0, s86, 0x2000
	s_add_u32 s86, s10, 0x100000
	s_addc_u32 s87, s11, 0
	s_add_i32 s88, s62, s51
	s_add_u32 s14, s34, 0x80
	s_addc_u32 s15, s35, 0
	global_load_lds_dwordx4 v136, s[10:11]
	s_mov_b32 m0, s88
	s_nop 0
	global_load_lds_dwordx4 v132, s[86:87]
	s_add_i32 m0, s88, 0x2000
	s_nop 0
	global_load_lds_dwordx4 v136, s[86:87]
	s_mov_b32 m0, s47
	s_nop 0
	global_load_lds_dwordx4 v130, s[34:35]
	s_mov_b32 m0, s54
	s_nop 0
	global_load_lds_dwordx4 v134, s[34:35]
	s_waitcnt vmcnt(8)
	s_waitcnt lgkmcnt(0)
	s_barrier
	s_setprio 1
	s_waitcnt lgkmcnt(0)
	v_mfma_f32_16x16x32_bf16 v[62:65], v[152:155], v[188:191], 0
	v_mfma_f32_16x16x32_bf16 v[54:57], v[160:163], v[188:191], 0
	v_mfma_f32_16x16x32_bf16 v[46:49], v[152:155], v[196:199], 0
	v_mfma_f32_16x16x32_bf16 v[38:41], v[160:163], v[196:199], 0
	v_mfma_f32_16x16x32_bf16 v[30:33], v[152:155], v[204:207], 0
	v_mfma_f32_16x16x32_bf16 v[22:25], v[160:163], v[204:207], 0
	v_mfma_f32_16x16x32_bf16 v[14:17], v[152:155], v[212:215], 0
	v_mfma_f32_16x16x32_bf16 v[6:9], v[160:163], v[212:215], 0
	v_mfma_f32_16x16x32_bf16 v[62:65], v[156:159], v[192:195], v[62:65]
	v_mfma_f32_16x16x32_bf16 v[54:57], v[164:167], v[192:195], v[54:57]
	v_mfma_f32_16x16x32_bf16 v[46:49], v[156:159], v[200:203], v[46:49]
	v_mfma_f32_16x16x32_bf16 v[38:41], v[164:167], v[200:203], v[38:41]
	v_mfma_f32_16x16x32_bf16 v[30:33], v[156:159], v[208:211], v[30:33]
	v_mfma_f32_16x16x32_bf16 v[22:25], v[164:167], v[208:211], v[22:25]
	v_mfma_f32_16x16x32_bf16 v[14:17], v[156:159], v[216:219], v[14:17]
	v_mfma_f32_16x16x32_bf16 v[6:9], v[164:167], v[216:219], v[6:9]
	s_setprio 0
	s_setprio 1
	v_mfma_f32_16x16x32_bf16 v[58:61], v[168:171], v[188:191], 0
	v_mfma_f32_16x16x32_bf16 v[50:53], v[180:183], v[188:191], 0
	v_mfma_f32_16x16x32_bf16 v[42:45], v[168:171], v[196:199], 0
	v_mfma_f32_16x16x32_bf16 v[34:37], v[180:183], v[196:199], 0
	v_mfma_f32_16x16x32_bf16 v[26:29], v[168:171], v[204:207], 0
	v_mfma_f32_16x16x32_bf16 v[18:21], v[180:183], v[204:207], 0
	v_mfma_f32_16x16x32_bf16 v[10:13], v[168:171], v[212:215], 0
	v_mfma_f32_16x16x32_bf16 v[2:5], v[180:183], v[212:215], 0
	v_mfma_f32_16x16x32_bf16 v[58:61], v[176:179], v[192:195], v[58:61]
	v_mfma_f32_16x16x32_bf16 v[50:53], v[184:187], v[192:195], v[50:53]
	v_mfma_f32_16x16x32_bf16 v[42:45], v[176:179], v[200:203], v[42:45]
	v_mfma_f32_16x16x32_bf16 v[34:37], v[184:187], v[200:203], v[34:37]
	v_mfma_f32_16x16x32_bf16 v[26:29], v[176:179], v[208:211], v[26:29]
	v_mfma_f32_16x16x32_bf16 v[18:21], v[184:187], v[208:211], v[18:21]
	v_mfma_f32_16x16x32_bf16 v[10:13], v[176:179], v[216:219], v[10:13]
	v_mfma_f32_16x16x32_bf16 v[2:5], v[184:187], v[216:219], v[2:5]
	s_setprio 0
	s_barrier
	s_add_i32 s86, 0, 0x18000
	v_add_u32_e32 v151, s86, v146
	s_add_i32 s87, 0, 0x1c000
	ds_read_b128 v[152:155], v151
	ds_read_b128 v[156:159], v151 offset:1024
	ds_read_b128 v[160:163], v151 offset:2048
	ds_read_b128 v[164:167], v151 offset:3072
	v_add_u32_e32 v151, s87, v146
	ds_read_b128 v[168:171], v151
	ds_read_b128 v[176:179], v151 offset:1024
	ds_read_b128 v[180:183], v151 offset:2048
	ds_read_b128 v[184:187], v151 offset:3072
	s_add_u32 s34, s34, 0x100000
	s_addc_u32 s35, s35, 0
	s_mov_b32 m0, s55
	ds_read_b128 v[188:191], v150 offset:32768
	ds_read_b128 v[192:195], v150 offset:33792
	ds_read_b128 v[196:199], v150 offset:34816
	ds_read_b128 v[200:203], v150 offset:35840
	ds_read_b128 v[204:207], v150 offset:36864
	ds_read_b128 v[208:211], v150 offset:37888
	ds_read_b128 v[212:215], v150 offset:38912
	ds_read_b128 v[216:219], v150 offset:39936
	global_load_lds_dwordx4 v130, s[34:35]
	s_mov_b32 m0, s56
	s_nop 0
	global_load_lds_dwordx4 v134, s[34:35]
	s_waitcnt vmcnt(8)
	s_waitcnt lgkmcnt(0)
	s_barrier
	s_setprio 1
	s_waitcnt lgkmcnt(0)
	v_mfma_f32_16x16x32_bf16 v[126:129], v[152:155], v[188:191], v[126:129]
	v_mfma_f32_16x16x32_bf16 v[118:121], v[160:163], v[188:191], v[118:121]
	v_mfma_f32_16x16x32_bf16 v[110:113], v[152:155], v[196:199], v[110:113]
	v_mfma_f32_16x16x32_bf16 v[102:105], v[160:163], v[196:199], v[102:105]
	v_mfma_f32_16x16x32_bf16 v[94:97], v[152:155], v[204:207], v[94:97]
	v_mfma_f32_16x16x32_bf16 v[86:89], v[160:163], v[204:207], v[86:89]
	v_mfma_f32_16x16x32_bf16 v[78:81], v[152:155], v[212:215], v[78:81]
	v_mfma_f32_16x16x32_bf16 v[70:73], v[160:163], v[212:215], v[70:73]
	v_mfma_f32_16x16x32_bf16 v[126:129], v[156:159], v[192:195], v[126:129]
	v_mfma_f32_16x16x32_bf16 v[118:121], v[164:167], v[192:195], v[118:121]
	v_mfma_f32_16x16x32_bf16 v[110:113], v[156:159], v[200:203], v[110:113]
	v_mfma_f32_16x16x32_bf16 v[102:105], v[164:167], v[200:203], v[102:105]
	v_mfma_f32_16x16x32_bf16 v[94:97], v[156:159], v[208:211], v[94:97]
	v_mfma_f32_16x16x32_bf16 v[86:89], v[164:167], v[208:211], v[86:89]
	v_mfma_f32_16x16x32_bf16 v[78:81], v[156:159], v[216:219], v[78:81]
	v_mfma_f32_16x16x32_bf16 v[70:73], v[164:167], v[216:219], v[70:73]
	s_setprio 0
	s_setprio 1
	v_mfma_f32_16x16x32_bf16 v[122:125], v[168:171], v[188:191], v[122:125]
	v_mfma_f32_16x16x32_bf16 v[114:117], v[180:183], v[188:191], v[114:117]
	v_mfma_f32_16x16x32_bf16 v[106:109], v[168:171], v[196:199], v[106:109]
	v_mfma_f32_16x16x32_bf16 v[98:101], v[180:183], v[196:199], v[98:101]
	v_mfma_f32_16x16x32_bf16 v[90:93], v[168:171], v[204:207], v[90:93]
	v_mfma_f32_16x16x32_bf16 v[82:85], v[180:183], v[204:207], v[82:85]
	v_mfma_f32_16x16x32_bf16 v[74:77], v[168:171], v[212:215], v[74:77]
	v_mfma_f32_16x16x32_bf16 v[66:69], v[180:183], v[212:215], v[66:69]
	v_mfma_f32_16x16x32_bf16 v[122:125], v[176:179], v[192:195], v[122:125]
	v_mfma_f32_16x16x32_bf16 v[114:117], v[184:187], v[192:195], v[114:117]
	v_mfma_f32_16x16x32_bf16 v[106:109], v[176:179], v[200:203], v[106:109]
	v_mfma_f32_16x16x32_bf16 v[98:101], v[184:187], v[200:203], v[98:101]
	v_mfma_f32_16x16x32_bf16 v[90:93], v[176:179], v[208:211], v[90:93]
	v_mfma_f32_16x16x32_bf16 v[82:85], v[184:187], v[208:211], v[82:85]
	v_mfma_f32_16x16x32_bf16 v[74:77], v[176:179], v[216:219], v[74:77]
	v_mfma_f32_16x16x32_bf16 v[66:69], v[184:187], v[216:219], v[66:69]
	s_setprio 0
	s_barrier
	s_add_u32 s12, s10, 0x80
	s_addc_u32 s13, s11, 0
	s_add_i32 s34, s86, s51
	s_mov_b32 m0, s34
	ds_read_b128 v[188:191], v150 offset:49152
	ds_read_b128 v[192:195], v150 offset:50176
	ds_read_b128 v[196:199], v150 offset:51200
	ds_read_b128 v[200:203], v150 offset:52224
	ds_read_b128 v[204:207], v150 offset:53248
	ds_read_b128 v[208:211], v150 offset:54272
	ds_read_b128 v[212:215], v150 offset:55296
	ds_read_b128 v[216:219], v150 offset:56320
	global_load_lds_dwordx4 v132, s[12:13]
	s_add_i32 m0, s34, 0x2000
	s_add_u32 s10, s10, 0x100080
	s_addc_u32 s11, s11, 0
	s_add_i32 s34, s87, s51
	global_load_lds_dwordx4 v136, s[12:13]
	s_mov_b32 m0, s34
	s_nop 0
	global_load_lds_dwordx4 v132, s[10:11]
	s_add_i32 m0, s34, 0x2000
	s_nop 0
	global_load_lds_dwordx4 v136, s[10:11]
	s_mov_b32 m0, s57
	s_nop 0
	global_load_lds_dwordx4 v130, s[14:15]
	s_mov_b32 m0, s58
	s_nop 0
	global_load_lds_dwordx4 v134, s[14:15]
	s_waitcnt vmcnt(8)
	s_waitcnt lgkmcnt(0)
	s_barrier
	s_setprio 1
	s_waitcnt lgkmcnt(0)
	v_mfma_f32_16x16x32_bf16 v[62:65], v[152:155], v[188:191], v[62:65]
	v_mfma_f32_16x16x32_bf16 v[54:57], v[160:163], v[188:191], v[54:57]
	v_mfma_f32_16x16x32_bf16 v[46:49], v[152:155], v[196:199], v[46:49]
	v_mfma_f32_16x16x32_bf16 v[38:41], v[160:163], v[196:199], v[38:41]
	v_mfma_f32_16x16x32_bf16 v[30:33], v[152:155], v[204:207], v[30:33]
	v_mfma_f32_16x16x32_bf16 v[22:25], v[160:163], v[204:207], v[22:25]
	v_mfma_f32_16x16x32_bf16 v[14:17], v[152:155], v[212:215], v[14:17]
	v_mfma_f32_16x16x32_bf16 v[6:9], v[160:163], v[212:215], v[6:9]
	v_mfma_f32_16x16x32_bf16 v[62:65], v[156:159], v[192:195], v[62:65]
	v_mfma_f32_16x16x32_bf16 v[54:57], v[164:167], v[192:195], v[54:57]
	v_mfma_f32_16x16x32_bf16 v[46:49], v[156:159], v[200:203], v[46:49]
	v_mfma_f32_16x16x32_bf16 v[38:41], v[164:167], v[200:203], v[38:41]
	v_mfma_f32_16x16x32_bf16 v[30:33], v[156:159], v[208:211], v[30:33]
	v_mfma_f32_16x16x32_bf16 v[22:25], v[164:167], v[208:211], v[22:25]
	v_mfma_f32_16x16x32_bf16 v[14:17], v[156:159], v[216:219], v[14:17]
	v_mfma_f32_16x16x32_bf16 v[6:9], v[164:167], v[216:219], v[6:9]
	s_setprio 0
	s_setprio 1
	v_mfma_f32_16x16x32_bf16 v[58:61], v[168:171], v[188:191], v[58:61]
	v_mfma_f32_16x16x32_bf16 v[50:53], v[180:183], v[188:191], v[50:53]
	v_mfma_f32_16x16x32_bf16 v[42:45], v[168:171], v[196:199], v[42:45]
	v_mfma_f32_16x16x32_bf16 v[34:37], v[180:183], v[196:199], v[34:37]
	v_mfma_f32_16x16x32_bf16 v[26:29], v[168:171], v[204:207], v[26:29]
	v_mfma_f32_16x16x32_bf16 v[18:21], v[180:183], v[204:207], v[18:21]
	v_mfma_f32_16x16x32_bf16 v[10:13], v[168:171], v[212:215], v[10:13]
	v_mfma_f32_16x16x32_bf16 v[2:5], v[180:183], v[212:215], v[2:5]
	v_mfma_f32_16x16x32_bf16 v[58:61], v[176:179], v[192:195], v[58:61]
	v_mfma_f32_16x16x32_bf16 v[50:53], v[184:187], v[192:195], v[50:53]
	v_mfma_f32_16x16x32_bf16 v[42:45], v[176:179], v[200:203], v[42:45]
	v_mfma_f32_16x16x32_bf16 v[34:37], v[184:187], v[200:203], v[34:37]
	v_mfma_f32_16x16x32_bf16 v[26:29], v[176:179], v[208:211], v[26:29]
	v_mfma_f32_16x16x32_bf16 v[18:21], v[184:187], v[208:211], v[18:21]
	v_mfma_f32_16x16x32_bf16 v[10:13], v[176:179], v[216:219], v[10:13]
	v_mfma_f32_16x16x32_bf16 v[2:5], v[184:187], v[216:219], v[2:5]
	s_setprio 0
	s_barrier
	s_add_i32 s85, s85, 2
	s_add_u32 s48, s48, 0x100
	s_addc_u32 s49, s49, 0
	s_add_u32 s83, s83, 0x100
	s_addc_u32 s84, s84, 0
	s_cmp_gt_u32 s85, 61
	s_cbranch_scc1 .Lpeel_exit_5
.LBB0_824:
	ds_read_b128 v[152:155], v148
	ds_read_b128 v[156:159], v148 offset:1024
	ds_read_b128 v[160:163], v148 offset:2048
	ds_read_b128 v[164:167], v148 offset:3072
	ds_read_b128 v[168:171], v149
	ds_read_b128 v[176:179], v149 offset:1024
	ds_read_b128 v[180:183], v149 offset:2048
	ds_read_b128 v[184:187], v149 offset:3072
	s_add_u32 s10, s48, 0xfff00080
	s_addc_u32 s11, s49, -1
	s_cmp_eq_u32 s85, 60
	s_cselect_b32 s35, s27, s11
	s_cselect_b32 s34, s30, s10
	s_cselect_b32 s11, s31, s84
	s_cselect_b32 s10, s37, s83
	s_add_i32 m0, s47, 0xc000
	ds_read_b128 v[188:191], v150
	ds_read_b128 v[192:195], v150 offset:1024
	ds_read_b128 v[196:199], v150 offset:2048
	ds_read_b128 v[200:203], v150 offset:3072
	ds_read_b128 v[204:207], v150 offset:4096
	ds_read_b128 v[208:211], v150 offset:5120
	ds_read_b128 v[212:215], v150 offset:6144
	ds_read_b128 v[216:219], v150 offset:7168
	global_load_lds_dwordx4 v138, s[48:49]
	s_add_i32 m0, s47, 0xe000
	s_nop 0
	global_load_lds_dwordx4 v140, s[48:49]
	s_waitcnt vmcnt(8)
	s_waitcnt lgkmcnt(0)
	s_barrier
	s_setprio 1
	s_waitcnt lgkmcnt(0)
	v_mfma_f32_16x16x32_bf16 v[126:129], v[152:155], v[188:191], v[126:129]
	v_mfma_f32_16x16x32_bf16 v[118:121], v[160:163], v[188:191], v[118:121]
	v_mfma_f32_16x16x32_bf16 v[110:113], v[152:155], v[196:199], v[110:113]
	v_mfma_f32_16x16x32_bf16 v[102:105], v[160:163], v[196:199], v[102:105]
	v_mfma_f32_16x16x32_bf16 v[94:97], v[152:155], v[204:207], v[94:97]
	v_mfma_f32_16x16x32_bf16 v[86:89], v[160:163], v[204:207], v[86:89]
	v_mfma_f32_16x16x32_bf16 v[78:81], v[152:155], v[212:215], v[78:81]
	v_mfma_f32_16x16x32_bf16 v[70:73], v[160:163], v[212:215], v[70:73]
	v_mfma_f32_16x16x32_bf16 v[126:129], v[156:159], v[192:195], v[126:129]
	v_mfma_f32_16x16x32_bf16 v[118:121], v[164:167], v[192:195], v[118:121]
	v_mfma_f32_16x16x32_bf16 v[110:113], v[156:159], v[200:203], v[110:113]
	v_mfma_f32_16x16x32_bf16 v[102:105], v[164:167], v[200:203], v[102:105]
	v_mfma_f32_16x16x32_bf16 v[94:97], v[156:159], v[208:211], v[94:97]
	v_mfma_f32_16x16x32_bf16 v[86:89], v[164:167], v[208:211], v[86:89]
	v_mfma_f32_16x16x32_bf16 v[78:81], v[156:159], v[216:219], v[78:81]
	v_mfma_f32_16x16x32_bf16 v[70:73], v[164:167], v[216:219], v[70:73]
	s_setprio 0
	s_setprio 1
	v_mfma_f32_16x16x32_bf16 v[122:125], v[168:171], v[188:191], v[122:125]
	v_mfma_f32_16x16x32_bf16 v[114:117], v[180:183], v[188:191], v[114:117]
	v_mfma_f32_16x16x32_bf16 v[106:109], v[168:171], v[196:199], v[106:109]
	v_mfma_f32_16x16x32_bf16 v[98:101], v[180:183], v[196:199], v[98:101]
	v_mfma_f32_16x16x32_bf16 v[90:93], v[168:171], v[204:207], v[90:93]
	v_mfma_f32_16x16x32_bf16 v[82:85], v[180:183], v[204:207], v[82:85]
	v_mfma_f32_16x16x32_bf16 v[74:77], v[168:171], v[212:215], v[74:77]
	v_mfma_f32_16x16x32_bf16 v[66:69], v[180:183], v[212:215], v[66:69]
	v_mfma_f32_16x16x32_bf16 v[122:125], v[176:179], v[192:195], v[122:125]
	v_mfma_f32_16x16x32_bf16 v[114:117], v[184:187], v[192:195], v[114:117]
	v_mfma_f32_16x16x32_bf16 v[106:109], v[176:179], v[200:203], v[106:109]
	v_mfma_f32_16x16x32_bf16 v[98:101], v[184:187], v[200:203], v[98:101]
	v_mfma_f32_16x16x32_bf16 v[90:93], v[176:179], v[208:211], v[90:93]
	v_mfma_f32_16x16x32_bf16 v[82:85], v[184:187], v[208:211], v[82:85]
	v_mfma_f32_16x16x32_bf16 v[74:77], v[176:179], v[216:219], v[74:77]
	v_mfma_f32_16x16x32_bf16 v[66:69], v[184:187], v[216:219], v[66:69]
	s_setprio 0
	s_barrier
	s_add_i32 s86, s61, s51
	s_mov_b32 m0, s86
	ds_read_b128 v[188:191], v150 offset:16384
	ds_read_b128 v[192:195], v150 offset:17408
	ds_read_b128 v[196:199], v150 offset:18432
	ds_read_b128 v[200:203], v150 offset:19456
	ds_read_b128 v[204:207], v150 offset:20480
	ds_read_b128 v[208:211], v150 offset:21504
	ds_read_b128 v[212:215], v150 offset:22528
	ds_read_b128 v[216:219], v150 offset:23552
	global_load_lds_dwordx4 v132, s[10:11]
	s_add_i32 m0, s86, 0x2000
	s_add_u32 s86, s10, 0x100000
	s_addc_u32 s87, s11, 0
	s_add_i32 s88, s62, s51
	s_add_u32 s14, s34, 0x80
	s_addc_u32 s15, s35, 0
	global_load_lds_dwordx4 v136, s[10:11]
	s_mov_b32 m0, s88
	s_nop 0
	global_load_lds_dwordx4 v132, s[86:87]
	s_add_i32 m0, s88, 0x2000
	s_nop 0
	global_load_lds_dwordx4 v136, s[86:87]
	s_mov_b32 m0, s47
	s_nop 0
	global_load_lds_dwordx4 v130, s[34:35]
	s_mov_b32 m0, s54
	s_nop 0
	global_load_lds_dwordx4 v134, s[34:35]
	s_waitcnt vmcnt(8)
	s_waitcnt lgkmcnt(0)
	s_barrier
	s_setprio 1
	s_waitcnt lgkmcnt(0)
	v_mfma_f32_16x16x32_bf16 v[62:65], v[152:155], v[188:191], v[62:65]
	v_mfma_f32_16x16x32_bf16 v[54:57], v[160:163], v[188:191], v[54:57]
	v_mfma_f32_16x16x32_bf16 v[46:49], v[152:155], v[196:199], v[46:49]
	v_mfma_f32_16x16x32_bf16 v[38:41], v[160:163], v[196:199], v[38:41]
	v_mfma_f32_16x16x32_bf16 v[30:33], v[152:155], v[204:207], v[30:33]
	v_mfma_f32_16x16x32_bf16 v[22:25], v[160:163], v[204:207], v[22:25]
	v_mfma_f32_16x16x32_bf16 v[14:17], v[152:155], v[212:215], v[14:17]
	v_mfma_f32_16x16x32_bf16 v[6:9], v[160:163], v[212:215], v[6:9]
	v_mfma_f32_16x16x32_bf16 v[62:65], v[156:159], v[192:195], v[62:65]
	v_mfma_f32_16x16x32_bf16 v[54:57], v[164:167], v[192:195], v[54:57]
	v_mfma_f32_16x16x32_bf16 v[46:49], v[156:159], v[200:203], v[46:49]
	v_mfma_f32_16x16x32_bf16 v[38:41], v[164:167], v[200:203], v[38:41]
	v_mfma_f32_16x16x32_bf16 v[30:33], v[156:159], v[208:211], v[30:33]
	v_mfma_f32_16x16x32_bf16 v[22:25], v[164:167], v[208:211], v[22:25]
	v_mfma_f32_16x16x32_bf16 v[14:17], v[156:159], v[216:219], v[14:17]
	v_mfma_f32_16x16x32_bf16 v[6:9], v[164:167], v[216:219], v[6:9]
	s_setprio 0
	s_setprio 1
	v_mfma_f32_16x16x32_bf16 v[58:61], v[168:171], v[188:191], v[58:61]
	v_mfma_f32_16x16x32_bf16 v[50:53], v[180:183], v[188:191], v[50:53]
	v_mfma_f32_16x16x32_bf16 v[42:45], v[168:171], v[196:199], v[42:45]
	v_mfma_f32_16x16x32_bf16 v[34:37], v[180:183], v[196:199], v[34:37]
	v_mfma_f32_16x16x32_bf16 v[26:29], v[168:171], v[204:207], v[26:29]
	v_mfma_f32_16x16x32_bf16 v[18:21], v[180:183], v[204:207], v[18:21]
	v_mfma_f32_16x16x32_bf16 v[10:13], v[168:171], v[212:215], v[10:13]
	v_mfma_f32_16x16x32_bf16 v[2:5], v[180:183], v[212:215], v[2:5]
	v_mfma_f32_16x16x32_bf16 v[58:61], v[176:179], v[192:195], v[58:61]
	v_mfma_f32_16x16x32_bf16 v[50:53], v[184:187], v[192:195], v[50:53]
	v_mfma_f32_16x16x32_bf16 v[42:45], v[176:179], v[200:203], v[42:45]
	v_mfma_f32_16x16x32_bf16 v[34:37], v[184:187], v[200:203], v[34:37]
	v_mfma_f32_16x16x32_bf16 v[26:29], v[176:179], v[208:211], v[26:29]
	v_mfma_f32_16x16x32_bf16 v[18:21], v[184:187], v[208:211], v[18:21]
	v_mfma_f32_16x16x32_bf16 v[10:13], v[176:179], v[216:219], v[10:13]
	v_mfma_f32_16x16x32_bf16 v[2:5], v[184:187], v[216:219], v[2:5]
	s_setprio 0
	s_barrier
	s_add_i32 s86, 0, 0x18000
	v_add_u32_e32 v151, s86, v146
	s_add_i32 s87, 0, 0x1c000
	ds_read_b128 v[152:155], v151
	ds_read_b128 v[156:159], v151 offset:1024
	ds_read_b128 v[160:163], v151 offset:2048
	ds_read_b128 v[164:167], v151 offset:3072
	v_add_u32_e32 v151, s87, v146
	ds_read_b128 v[168:171], v151
	ds_read_b128 v[176:179], v151 offset:1024
	ds_read_b128 v[180:183], v151 offset:2048
	ds_read_b128 v[184:187], v151 offset:3072
	s_add_u32 s34, s34, 0x100000
	s_addc_u32 s35, s35, 0
	s_mov_b32 m0, s55
	ds_read_b128 v[188:191], v150 offset:32768
	ds_read_b128 v[192:195], v150 offset:33792
	ds_read_b128 v[196:199], v150 offset:34816
	ds_read_b128 v[200:203], v150 offset:35840
	ds_read_b128 v[204:207], v150 offset:36864
	ds_read_b128 v[208:211], v150 offset:37888
	ds_read_b128 v[212:215], v150 offset:38912
	ds_read_b128 v[216:219], v150 offset:39936
	global_load_lds_dwordx4 v130, s[34:35]
	s_mov_b32 m0, s56
	s_nop 0
	global_load_lds_dwordx4 v134, s[34:35]
	s_waitcnt vmcnt(8)
	s_waitcnt lgkmcnt(0)
	s_barrier
	s_setprio 1
	s_waitcnt lgkmcnt(0)
	v_mfma_f32_16x16x32_bf16 v[126:129], v[152:155], v[188:191], v[126:129]
	v_mfma_f32_16x16x32_bf16 v[118:121], v[160:163], v[188:191], v[118:121]
	v_mfma_f32_16x16x32_bf16 v[110:113], v[152:155], v[196:199], v[110:113]
	v_mfma_f32_16x16x32_bf16 v[102:105], v[160:163], v[196:199], v[102:105]
	v_mfma_f32_16x16x32_bf16 v[94:97], v[152:155], v[204:207], v[94:97]
	v_mfma_f32_16x16x32_bf16 v[86:89], v[160:163], v[204:207], v[86:89]
	v_mfma_f32_16x16x32_bf16 v[78:81], v[152:155], v[212:215], v[78:81]
	v_mfma_f32_16x16x32_bf16 v[70:73], v[160:163], v[212:215], v[70:73]
	v_mfma_f32_16x16x32_bf16 v[126:129], v[156:159], v[192:195], v[126:129]
	v_mfma_f32_16x16x32_bf16 v[118:121], v[164:167], v[192:195], v[118:121]
	v_mfma_f32_16x16x32_bf16 v[110:113], v[156:159], v[200:203], v[110:113]
	v_mfma_f32_16x16x32_bf16 v[102:105], v[164:167], v[200:203], v[102:105]
	v_mfma_f32_16x16x32_bf16 v[94:97], v[156:159], v[208:211], v[94:97]
	v_mfma_f32_16x16x32_bf16 v[86:89], v[164:167], v[208:211], v[86:89]
	v_mfma_f32_16x16x32_bf16 v[78:81], v[156:159], v[216:219], v[78:81]
	v_mfma_f32_16x16x32_bf16 v[70:73], v[164:167], v[216:219], v[70:73]
	s_setprio 0
	s_setprio 1
	v_mfma_f32_16x16x32_bf16 v[122:125], v[168:171], v[188:191], v[122:125]
	v_mfma_f32_16x16x32_bf16 v[114:117], v[180:183], v[188:191], v[114:117]
	v_mfma_f32_16x16x32_bf16 v[106:109], v[168:171], v[196:199], v[106:109]
	v_mfma_f32_16x16x32_bf16 v[98:101], v[180:183], v[196:199], v[98:101]
	v_mfma_f32_16x16x32_bf16 v[90:93], v[168:171], v[204:207], v[90:93]
	v_mfma_f32_16x16x32_bf16 v[82:85], v[180:183], v[204:207], v[82:85]
	v_mfma_f32_16x16x32_bf16 v[74:77], v[168:171], v[212:215], v[74:77]
	v_mfma_f32_16x16x32_bf16 v[66:69], v[180:183], v[212:215], v[66:69]
	v_mfma_f32_16x16x32_bf16 v[122:125], v[176:179], v[192:195], v[122:125]
	v_mfma_f32_16x16x32_bf16 v[114:117], v[184:187], v[192:195], v[114:117]
	v_mfma_f32_16x16x32_bf16 v[106:109], v[176:179], v[200:203], v[106:109]
	v_mfma_f32_16x16x32_bf16 v[98:101], v[184:187], v[200:203], v[98:101]
	v_mfma_f32_16x16x32_bf16 v[90:93], v[176:179], v[208:211], v[90:93]
	v_mfma_f32_16x16x32_bf16 v[82:85], v[184:187], v[208:211], v[82:85]
	v_mfma_f32_16x16x32_bf16 v[74:77], v[176:179], v[216:219], v[74:77]
	v_mfma_f32_16x16x32_bf16 v[66:69], v[184:187], v[216:219], v[66:69]
	s_setprio 0
	s_barrier
	s_add_u32 s12, s10, 0x80
	s_addc_u32 s13, s11, 0
	s_add_i32 s34, s86, s51
	s_mov_b32 m0, s34
	ds_read_b128 v[188:191], v150 offset:49152
	ds_read_b128 v[192:195], v150 offset:50176
	ds_read_b128 v[196:199], v150 offset:51200
	ds_read_b128 v[200:203], v150 offset:52224
	ds_read_b128 v[204:207], v150 offset:53248
	ds_read_b128 v[208:211], v150 offset:54272
	ds_read_b128 v[212:215], v150 offset:55296
	ds_read_b128 v[216:219], v150 offset:56320
	global_load_lds_dwordx4 v132, s[12:13]
	s_add_i32 m0, s34, 0x2000
	s_add_u32 s10, s10, 0x100080
	s_addc_u32 s11, s11, 0
	s_add_i32 s34, s87, s51
	global_load_lds_dwordx4 v136, s[12:13]
	s_mov_b32 m0, s34
	s_nop 0
	global_load_lds_dwordx4 v132, s[10:11]
	s_add_i32 m0, s34, 0x2000
	s_nop 0
	global_load_lds_dwordx4 v136, s[10:11]
	s_mov_b32 m0, s57
	s_nop 0
	global_load_lds_dwordx4 v130, s[14:15]
	s_mov_b32 m0, s58
	s_nop 0
	global_load_lds_dwordx4 v134, s[14:15]
	s_waitcnt vmcnt(8)
	s_waitcnt lgkmcnt(0)
	s_barrier
	s_setprio 1
	s_waitcnt lgkmcnt(0)
	v_mfma_f32_16x16x32_bf16 v[62:65], v[152:155], v[188:191], v[62:65]
	v_mfma_f32_16x16x32_bf16 v[54:57], v[160:163], v[188:191], v[54:57]
	v_mfma_f32_16x16x32_bf16 v[46:49], v[152:155], v[196:199], v[46:49]
	v_mfma_f32_16x16x32_bf16 v[38:41], v[160:163], v[196:199], v[38:41]
	v_mfma_f32_16x16x32_bf16 v[30:33], v[152:155], v[204:207], v[30:33]
	v_mfma_f32_16x16x32_bf16 v[22:25], v[160:163], v[204:207], v[22:25]
	v_mfma_f32_16x16x32_bf16 v[14:17], v[152:155], v[212:215], v[14:17]
	v_mfma_f32_16x16x32_bf16 v[6:9], v[160:163], v[212:215], v[6:9]
	v_mfma_f32_16x16x32_bf16 v[62:65], v[156:159], v[192:195], v[62:65]
	v_mfma_f32_16x16x32_bf16 v[54:57], v[164:167], v[192:195], v[54:57]
	v_mfma_f32_16x16x32_bf16 v[46:49], v[156:159], v[200:203], v[46:49]
	v_mfma_f32_16x16x32_bf16 v[38:41], v[164:167], v[200:203], v[38:41]
	v_mfma_f32_16x16x32_bf16 v[30:33], v[156:159], v[208:211], v[30:33]
	v_mfma_f32_16x16x32_bf16 v[22:25], v[164:167], v[208:211], v[22:25]
	v_mfma_f32_16x16x32_bf16 v[14:17], v[156:159], v[216:219], v[14:17]
	v_mfma_f32_16x16x32_bf16 v[6:9], v[164:167], v[216:219], v[6:9]
	s_setprio 0
	s_setprio 1
	v_mfma_f32_16x16x32_bf16 v[58:61], v[168:171], v[188:191], v[58:61]
	v_mfma_f32_16x16x32_bf16 v[50:53], v[180:183], v[188:191], v[50:53]
	v_mfma_f32_16x16x32_bf16 v[42:45], v[168:171], v[196:199], v[42:45]
	v_mfma_f32_16x16x32_bf16 v[34:37], v[180:183], v[196:199], v[34:37]
	v_mfma_f32_16x16x32_bf16 v[26:29], v[168:171], v[204:207], v[26:29]
	v_mfma_f32_16x16x32_bf16 v[18:21], v[180:183], v[204:207], v[18:21]
	v_mfma_f32_16x16x32_bf16 v[10:13], v[168:171], v[212:215], v[10:13]
	v_mfma_f32_16x16x32_bf16 v[2:5], v[180:183], v[212:215], v[2:5]
	v_mfma_f32_16x16x32_bf16 v[58:61], v[176:179], v[192:195], v[58:61]
	v_mfma_f32_16x16x32_bf16 v[50:53], v[184:187], v[192:195], v[50:53]
	v_mfma_f32_16x16x32_bf16 v[42:45], v[176:179], v[200:203], v[42:45]
	v_mfma_f32_16x16x32_bf16 v[34:37], v[184:187], v[200:203], v[34:37]
	v_mfma_f32_16x16x32_bf16 v[26:29], v[176:179], v[208:211], v[26:29]
	v_mfma_f32_16x16x32_bf16 v[18:21], v[184:187], v[208:211], v[18:21]
	v_mfma_f32_16x16x32_bf16 v[10:13], v[176:179], v[216:219], v[10:13]
	v_mfma_f32_16x16x32_bf16 v[2:5], v[184:187], v[216:219], v[2:5]
	s_setprio 0
	s_barrier
	s_add_i32 s85, s85, 2
	s_add_u32 s48, s48, 0x100
	s_addc_u32 s49, s49, 0
	s_add_u32 s83, s83, 0x100
	s_addc_u32 s84, s84, 0
	s_cmp_gt_u32 s85, 61
	s_cbranch_scc0 .LBB0_824

.LBB0_922:
	s_add_u32 s42, s42, 0x2b0080
	s_addc_u32 s43, s43, 0
	s_add_u32 s62, s34, 0x100
	s_addc_u32 s63, s35, 0
	s_mov_b32 s64, -2
	ds_read_b128 v[152:155], v149
	ds_read_b128 v[156:159], v149 offset:1024
	ds_read_b128 v[160:163], v149 offset:2048
	ds_read_b128 v[164:167], v149 offset:3072
	ds_read_b128 v[168:171], v150
	ds_read_b128 v[176:179], v150 offset:1024
	ds_read_b128 v[180:183], v150 offset:2048
	ds_read_b128 v[184:187], v150 offset:3072
	s_add_u32 s10, s42, 0xffd50080
	s_addc_u32 s11, s43, -1
	s_cmpk_eq_i32 s64, 0xa8
	s_cselect_b32 s35, s7, s11
	s_cselect_b32 s34, s6, s10
	s_cselect_b32 s11, s41, s63
	s_cselect_b32 s10, s40, s62
	s_add_i32 m0, s44, 0xc000
	ds_read_b128 v[188:191], v151
	ds_read_b128 v[192:195], v151 offset:1024
	ds_read_b128 v[196:199], v151 offset:2048
	ds_read_b128 v[200:203], v151 offset:3072
	ds_read_b128 v[204:207], v151 offset:4096
	ds_read_b128 v[208:211], v151 offset:5120
	ds_read_b128 v[212:215], v151 offset:6144
	ds_read_b128 v[216:219], v151 offset:7168
	global_load_lds_dwordx4 v136, s[42:43]
	s_add_i32 m0, s44, 0xe000
	s_nop 0
	global_load_lds_dwordx4 v138, s[42:43]
	s_waitcnt vmcnt(8)
	s_waitcnt lgkmcnt(0)
	s_barrier
	s_setprio 1
	s_waitcnt lgkmcnt(0)
	v_mfma_f32_16x16x32_bf16 v[124:127], v[152:155], v[188:191], 0
	v_mfma_f32_16x16x32_bf16 v[120:123], v[160:163], v[188:191], 0
	v_mfma_f32_16x16x32_bf16 v[112:115], v[152:155], v[196:199], 0
	v_mfma_f32_16x16x32_bf16 v[104:107], v[160:163], v[196:199], 0
	v_mfma_f32_16x16x32_bf16 v[96:99], v[152:155], v[204:207], 0
	v_mfma_f32_16x16x32_bf16 v[88:91], v[160:163], v[204:207], 0
	v_mfma_f32_16x16x32_bf16 v[80:83], v[152:155], v[212:215], 0
	v_mfma_f32_16x16x32_bf16 v[72:75], v[160:163], v[212:215], 0
	v_mfma_f32_16x16x32_bf16 v[124:127], v[156:159], v[192:195], v[124:127]
	v_mfma_f32_16x16x32_bf16 v[120:123], v[164:167], v[192:195], v[120:123]
	v_mfma_f32_16x16x32_bf16 v[112:115], v[156:159], v[200:203], v[112:115]
	v_mfma_f32_16x16x32_bf16 v[104:107], v[164:167], v[200:203], v[104:107]
	v_mfma_f32_16x16x32_bf16 v[96:99], v[156:159], v[208:211], v[96:99]
	v_mfma_f32_16x16x32_bf16 v[88:91], v[164:167], v[208:211], v[88:91]
	v_mfma_f32_16x16x32_bf16 v[80:83], v[156:159], v[216:219], v[80:83]
	v_mfma_f32_16x16x32_bf16 v[72:75], v[164:167], v[216:219], v[72:75]
	s_setprio 0
	s_setprio 1
	v_mfma_f32_16x16x32_bf16 v[116:119], v[168:171], v[188:191], 0
	v_mfma_f32_16x16x32_bf16 v[108:111], v[180:183], v[188:191], 0
	v_mfma_f32_16x16x32_bf16 v[100:103], v[168:171], v[196:199], 0
	v_mfma_f32_16x16x32_bf16 v[92:95], v[180:183], v[196:199], 0
	v_mfma_f32_16x16x32_bf16 v[84:87], v[168:171], v[204:207], 0
	v_mfma_f32_16x16x32_bf16 v[76:79], v[180:183], v[204:207], 0
	v_mfma_f32_16x16x32_bf16 v[68:71], v[168:171], v[212:215], 0
	v_mfma_f32_16x16x32_bf16 v[64:67], v[180:183], v[212:215], 0
	v_mfma_f32_16x16x32_bf16 v[116:119], v[176:179], v[192:195], v[116:119]
	v_mfma_f32_16x16x32_bf16 v[108:111], v[184:187], v[192:195], v[108:111]
	v_mfma_f32_16x16x32_bf16 v[100:103], v[176:179], v[200:203], v[100:103]
	v_mfma_f32_16x16x32_bf16 v[92:95], v[184:187], v[200:203], v[92:95]
	v_mfma_f32_16x16x32_bf16 v[84:87], v[176:179], v[208:211], v[84:87]
	v_mfma_f32_16x16x32_bf16 v[76:79], v[184:187], v[208:211], v[76:79]
	v_mfma_f32_16x16x32_bf16 v[68:71], v[176:179], v[216:219], v[68:71]
	v_mfma_f32_16x16x32_bf16 v[64:67], v[184:187], v[216:219], v[64:67]
	s_setprio 0
	s_barrier
	s_add_i32 s65, s52, s3
	s_mov_b32 m0, s65
	ds_read_b128 v[188:191], v151 offset:16384
	ds_read_b128 v[192:195], v151 offset:17408
	ds_read_b128 v[196:199], v151 offset:18432
	ds_read_b128 v[200:203], v151 offset:19456
	ds_read_b128 v[204:207], v151 offset:20480
	ds_read_b128 v[208:211], v151 offset:21504
	ds_read_b128 v[212:215], v151 offset:22528
	ds_read_b128 v[216:219], v151 offset:23552
	global_load_lds_dwordx4 v132, s[10:11]
	s_add_i32 m0, s65, 0x2000
	s_add_u32 s66, s10, 0x2b0000
	s_addc_u32 s67, s11, 0
	s_add_i32 s65, s53, s3
	s_add_u32 s22, s34, 0x80
	s_addc_u32 s23, s35, 0
	global_load_lds_dwordx4 v128, s[10:11]
	s_mov_b32 m0, s65
	s_nop 0
	global_load_lds_dwordx4 v132, s[66:67]
	s_add_i32 m0, s65, 0x2000
	s_nop 0
	global_load_lds_dwordx4 v128, s[66:67]
	s_mov_b32 m0, s44
	s_nop 0
	global_load_lds_dwordx4 v134, s[34:35]
	s_mov_b32 m0, s45
	s_nop 0
	global_load_lds_dwordx4 v130, s[34:35]
	s_waitcnt vmcnt(8)
	s_waitcnt lgkmcnt(0)
	s_barrier
	s_setprio 1
	s_waitcnt lgkmcnt(0)
	v_mfma_f32_16x16x32_bf16 v[60:63], v[152:155], v[188:191], 0
	v_mfma_f32_16x16x32_bf16 v[56:59], v[160:163], v[188:191], 0
	v_mfma_f32_16x16x32_bf16 v[48:51], v[152:155], v[196:199], 0
	v_mfma_f32_16x16x32_bf16 v[40:43], v[160:163], v[196:199], 0
	v_mfma_f32_16x16x32_bf16 v[32:35], v[152:155], v[204:207], 0
	v_mfma_f32_16x16x32_bf16 v[24:27], v[160:163], v[204:207], 0
	v_mfma_f32_16x16x32_bf16 v[16:19], v[152:155], v[212:215], 0
	v_mfma_f32_16x16x32_bf16 v[8:11], v[160:163], v[212:215], 0
	v_mfma_f32_16x16x32_bf16 v[60:63], v[156:159], v[192:195], v[60:63]
	v_mfma_f32_16x16x32_bf16 v[56:59], v[164:167], v[192:195], v[56:59]
	v_mfma_f32_16x16x32_bf16 v[48:51], v[156:159], v[200:203], v[48:51]
	v_mfma_f32_16x16x32_bf16 v[40:43], v[164:167], v[200:203], v[40:43]
	v_mfma_f32_16x16x32_bf16 v[32:35], v[156:159], v[208:211], v[32:35]
	v_mfma_f32_16x16x32_bf16 v[24:27], v[164:167], v[208:211], v[24:27]
	v_mfma_f32_16x16x32_bf16 v[16:19], v[156:159], v[216:219], v[16:19]
	v_mfma_f32_16x16x32_bf16 v[8:11], v[164:167], v[216:219], v[8:11]
	s_setprio 0
	s_setprio 1
	v_mfma_f32_16x16x32_bf16 v[52:55], v[168:171], v[188:191], 0
	v_mfma_f32_16x16x32_bf16 v[44:47], v[180:183], v[188:191], 0
	v_mfma_f32_16x16x32_bf16 v[36:39], v[168:171], v[196:199], 0
	v_mfma_f32_16x16x32_bf16 v[28:31], v[180:183], v[196:199], 0
	v_mfma_f32_16x16x32_bf16 v[20:23], v[168:171], v[204:207], 0
	v_mfma_f32_16x16x32_bf16 v[12:15], v[180:183], v[204:207], 0
	v_mfma_f32_16x16x32_bf16 v[4:7], v[168:171], v[212:215], 0
	v_mfma_f32_16x16x32_bf16 v[0:3], v[180:183], v[212:215], 0
	v_mfma_f32_16x16x32_bf16 v[52:55], v[176:179], v[192:195], v[52:55]
	v_mfma_f32_16x16x32_bf16 v[44:47], v[184:187], v[192:195], v[44:47]
	v_mfma_f32_16x16x32_bf16 v[36:39], v[176:179], v[200:203], v[36:39]
	v_mfma_f32_16x16x32_bf16 v[28:31], v[184:187], v[200:203], v[28:31]
	v_mfma_f32_16x16x32_bf16 v[20:23], v[176:179], v[208:211], v[20:23]
	v_mfma_f32_16x16x32_bf16 v[12:15], v[184:187], v[208:211], v[12:15]
	v_mfma_f32_16x16x32_bf16 v[4:7], v[176:179], v[216:219], v[4:7]
	v_mfma_f32_16x16x32_bf16 v[0:3], v[184:187], v[216:219], v[0:3]
	s_setprio 0
	s_barrier
	s_add_i32 s65, 0, 0x18000
	s_add_i32 s66, 0, 0x1c000
	v_add_u32_e32 v164, s65, v147
	v_add_u32_e32 v175, s66, v147
	ds_read_b128 v[152:155], v164
	ds_read_b128 v[156:159], v164 offset:1024
	ds_read_b128 v[160:163], v164 offset:2048
	ds_read_b128 v[164:167], v164 offset:3072
	ds_read_b128 v[168:171], v175
	ds_read_b128 v[176:179], v175 offset:1024
	ds_read_b128 v[180:183], v175 offset:2048
	ds_read_b128 v[184:187], v175 offset:3072
	s_add_u32 s34, s34, 0x2b0000
	s_addc_u32 s35, s35, 0
	s_mov_b32 m0, s46
	ds_read_b128 v[188:191], v151 offset:32768
	ds_read_b128 v[192:195], v151 offset:33792
	ds_read_b128 v[196:199], v151 offset:34816
	ds_read_b128 v[200:203], v151 offset:35840
	ds_read_b128 v[204:207], v151 offset:36864
	ds_read_b128 v[208:211], v151 offset:37888
	ds_read_b128 v[212:215], v151 offset:38912
	ds_read_b128 v[216:219], v151 offset:39936
	global_load_lds_dwordx4 v134, s[34:35]
	s_mov_b32 m0, s47
	s_nop 0
	global_load_lds_dwordx4 v130, s[34:35]
	s_waitcnt vmcnt(8)
	s_waitcnt lgkmcnt(0)
	s_barrier
	s_setprio 1
	s_waitcnt lgkmcnt(0)
	v_mfma_f32_16x16x32_bf16 v[124:127], v[152:155], v[188:191], v[124:127]
	v_mfma_f32_16x16x32_bf16 v[120:123], v[160:163], v[188:191], v[120:123]
	v_mfma_f32_16x16x32_bf16 v[112:115], v[152:155], v[196:199], v[112:115]
	v_mfma_f32_16x16x32_bf16 v[104:107], v[160:163], v[196:199], v[104:107]
	v_mfma_f32_16x16x32_bf16 v[96:99], v[152:155], v[204:207], v[96:99]
	v_mfma_f32_16x16x32_bf16 v[88:91], v[160:163], v[204:207], v[88:91]
	v_mfma_f32_16x16x32_bf16 v[80:83], v[152:155], v[212:215], v[80:83]
	v_mfma_f32_16x16x32_bf16 v[72:75], v[160:163], v[212:215], v[72:75]
	v_mfma_f32_16x16x32_bf16 v[124:127], v[156:159], v[192:195], v[124:127]
	v_mfma_f32_16x16x32_bf16 v[120:123], v[164:167], v[192:195], v[120:123]
	v_mfma_f32_16x16x32_bf16 v[112:115], v[156:159], v[200:203], v[112:115]
	v_mfma_f32_16x16x32_bf16 v[104:107], v[164:167], v[200:203], v[104:107]
	v_mfma_f32_16x16x32_bf16 v[96:99], v[156:159], v[208:211], v[96:99]
	v_mfma_f32_16x16x32_bf16 v[88:91], v[164:167], v[208:211], v[88:91]
	v_mfma_f32_16x16x32_bf16 v[80:83], v[156:159], v[216:219], v[80:83]
	v_mfma_f32_16x16x32_bf16 v[72:75], v[164:167], v[216:219], v[72:75]
	s_setprio 0
	s_setprio 1
	v_mfma_f32_16x16x32_bf16 v[116:119], v[168:171], v[188:191], v[116:119]
	v_mfma_f32_16x16x32_bf16 v[108:111], v[180:183], v[188:191], v[108:111]
	v_mfma_f32_16x16x32_bf16 v[100:103], v[168:171], v[196:199], v[100:103]
	v_mfma_f32_16x16x32_bf16 v[92:95], v[180:183], v[196:199], v[92:95]
	v_mfma_f32_16x16x32_bf16 v[84:87], v[168:171], v[204:207], v[84:87]
	v_mfma_f32_16x16x32_bf16 v[76:79], v[180:183], v[204:207], v[76:79]
	v_mfma_f32_16x16x32_bf16 v[68:71], v[168:171], v[212:215], v[68:71]
	v_mfma_f32_16x16x32_bf16 v[64:67], v[180:183], v[212:215], v[64:67]
	v_mfma_f32_16x16x32_bf16 v[116:119], v[176:179], v[192:195], v[116:119]
	v_mfma_f32_16x16x32_bf16 v[108:111], v[184:187], v[192:195], v[108:111]
	v_mfma_f32_16x16x32_bf16 v[100:103], v[176:179], v[200:203], v[100:103]
	v_mfma_f32_16x16x32_bf16 v[92:95], v[184:187], v[200:203], v[92:95]
	v_mfma_f32_16x16x32_bf16 v[84:87], v[176:179], v[208:211], v[84:87]
	v_mfma_f32_16x16x32_bf16 v[76:79], v[184:187], v[208:211], v[76:79]
	v_mfma_f32_16x16x32_bf16 v[68:71], v[176:179], v[216:219], v[68:71]
	v_mfma_f32_16x16x32_bf16 v[64:67], v[184:187], v[216:219], v[64:67]
	s_setprio 0
	s_barrier
	s_add_u32 s16, s10, 0x80
	s_addc_u32 s17, s11, 0
	s_add_i32 s34, s65, s3
	s_mov_b32 m0, s34
	ds_read_b128 v[188:191], v151 offset:49152
	ds_read_b128 v[192:195], v151 offset:50176
	ds_read_b128 v[196:199], v151 offset:51200
	ds_read_b128 v[200:203], v151 offset:52224
	ds_read_b128 v[204:207], v151 offset:53248
	ds_read_b128 v[208:211], v151 offset:54272
	ds_read_b128 v[212:215], v151 offset:55296
	ds_read_b128 v[216:219], v151 offset:56320
	global_load_lds_dwordx4 v132, s[16:17]
	s_add_i32 m0, s34, 0x2000
	s_add_u32 s10, s10, 0x2b0080
	s_addc_u32 s11, s11, 0
	s_add_i32 s34, s66, s3
	global_load_lds_dwordx4 v128, s[16:17]
	s_mov_b32 m0, s34
	s_nop 0
	global_load_lds_dwordx4 v132, s[10:11]
	s_add_i32 m0, s34, 0x2000
	s_nop 0
	global_load_lds_dwordx4 v128, s[10:11]
	s_mov_b32 m0, s49
	s_nop 0
	global_load_lds_dwordx4 v134, s[22:23]
	s_mov_b32 m0, s50
	s_nop 0
	global_load_lds_dwordx4 v130, s[22:23]
	s_waitcnt vmcnt(8)
	s_waitcnt lgkmcnt(0)
	s_barrier
	s_setprio 1
	s_waitcnt lgkmcnt(0)
	v_mfma_f32_16x16x32_bf16 v[60:63], v[152:155], v[188:191], v[60:63]
	v_mfma_f32_16x16x32_bf16 v[56:59], v[160:163], v[188:191], v[56:59]
	v_mfma_f32_16x16x32_bf16 v[48:51], v[152:155], v[196:199], v[48:51]
	v_mfma_f32_16x16x32_bf16 v[40:43], v[160:163], v[196:199], v[40:43]
	v_mfma_f32_16x16x32_bf16 v[32:35], v[152:155], v[204:207], v[32:35]
	v_mfma_f32_16x16x32_bf16 v[24:27], v[160:163], v[204:207], v[24:27]
	v_mfma_f32_16x16x32_bf16 v[16:19], v[152:155], v[212:215], v[16:19]
	v_mfma_f32_16x16x32_bf16 v[8:11], v[160:163], v[212:215], v[8:11]
	v_mfma_f32_16x16x32_bf16 v[60:63], v[156:159], v[192:195], v[60:63]
	v_mfma_f32_16x16x32_bf16 v[56:59], v[164:167], v[192:195], v[56:59]
	v_mfma_f32_16x16x32_bf16 v[48:51], v[156:159], v[200:203], v[48:51]
	v_mfma_f32_16x16x32_bf16 v[40:43], v[164:167], v[200:203], v[40:43]
	v_mfma_f32_16x16x32_bf16 v[32:35], v[156:159], v[208:211], v[32:35]
	v_mfma_f32_16x16x32_bf16 v[24:27], v[164:167], v[208:211], v[24:27]
	v_mfma_f32_16x16x32_bf16 v[16:19], v[156:159], v[216:219], v[16:19]
	v_mfma_f32_16x16x32_bf16 v[8:11], v[164:167], v[216:219], v[8:11]
	s_setprio 0
	s_setprio 1
	v_mfma_f32_16x16x32_bf16 v[52:55], v[168:171], v[188:191], v[52:55]
	v_mfma_f32_16x16x32_bf16 v[44:47], v[180:183], v[188:191], v[44:47]
	v_mfma_f32_16x16x32_bf16 v[36:39], v[168:171], v[196:199], v[36:39]
	v_mfma_f32_16x16x32_bf16 v[28:31], v[180:183], v[196:199], v[28:31]
	v_mfma_f32_16x16x32_bf16 v[20:23], v[168:171], v[204:207], v[20:23]
	v_mfma_f32_16x16x32_bf16 v[12:15], v[180:183], v[204:207], v[12:15]
	v_mfma_f32_16x16x32_bf16 v[4:7], v[168:171], v[212:215], v[4:7]
	v_mfma_f32_16x16x32_bf16 v[0:3], v[180:183], v[212:215], v[0:3]
	v_mfma_f32_16x16x32_bf16 v[52:55], v[176:179], v[192:195], v[52:55]
	v_mfma_f32_16x16x32_bf16 v[44:47], v[184:187], v[192:195], v[44:47]
	v_mfma_f32_16x16x32_bf16 v[36:39], v[176:179], v[200:203], v[36:39]
	v_mfma_f32_16x16x32_bf16 v[28:31], v[184:187], v[200:203], v[28:31]
	v_mfma_f32_16x16x32_bf16 v[20:23], v[176:179], v[208:211], v[20:23]
	v_mfma_f32_16x16x32_bf16 v[12:15], v[184:187], v[208:211], v[12:15]
	v_mfma_f32_16x16x32_bf16 v[4:7], v[176:179], v[216:219], v[4:7]
	v_mfma_f32_16x16x32_bf16 v[0:3], v[184:187], v[216:219], v[0:3]
	s_setprio 0
	s_barrier
	s_add_i32 s64, s64, 2
	s_add_u32 s42, s42, 0x100
	s_addc_u32 s43, s43, 0
	s_add_u32 s62, s62, 0x100
	s_addc_u32 s63, s63, 0
	s_cmpk_gt_u32 s64, 0xa9
	s_cbranch_scc1 .Lpeel_exit_6
.LBB0_923:
	ds_read_b128 v[152:155], v149
	ds_read_b128 v[156:159], v149 offset:1024
	ds_read_b128 v[160:163], v149 offset:2048
	ds_read_b128 v[164:167], v149 offset:3072
	ds_read_b128 v[168:171], v150
	ds_read_b128 v[176:179], v150 offset:1024
	ds_read_b128 v[180:183], v150 offset:2048
	ds_read_b128 v[184:187], v150 offset:3072
	s_add_u32 s10, s42, 0xffd50080
	s_addc_u32 s11, s43, -1
	s_cmpk_eq_i32 s64, 0xa8
	s_cselect_b32 s35, s7, s11
	s_cselect_b32 s34, s6, s10
	s_cselect_b32 s11, s41, s63
	s_cselect_b32 s10, s40, s62
	s_add_i32 m0, s44, 0xc000
	ds_read_b128 v[188:191], v151
	ds_read_b128 v[192:195], v151 offset:1024
	ds_read_b128 v[196:199], v151 offset:2048
	ds_read_b128 v[200:203], v151 offset:3072
	ds_read_b128 v[204:207], v151 offset:4096
	ds_read_b128 v[208:211], v151 offset:5120
	ds_read_b128 v[212:215], v151 offset:6144
	ds_read_b128 v[216:219], v151 offset:7168
	global_load_lds_dwordx4 v136, s[42:43]
	s_add_i32 m0, s44, 0xe000
	s_nop 0
	global_load_lds_dwordx4 v138, s[42:43]
	s_waitcnt vmcnt(8)
	s_waitcnt lgkmcnt(0)
	s_barrier
	s_setprio 1
	s_waitcnt lgkmcnt(0)
	v_mfma_f32_16x16x32_bf16 v[124:127], v[152:155], v[188:191], v[124:127]
	v_mfma_f32_16x16x32_bf16 v[120:123], v[160:163], v[188:191], v[120:123]
	v_mfma_f32_16x16x32_bf16 v[112:115], v[152:155], v[196:199], v[112:115]
	v_mfma_f32_16x16x32_bf16 v[104:107], v[160:163], v[196:199], v[104:107]
	v_mfma_f32_16x16x32_bf16 v[96:99], v[152:155], v[204:207], v[96:99]
	v_mfma_f32_16x16x32_bf16 v[88:91], v[160:163], v[204:207], v[88:91]
	v_mfma_f32_16x16x32_bf16 v[80:83], v[152:155], v[212:215], v[80:83]
	v_mfma_f32_16x16x32_bf16 v[72:75], v[160:163], v[212:215], v[72:75]
	v_mfma_f32_16x16x32_bf16 v[124:127], v[156:159], v[192:195], v[124:127]
	v_mfma_f32_16x16x32_bf16 v[120:123], v[164:167], v[192:195], v[120:123]
	v_mfma_f32_16x16x32_bf16 v[112:115], v[156:159], v[200:203], v[112:115]
	v_mfma_f32_16x16x32_bf16 v[104:107], v[164:167], v[200:203], v[104:107]
	v_mfma_f32_16x16x32_bf16 v[96:99], v[156:159], v[208:211], v[96:99]
	v_mfma_f32_16x16x32_bf16 v[88:91], v[164:167], v[208:211], v[88:91]
	v_mfma_f32_16x16x32_bf16 v[80:83], v[156:159], v[216:219], v[80:83]
	v_mfma_f32_16x16x32_bf16 v[72:75], v[164:167], v[216:219], v[72:75]
	s_setprio 0
	s_setprio 1
	v_mfma_f32_16x16x32_bf16 v[116:119], v[168:171], v[188:191], v[116:119]
	v_mfma_f32_16x16x32_bf16 v[108:111], v[180:183], v[188:191], v[108:111]
	v_mfma_f32_16x16x32_bf16 v[100:103], v[168:171], v[196:199], v[100:103]
	v_mfma_f32_16x16x32_bf16 v[92:95], v[180:183], v[196:199], v[92:95]
	v_mfma_f32_16x16x32_bf16 v[84:87], v[168:171], v[204:207], v[84:87]
	v_mfma_f32_16x16x32_bf16 v[76:79], v[180:183], v[204:207], v[76:79]
	v_mfma_f32_16x16x32_bf16 v[68:71], v[168:171], v[212:215], v[68:71]
	v_mfma_f32_16x16x32_bf16 v[64:67], v[180:183], v[212:215], v[64:67]
	v_mfma_f32_16x16x32_bf16 v[116:119], v[176:179], v[192:195], v[116:119]
	v_mfma_f32_16x16x32_bf16 v[108:111], v[184:187], v[192:195], v[108:111]
	v_mfma_f32_16x16x32_bf16 v[100:103], v[176:179], v[200:203], v[100:103]
	v_mfma_f32_16x16x32_bf16 v[92:95], v[184:187], v[200:203], v[92:95]
	v_mfma_f32_16x16x32_bf16 v[84:87], v[176:179], v[208:211], v[84:87]
	v_mfma_f32_16x16x32_bf16 v[76:79], v[184:187], v[208:211], v[76:79]
	v_mfma_f32_16x16x32_bf16 v[68:71], v[176:179], v[216:219], v[68:71]
	v_mfma_f32_16x16x32_bf16 v[64:67], v[184:187], v[216:219], v[64:67]
	s_setprio 0
	s_barrier
	s_add_i32 s65, s52, s3
	s_mov_b32 m0, s65
	ds_read_b128 v[188:191], v151 offset:16384
	ds_read_b128 v[192:195], v151 offset:17408
	ds_read_b128 v[196:199], v151 offset:18432
	ds_read_b128 v[200:203], v151 offset:19456
	ds_read_b128 v[204:207], v151 offset:20480
	ds_read_b128 v[208:211], v151 offset:21504
	ds_read_b128 v[212:215], v151 offset:22528
	ds_read_b128 v[216:219], v151 offset:23552
	global_load_lds_dwordx4 v132, s[10:11]
	s_add_i32 m0, s65, 0x2000
	s_add_u32 s66, s10, 0x2b0000
	s_addc_u32 s67, s11, 0
	s_add_i32 s65, s53, s3
	s_add_u32 s22, s34, 0x80
	s_addc_u32 s23, s35, 0
	global_load_lds_dwordx4 v128, s[10:11]
	s_mov_b32 m0, s65
	s_nop 0
	global_load_lds_dwordx4 v132, s[66:67]
	s_add_i32 m0, s65, 0x2000
	s_nop 0
	global_load_lds_dwordx4 v128, s[66:67]
	s_mov_b32 m0, s44
	s_nop 0
	global_load_lds_dwordx4 v134, s[34:35]
	s_mov_b32 m0, s45
	s_nop 0
	global_load_lds_dwordx4 v130, s[34:35]
	s_waitcnt vmcnt(8)
	s_waitcnt lgkmcnt(0)
	s_barrier
	s_setprio 1
	s_waitcnt lgkmcnt(0)
	v_mfma_f32_16x16x32_bf16 v[60:63], v[152:155], v[188:191], v[60:63]
	v_mfma_f32_16x16x32_bf16 v[56:59], v[160:163], v[188:191], v[56:59]
	v_mfma_f32_16x16x32_bf16 v[48:51], v[152:155], v[196:199], v[48:51]
	v_mfma_f32_16x16x32_bf16 v[40:43], v[160:163], v[196:199], v[40:43]
	v_mfma_f32_16x16x32_bf16 v[32:35], v[152:155], v[204:207], v[32:35]
	v_mfma_f32_16x16x32_bf16 v[24:27], v[160:163], v[204:207], v[24:27]
	v_mfma_f32_16x16x32_bf16 v[16:19], v[152:155], v[212:215], v[16:19]
	v_mfma_f32_16x16x32_bf16 v[8:11], v[160:163], v[212:215], v[8:11]
	v_mfma_f32_16x16x32_bf16 v[60:63], v[156:159], v[192:195], v[60:63]
	v_mfma_f32_16x16x32_bf16 v[56:59], v[164:167], v[192:195], v[56:59]
	v_mfma_f32_16x16x32_bf16 v[48:51], v[156:159], v[200:203], v[48:51]
	v_mfma_f32_16x16x32_bf16 v[40:43], v[164:167], v[200:203], v[40:43]
	v_mfma_f32_16x16x32_bf16 v[32:35], v[156:159], v[208:211], v[32:35]
	v_mfma_f32_16x16x32_bf16 v[24:27], v[164:167], v[208:211], v[24:27]
	v_mfma_f32_16x16x32_bf16 v[16:19], v[156:159], v[216:219], v[16:19]
	v_mfma_f32_16x16x32_bf16 v[8:11], v[164:167], v[216:219], v[8:11]
	s_setprio 0
	s_setprio 1
	v_mfma_f32_16x16x32_bf16 v[52:55], v[168:171], v[188:191], v[52:55]
	v_mfma_f32_16x16x32_bf16 v[44:47], v[180:183], v[188:191], v[44:47]
	v_mfma_f32_16x16x32_bf16 v[36:39], v[168:171], v[196:199], v[36:39]
	v_mfma_f32_16x16x32_bf16 v[28:31], v[180:183], v[196:199], v[28:31]
	v_mfma_f32_16x16x32_bf16 v[20:23], v[168:171], v[204:207], v[20:23]
	v_mfma_f32_16x16x32_bf16 v[12:15], v[180:183], v[204:207], v[12:15]
	v_mfma_f32_16x16x32_bf16 v[4:7], v[168:171], v[212:215], v[4:7]
	v_mfma_f32_16x16x32_bf16 v[0:3], v[180:183], v[212:215], v[0:3]
	v_mfma_f32_16x16x32_bf16 v[52:55], v[176:179], v[192:195], v[52:55]
	v_mfma_f32_16x16x32_bf16 v[44:47], v[184:187], v[192:195], v[44:47]
	v_mfma_f32_16x16x32_bf16 v[36:39], v[176:179], v[200:203], v[36:39]
	v_mfma_f32_16x16x32_bf16 v[28:31], v[184:187], v[200:203], v[28:31]
	v_mfma_f32_16x16x32_bf16 v[20:23], v[176:179], v[208:211], v[20:23]
	v_mfma_f32_16x16x32_bf16 v[12:15], v[184:187], v[208:211], v[12:15]
	v_mfma_f32_16x16x32_bf16 v[4:7], v[176:179], v[216:219], v[4:7]
	v_mfma_f32_16x16x32_bf16 v[0:3], v[184:187], v[216:219], v[0:3]
	s_setprio 0
	s_barrier
	s_add_i32 s65, 0, 0x18000
	s_add_i32 s66, 0, 0x1c000
	v_add_u32_e32 v164, s65, v147
	v_add_u32_e32 v175, s66, v147
	ds_read_b128 v[152:155], v164
	ds_read_b128 v[156:159], v164 offset:1024
	ds_read_b128 v[160:163], v164 offset:2048
	ds_read_b128 v[164:167], v164 offset:3072
	ds_read_b128 v[168:171], v175
	ds_read_b128 v[176:179], v175 offset:1024
	ds_read_b128 v[180:183], v175 offset:2048
	ds_read_b128 v[184:187], v175 offset:3072
	s_add_u32 s34, s34, 0x2b0000
	s_addc_u32 s35, s35, 0
	s_mov_b32 m0, s46
	ds_read_b128 v[188:191], v151 offset:32768
	ds_read_b128 v[192:195], v151 offset:33792
	ds_read_b128 v[196:199], v151 offset:34816
	ds_read_b128 v[200:203], v151 offset:35840
	ds_read_b128 v[204:207], v151 offset:36864
	ds_read_b128 v[208:211], v151 offset:37888
	ds_read_b128 v[212:215], v151 offset:38912
	ds_read_b128 v[216:219], v151 offset:39936
	global_load_lds_dwordx4 v134, s[34:35]
	s_mov_b32 m0, s47
	s_nop 0
	global_load_lds_dwordx4 v130, s[34:35]
	s_waitcnt vmcnt(8)
	s_waitcnt lgkmcnt(0)
	s_barrier
	s_setprio 1
	s_waitcnt lgkmcnt(0)
	v_mfma_f32_16x16x32_bf16 v[124:127], v[152:155], v[188:191], v[124:127]
	v_mfma_f32_16x16x32_bf16 v[120:123], v[160:163], v[188:191], v[120:123]
	v_mfma_f32_16x16x32_bf16 v[112:115], v[152:155], v[196:199], v[112:115]
	v_mfma_f32_16x16x32_bf16 v[104:107], v[160:163], v[196:199], v[104:107]
	v_mfma_f32_16x16x32_bf16 v[96:99], v[152:155], v[204:207], v[96:99]
	v_mfma_f32_16x16x32_bf16 v[88:91], v[160:163], v[204:207], v[88:91]
	v_mfma_f32_16x16x32_bf16 v[80:83], v[152:155], v[212:215], v[80:83]
	v_mfma_f32_16x16x32_bf16 v[72:75], v[160:163], v[212:215], v[72:75]
	v_mfma_f32_16x16x32_bf16 v[124:127], v[156:159], v[192:195], v[124:127]
	v_mfma_f32_16x16x32_bf16 v[120:123], v[164:167], v[192:195], v[120:123]
	v_mfma_f32_16x16x32_bf16 v[112:115], v[156:159], v[200:203], v[112:115]
	v_mfma_f32_16x16x32_bf16 v[104:107], v[164:167], v[200:203], v[104:107]
	v_mfma_f32_16x16x32_bf16 v[96:99], v[156:159], v[208:211], v[96:99]
	v_mfma_f32_16x16x32_bf16 v[88:91], v[164:167], v[208:211], v[88:91]
	v_mfma_f32_16x16x32_bf16 v[80:83], v[156:159], v[216:219], v[80:83]
	v_mfma_f32_16x16x32_bf16 v[72:75], v[164:167], v[216:219], v[72:75]
	s_setprio 0
	s_setprio 1
	v_mfma_f32_16x16x32_bf16 v[116:119], v[168:171], v[188:191], v[116:119]
	v_mfma_f32_16x16x32_bf16 v[108:111], v[180:183], v[188:191], v[108:111]
	v_mfma_f32_16x16x32_bf16 v[100:103], v[168:171], v[196:199], v[100:103]
	v_mfma_f32_16x16x32_bf16 v[92:95], v[180:183], v[196:199], v[92:95]
	v_mfma_f32_16x16x32_bf16 v[84:87], v[168:171], v[204:207], v[84:87]
	v_mfma_f32_16x16x32_bf16 v[76:79], v[180:183], v[204:207], v[76:79]
	v_mfma_f32_16x16x32_bf16 v[68:71], v[168:171], v[212:215], v[68:71]
	v_mfma_f32_16x16x32_bf16 v[64:67], v[180:183], v[212:215], v[64:67]
	v_mfma_f32_16x16x32_bf16 v[116:119], v[176:179], v[192:195], v[116:119]
	v_mfma_f32_16x16x32_bf16 v[108:111], v[184:187], v[192:195], v[108:111]
	v_mfma_f32_16x16x32_bf16 v[100:103], v[176:179], v[200:203], v[100:103]
	v_mfma_f32_16x16x32_bf16 v[92:95], v[184:187], v[200:203], v[92:95]
	v_mfma_f32_16x16x32_bf16 v[84:87], v[176:179], v[208:211], v[84:87]
	v_mfma_f32_16x16x32_bf16 v[76:79], v[184:187], v[208:211], v[76:79]
	v_mfma_f32_16x16x32_bf16 v[68:71], v[176:179], v[216:219], v[68:71]
	v_mfma_f32_16x16x32_bf16 v[64:67], v[184:187], v[216:219], v[64:67]
	s_setprio 0
	s_barrier
	s_add_u32 s16, s10, 0x80
	s_addc_u32 s17, s11, 0
	s_add_i32 s34, s65, s3
	s_mov_b32 m0, s34
	ds_read_b128 v[188:191], v151 offset:49152
	ds_read_b128 v[192:195], v151 offset:50176
	ds_read_b128 v[196:199], v151 offset:51200
	ds_read_b128 v[200:203], v151 offset:52224
	ds_read_b128 v[204:207], v151 offset:53248
	ds_read_b128 v[208:211], v151 offset:54272
	ds_read_b128 v[212:215], v151 offset:55296
	ds_read_b128 v[216:219], v151 offset:56320
	global_load_lds_dwordx4 v132, s[16:17]
	s_add_i32 m0, s34, 0x2000
	s_add_u32 s10, s10, 0x2b0080
	s_addc_u32 s11, s11, 0
	s_add_i32 s34, s66, s3
	global_load_lds_dwordx4 v128, s[16:17]
	s_mov_b32 m0, s34
	s_nop 0
	global_load_lds_dwordx4 v132, s[10:11]
	s_add_i32 m0, s34, 0x2000
	s_nop 0
	global_load_lds_dwordx4 v128, s[10:11]
	s_mov_b32 m0, s49
	s_nop 0
	global_load_lds_dwordx4 v134, s[22:23]
	s_mov_b32 m0, s50
	s_nop 0
	global_load_lds_dwordx4 v130, s[22:23]
	s_waitcnt vmcnt(8)
	s_waitcnt lgkmcnt(0)
	s_barrier
	s_setprio 1
	s_waitcnt lgkmcnt(0)
	v_mfma_f32_16x16x32_bf16 v[60:63], v[152:155], v[188:191], v[60:63]
	v_mfma_f32_16x16x32_bf16 v[56:59], v[160:163], v[188:191], v[56:59]
	v_mfma_f32_16x16x32_bf16 v[48:51], v[152:155], v[196:199], v[48:51]
	v_mfma_f32_16x16x32_bf16 v[40:43], v[160:163], v[196:199], v[40:43]
	v_mfma_f32_16x16x32_bf16 v[32:35], v[152:155], v[204:207], v[32:35]
	v_mfma_f32_16x16x32_bf16 v[24:27], v[160:163], v[204:207], v[24:27]
	v_mfma_f32_16x16x32_bf16 v[16:19], v[152:155], v[212:215], v[16:19]
	v_mfma_f32_16x16x32_bf16 v[8:11], v[160:163], v[212:215], v[8:11]
	v_mfma_f32_16x16x32_bf16 v[60:63], v[156:159], v[192:195], v[60:63]
	v_mfma_f32_16x16x32_bf16 v[56:59], v[164:167], v[192:195], v[56:59]
	v_mfma_f32_16x16x32_bf16 v[48:51], v[156:159], v[200:203], v[48:51]
	v_mfma_f32_16x16x32_bf16 v[40:43], v[164:167], v[200:203], v[40:43]
	v_mfma_f32_16x16x32_bf16 v[32:35], v[156:159], v[208:211], v[32:35]
	v_mfma_f32_16x16x32_bf16 v[24:27], v[164:167], v[208:211], v[24:27]
	v_mfma_f32_16x16x32_bf16 v[16:19], v[156:159], v[216:219], v[16:19]
	v_mfma_f32_16x16x32_bf16 v[8:11], v[164:167], v[216:219], v[8:11]
	s_setprio 0
	s_setprio 1
	v_mfma_f32_16x16x32_bf16 v[52:55], v[168:171], v[188:191], v[52:55]
	v_mfma_f32_16x16x32_bf16 v[44:47], v[180:183], v[188:191], v[44:47]
	v_mfma_f32_16x16x32_bf16 v[36:39], v[168:171], v[196:199], v[36:39]
	v_mfma_f32_16x16x32_bf16 v[28:31], v[180:183], v[196:199], v[28:31]
	v_mfma_f32_16x16x32_bf16 v[20:23], v[168:171], v[204:207], v[20:23]
	v_mfma_f32_16x16x32_bf16 v[12:15], v[180:183], v[204:207], v[12:15]
	v_mfma_f32_16x16x32_bf16 v[4:7], v[168:171], v[212:215], v[4:7]
	v_mfma_f32_16x16x32_bf16 v[0:3], v[180:183], v[212:215], v[0:3]
	v_mfma_f32_16x16x32_bf16 v[52:55], v[176:179], v[192:195], v[52:55]
	v_mfma_f32_16x16x32_bf16 v[44:47], v[184:187], v[192:195], v[44:47]
	v_mfma_f32_16x16x32_bf16 v[36:39], v[176:179], v[200:203], v[36:39]
	v_mfma_f32_16x16x32_bf16 v[28:31], v[184:187], v[200:203], v[28:31]
	v_mfma_f32_16x16x32_bf16 v[20:23], v[176:179], v[208:211], v[20:23]
	v_mfma_f32_16x16x32_bf16 v[12:15], v[184:187], v[208:211], v[12:15]
	v_mfma_f32_16x16x32_bf16 v[4:7], v[176:179], v[216:219], v[4:7]
	v_mfma_f32_16x16x32_bf16 v[0:3], v[184:187], v[216:219], v[0:3]
	s_setprio 0
	s_barrier
	s_add_i32 s64, s64, 2
	s_add_u32 s42, s42, 0x100
	s_addc_u32 s43, s43, 0
	s_add_u32 s62, s62, 0x100
	s_addc_u32 s63, s63, 0
	s_cmpk_gt_u32 s64, 0xa9
	s_cbranch_scc0 .LBB0_923
